# GEMM K loops: 48 back-to-back duplicate s_waitcnt lgkmcnt(0) (hipcc's copy right behind the template's own) removed; on v085
# speedup vs baseline: 1.0051x; 1.0051x over previous
.LBB0_178:
	ds_read_b128 v[148:151], v159
	ds_read_b128 v[152:155], v159 offset:1024
	ds_read_b128 v[164:167], v159 offset:2048
	ds_read_b128 v[168:171], v159 offset:3072
	s_add_u32 s52, s50, 0xfffc0080
	s_addc_u32 s53, s51, -1
	s_cmp_eq_u32 s92, 12
	s_cselect_b32 s55, s11, s53
	s_cselect_b32 s54, s13, s52
	s_cselect_b32 s53, s17, s91
	s_cselect_b32 s52, s43, s45
	v_lshl_add_u64 v[156:157], s[50:51], 0, v[140:141]
	s_add_i32 m0, s58, 0xc000
	ds_read_b128 v[172:175], v160
	ds_read_b128 v[176:179], v160 offset:1024
	ds_read_b128 v[180:183], v160 offset:2048
	ds_read_b128 v[184:187], v160 offset:3072
	ds_read_b128 v[188:191], v160 offset:4096
	ds_read_b128 v[196:199], v160 offset:5120
	ds_read_b128 v[200:203], v160 offset:6144
	ds_read_b128 v[204:207], v160 offset:7168
	global_load_lds_dwordx4 v[156:157], off
	v_lshl_add_u64 v[156:157], s[50:51], 0, v[142:143]
	s_add_i32 m0, s58, 0xe000
	s_nop 0
	global_load_lds_dwordx4 v[156:157], off
	s_waitcnt lgkmcnt(8)
	s_barrier
	s_waitcnt lgkmcnt(0)
	s_cmp_eq_u32 s92, -2
	s_cbranch_scc1 .Lz1_0_first
	v_mfma_f32_16x16x32_bf16 v[124:127], v[148:151], v[172:175], v[124:127]
	v_mfma_f32_16x16x32_bf16 v[120:123], v[164:167], v[172:175], v[120:123]
	v_mfma_f32_16x16x32_bf16 v[108:111], v[148:151], v[180:183], v[108:111]
	v_mfma_f32_16x16x32_bf16 v[104:107], v[164:167], v[180:183], v[104:107]
	v_mfma_f32_16x16x32_bf16 v[92:95], v[148:151], v[188:191], v[92:95]
	v_mfma_f32_16x16x32_bf16 v[88:91], v[164:167], v[188:191], v[88:91]
	v_mfma_f32_16x16x32_bf16 v[76:79], v[148:151], v[200:203], v[76:79]
	v_mfma_f32_16x16x32_bf16 v[72:75], v[164:167], v[200:203], v[72:75]
	v_mfma_f32_16x16x32_bf16 v[124:127], v[152:155], v[176:179], v[124:127]
	v_mfma_f32_16x16x32_bf16 v[120:123], v[168:171], v[176:179], v[120:123]
	v_mfma_f32_16x16x32_bf16 v[108:111], v[152:155], v[184:187], v[108:111]
	v_mfma_f32_16x16x32_bf16 v[104:107], v[168:171], v[184:187], v[104:107]
	v_mfma_f32_16x16x32_bf16 v[92:95], v[152:155], v[196:199], v[92:95]
	v_mfma_f32_16x16x32_bf16 v[88:91], v[168:171], v[196:199], v[88:91]
	v_mfma_f32_16x16x32_bf16 v[76:79], v[152:155], v[204:207], v[76:79]
	v_mfma_f32_16x16x32_bf16 v[72:75], v[168:171], v[204:207], v[72:75]
.Lz1_0_join:
	s_barrier
	s_add_i32 s93, s89, s57
	v_lshl_add_u64 v[156:157], s[52:53], 0, v[130:131]
	s_mov_b32 m0, s93
	ds_read_b128 v[208:211], v161
	ds_read_b128 v[212:215], v161 offset:1024
	ds_read_b128 v[216:219], v161 offset:2048
	ds_read_b128 v[220:223], v161 offset:3072
	global_load_lds_dwordx4 v[156:157], off
	v_lshl_add_u64 v[224:225], s[52:53], 0, v[134:135]
	s_add_i32 m0, s93, 0x2000
	s_nop 0
	global_load_lds_dwordx4 v[224:225], off
	s_barrier
	s_waitcnt lgkmcnt(0)
	s_cmp_eq_u32 s92, -2
	s_cbranch_scc1 .Lz1_1_first
	v_mfma_f32_16x16x32_bf16 v[116:119], v[208:211], v[172:175], v[116:119]
	v_mfma_f32_16x16x32_bf16 v[112:115], v[216:219], v[172:175], v[112:115]
	v_mfma_f32_16x16x32_bf16 v[100:103], v[208:211], v[180:183], v[100:103]
	v_mfma_f32_16x16x32_bf16 v[96:99], v[216:219], v[180:183], v[96:99]
	v_mfma_f32_16x16x32_bf16 v[84:87], v[208:211], v[188:191], v[84:87]
	v_mfma_f32_16x16x32_bf16 v[80:83], v[216:219], v[188:191], v[80:83]
	v_mfma_f32_16x16x32_bf16 v[68:71], v[208:211], v[200:203], v[68:71]
	v_mfma_f32_16x16x32_bf16 v[64:67], v[216:219], v[200:203], v[64:67]
	v_mfma_f32_16x16x32_bf16 v[116:119], v[212:215], v[176:179], v[116:119]
	v_mfma_f32_16x16x32_bf16 v[112:115], v[220:223], v[176:179], v[112:115]
	v_mfma_f32_16x16x32_bf16 v[100:103], v[212:215], v[184:187], v[100:103]
	v_mfma_f32_16x16x32_bf16 v[96:99], v[220:223], v[184:187], v[96:99]
	v_mfma_f32_16x16x32_bf16 v[84:87], v[212:215], v[196:199], v[84:87]
	v_mfma_f32_16x16x32_bf16 v[80:83], v[220:223], v[196:199], v[80:83]
	v_mfma_f32_16x16x32_bf16 v[68:71], v[212:215], v[204:207], v[68:71]
	v_mfma_f32_16x16x32_bf16 v[64:67], v[220:223], v[204:207], v[64:67]
.Lz1_1_join:
	s_mov_b32 m0, s58
	v_lshl_add_u64 v[226:227], s[54:55], 0, v[128:129]
	s_barrier
	ds_read_b128 v[172:175], v160 offset:16384
	ds_read_b128 v[176:179], v160 offset:17408
	ds_read_b128 v[180:183], v160 offset:18432
	ds_read_b128 v[184:187], v160 offset:19456
	ds_read_b128 v[188:191], v160 offset:20480
	ds_read_b128 v[196:199], v160 offset:21504
	ds_read_b128 v[200:203], v160 offset:22528
	ds_read_b128 v[204:207], v160 offset:23552
	global_load_lds_dwordx4 v[226:227], off
	v_lshl_add_u64 v[228:229], s[54:55], 0, v[132:133]
	s_mov_b32 m0, s59
	s_nop 0
	global_load_lds_dwordx4 v[228:229], off
	s_barrier
	s_waitcnt lgkmcnt(0)
	s_cmp_eq_u32 s92, -2
	s_cbranch_scc1 .Lz1_2_first
	v_mfma_f32_16x16x32_bf16 v[60:63], v[148:151], v[172:175], v[60:63]
	v_mfma_f32_16x16x32_bf16 v[56:59], v[164:167], v[172:175], v[56:59]
	v_mfma_f32_16x16x32_bf16 v[44:47], v[148:151], v[180:183], v[44:47]
	v_mfma_f32_16x16x32_bf16 v[40:43], v[164:167], v[180:183], v[40:43]
	v_mfma_f32_16x16x32_bf16 v[28:31], v[148:151], v[188:191], v[28:31]
	v_mfma_f32_16x16x32_bf16 v[24:27], v[164:167], v[188:191], v[24:27]
	v_mfma_f32_16x16x32_bf16 v[12:15], v[148:151], v[200:203], v[12:15]
	v_mfma_f32_16x16x32_bf16 v[8:11], v[164:167], v[200:203], v[8:11]
	v_mfma_f32_16x16x32_bf16 v[60:63], v[152:155], v[176:179], v[60:63]
	v_mfma_f32_16x16x32_bf16 v[56:59], v[168:171], v[176:179], v[56:59]
	v_mfma_f32_16x16x32_bf16 v[44:47], v[152:155], v[184:187], v[44:47]
	v_mfma_f32_16x16x32_bf16 v[40:43], v[168:171], v[184:187], v[40:43]
	v_mfma_f32_16x16x32_bf16 v[28:31], v[152:155], v[196:199], v[28:31]
	v_mfma_f32_16x16x32_bf16 v[24:27], v[168:171], v[196:199], v[24:27]
	v_mfma_f32_16x16x32_bf16 v[12:15], v[152:155], v[204:207], v[12:15]
	v_mfma_f32_16x16x32_bf16 v[8:11], v[168:171], v[204:207], v[8:11]

.Lz1_3_join:
	s_add_i32 s93, 0, 0x18000
	v_add_u32_e32 v136, s93, v158
	s_barrier
	ds_read_b128 v[148:151], v136
	ds_read_b128 v[152:155], v136 offset:1024
	ds_read_b128 v[164:167], v136 offset:2048
	ds_read_b128 v[168:171], v136 offset:3072
	s_add_u32 s54, s54, 0x40000
	s_addc_u32 s55, s55, 0
	s_mov_b32 m0, s60
	v_lshl_add_u64 v[208:209], s[54:55], 0, v[128:129]
	ds_read_b128 v[172:175], v160 offset:32768
	ds_read_b128 v[176:179], v160 offset:33792
	ds_read_b128 v[180:183], v160 offset:34816
	ds_read_b128 v[184:187], v160 offset:35840
	ds_read_b128 v[188:191], v160 offset:36864
	ds_read_b128 v[196:199], v160 offset:37888
	ds_read_b128 v[200:203], v160 offset:38912
	ds_read_b128 v[204:207], v160 offset:39936
	global_load_lds_dwordx4 v[208:209], off
	v_lshl_add_u64 v[208:209], s[54:55], 0, v[132:133]
	s_mov_b32 m0, s61
	s_nop 0
	global_load_lds_dwordx4 v[208:209], off
	s_waitcnt lgkmcnt(8)
	s_barrier
	s_waitcnt lgkmcnt(0)
	v_mfma_f32_16x16x32_bf16 v[124:127], v[148:151], v[172:175], v[124:127]
	v_mfma_f32_16x16x32_bf16 v[120:123], v[164:167], v[172:175], v[120:123]
	v_mfma_f32_16x16x32_bf16 v[108:111], v[148:151], v[180:183], v[108:111]
	v_mfma_f32_16x16x32_bf16 v[104:107], v[164:167], v[180:183], v[104:107]
	v_mfma_f32_16x16x32_bf16 v[92:95], v[148:151], v[188:191], v[92:95]
	v_mfma_f32_16x16x32_bf16 v[88:91], v[164:167], v[188:191], v[88:91]
	v_mfma_f32_16x16x32_bf16 v[76:79], v[148:151], v[200:203], v[76:79]
	v_mfma_f32_16x16x32_bf16 v[72:75], v[164:167], v[200:203], v[72:75]
	v_mfma_f32_16x16x32_bf16 v[124:127], v[152:155], v[176:179], v[124:127]
	v_mfma_f32_16x16x32_bf16 v[120:123], v[168:171], v[176:179], v[120:123]
	v_mfma_f32_16x16x32_bf16 v[108:111], v[152:155], v[184:187], v[108:111]
	v_mfma_f32_16x16x32_bf16 v[104:107], v[168:171], v[184:187], v[104:107]
	v_mfma_f32_16x16x32_bf16 v[92:95], v[152:155], v[196:199], v[92:95]
	v_mfma_f32_16x16x32_bf16 v[88:91], v[168:171], v[196:199], v[88:91]
	v_mfma_f32_16x16x32_bf16 v[76:79], v[152:155], v[204:207], v[76:79]
	v_mfma_f32_16x16x32_bf16 v[72:75], v[168:171], v[204:207], v[72:75]
	s_barrier
	s_add_i32 s54, 0, 0x1c000
	s_add_i32 s55, s93, s57
	v_add_u32_e32 v136, s54, v158
	v_lshl_add_u64 v[156:157], v[156:157], 0, s[0:1]
	s_mov_b32 m0, s55
	ds_read_b128 v[208:211], v136
	ds_read_b128 v[212:215], v136 offset:1024
	ds_read_b128 v[216:219], v136 offset:2048
	ds_read_b128 v[220:223], v136 offset:3072
	global_load_lds_dwordx4 v[156:157], off
	v_lshl_add_u64 v[156:157], v[224:225], 0, s[0:1]
	s_add_i32 m0, s55, 0x2000
	s_nop 0
	global_load_lds_dwordx4 v[156:157], off
	s_barrier
	s_waitcnt lgkmcnt(0)
	v_mfma_f32_16x16x32_bf16 v[116:119], v[208:211], v[172:175], v[116:119]
	v_mfma_f32_16x16x32_bf16 v[112:115], v[216:219], v[172:175], v[112:115]
	v_mfma_f32_16x16x32_bf16 v[100:103], v[208:211], v[180:183], v[100:103]
	v_mfma_f32_16x16x32_bf16 v[96:99], v[216:219], v[180:183], v[96:99]
	v_mfma_f32_16x16x32_bf16 v[84:87], v[208:211], v[188:191], v[84:87]
	v_mfma_f32_16x16x32_bf16 v[80:83], v[216:219], v[188:191], v[80:83]
	v_mfma_f32_16x16x32_bf16 v[68:71], v[208:211], v[200:203], v[68:71]
	v_mfma_f32_16x16x32_bf16 v[64:67], v[216:219], v[200:203], v[64:67]
	v_mfma_f32_16x16x32_bf16 v[116:119], v[212:215], v[176:179], v[116:119]
	v_mfma_f32_16x16x32_bf16 v[112:115], v[220:223], v[176:179], v[112:115]
	v_mfma_f32_16x16x32_bf16 v[100:103], v[212:215], v[184:187], v[100:103]
	v_mfma_f32_16x16x32_bf16 v[96:99], v[220:223], v[184:187], v[96:99]
	v_mfma_f32_16x16x32_bf16 v[84:87], v[212:215], v[196:199], v[84:87]
	v_mfma_f32_16x16x32_bf16 v[80:83], v[220:223], v[196:199], v[80:83]
	v_mfma_f32_16x16x32_bf16 v[68:71], v[212:215], v[204:207], v[68:71]
	v_mfma_f32_16x16x32_bf16 v[64:67], v[220:223], v[204:207], v[64:67]
	s_mov_b32 m0, s65
	v_lshl_add_u64 v[156:157], v[226:227], 0, s[0:1]
	s_waitcnt vmcnt(10)
	s_barrier
	ds_read_b128 v[172:175], v160 offset:49152
	ds_read_b128 v[176:179], v160 offset:50176
	ds_read_b128 v[180:183], v160 offset:51200
	ds_read_b128 v[184:187], v160 offset:52224
	ds_read_b128 v[188:191], v160 offset:53248
	ds_read_b128 v[196:199], v160 offset:54272
	ds_read_b128 v[200:203], v160 offset:55296
	ds_read_b128 v[204:207], v160 offset:56320
	global_load_lds_dwordx4 v[156:157], off
	v_lshl_add_u64 v[156:157], v[228:229], 0, s[0:1]
	s_mov_b32 m0, s66
	s_nop 0
	global_load_lds_dwordx4 v[156:157], off
	s_barrier
	s_waitcnt lgkmcnt(0)
	v_mfma_f32_16x16x32_bf16 v[60:63], v[148:151], v[172:175], v[60:63]
	v_mfma_f32_16x16x32_bf16 v[56:59], v[164:167], v[172:175], v[56:59]
	v_mfma_f32_16x16x32_bf16 v[44:47], v[148:151], v[180:183], v[44:47]
	v_mfma_f32_16x16x32_bf16 v[40:43], v[164:167], v[180:183], v[40:43]
	v_mfma_f32_16x16x32_bf16 v[28:31], v[148:151], v[188:191], v[28:31]
	v_mfma_f32_16x16x32_bf16 v[24:27], v[164:167], v[188:191], v[24:27]
	v_mfma_f32_16x16x32_bf16 v[12:15], v[148:151], v[200:203], v[12:15]
	v_mfma_f32_16x16x32_bf16 v[8:11], v[164:167], v[200:203], v[8:11]
	v_mfma_f32_16x16x32_bf16 v[60:63], v[152:155], v[176:179], v[60:63]
	v_mfma_f32_16x16x32_bf16 v[56:59], v[168:171], v[176:179], v[56:59]
	v_mfma_f32_16x16x32_bf16 v[44:47], v[152:155], v[184:187], v[44:47]
	v_mfma_f32_16x16x32_bf16 v[40:43], v[168:171], v[184:187], v[40:43]
	v_mfma_f32_16x16x32_bf16 v[28:31], v[152:155], v[196:199], v[28:31]
	v_mfma_f32_16x16x32_bf16 v[24:27], v[168:171], v[196:199], v[24:27]
	v_mfma_f32_16x16x32_bf16 v[12:15], v[152:155], v[204:207], v[12:15]
	v_mfma_f32_16x16x32_bf16 v[8:11], v[168:171], v[204:207], v[8:11]
	s_barrier
	s_add_u32 s52, s52, 0x10080
	s_addc_u32 s53, s53, 0
	s_add_i32 s54, s54, s57
	v_lshl_add_u64 v[148:149], s[52:53], 0, v[130:131]
	s_mov_b32 m0, s54
	s_nop 0
	global_load_lds_dwordx4 v[148:149], off
	v_lshl_add_u64 v[148:149], s[52:53], 0, v[134:135]
	s_add_i32 m0, s54, 0x2000
	s_nop 0
	global_load_lds_dwordx4 v[148:149], off
	s_waitcnt vmcnt(6)
	s_barrier
	v_mfma_f32_16x16x32_bf16 v[52:55], v[208:211], v[172:175], v[52:55]
	v_mfma_f32_16x16x32_bf16 v[48:51], v[216:219], v[172:175], v[48:51]
	v_mfma_f32_16x16x32_bf16 v[36:39], v[208:211], v[180:183], v[36:39]
	v_mfma_f32_16x16x32_bf16 v[32:35], v[216:219], v[180:183], v[32:35]
	v_mfma_f32_16x16x32_bf16 v[20:23], v[208:211], v[188:191], v[20:23]
	v_mfma_f32_16x16x32_bf16 v[16:19], v[216:219], v[188:191], v[16:19]
	v_mfma_f32_16x16x32_bf16 v[4:7], v[208:211], v[200:203], v[4:7]
	v_mfma_f32_16x16x32_bf16 v[0:3], v[216:219], v[200:203], v[0:3]
	v_mfma_f32_16x16x32_bf16 v[52:55], v[212:215], v[176:179], v[52:55]
	v_mfma_f32_16x16x32_bf16 v[48:51], v[220:223], v[176:179], v[48:51]
	v_mfma_f32_16x16x32_bf16 v[36:39], v[212:215], v[184:187], v[36:39]
	v_mfma_f32_16x16x32_bf16 v[32:35], v[220:223], v[184:187], v[32:35]
	v_mfma_f32_16x16x32_bf16 v[20:23], v[212:215], v[196:199], v[20:23]
	v_mfma_f32_16x16x32_bf16 v[16:19], v[220:223], v[196:199], v[16:19]
	v_mfma_f32_16x16x32_bf16 v[4:7], v[212:215], v[204:207], v[4:7]
	v_mfma_f32_16x16x32_bf16 v[0:3], v[220:223], v[204:207], v[0:3]
	s_add_i32 s92, s92, 2
	s_add_u32 s50, s50, 0x100
	s_addc_u32 s51, s51, 0
	s_add_u32 s45, s45, 0x100
	s_addc_u32 s91, s91, 0
	s_cmp_gt_u32 s92, 13
	s_barrier
	s_cbranch_scc0 .LBB0_178
	s_branch .Lz1_skip

.LBB0_342:
	ds_read_b128 v[146:149], v143
	ds_read_b128 v[150:153], v143 offset:1024
	ds_read_b128 v[154:157], v143 offset:2048
	ds_read_b128 v[158:161], v143 offset:3072
	s_add_u32 s46, s44, 0xfffc0080
	s_addc_u32 s47, s45, -1
	s_cmp_eq_u32 s67, 12
	s_cselect_b32 s49, s9, s47
	s_cselect_b32 s48, s63, s46
	s_cselect_b32 s47, s7, s66
	s_cselect_b32 s46, s64, s65
	v_lshl_add_u64 v[190:191], s[44:45], 0, v[136:137]
	s_add_i32 m0, s43, 0xc000
	ds_read_b128 v[162:165], v144
	ds_read_b128 v[166:169], v144 offset:1024
	ds_read_b128 v[170:173], v144 offset:2048
	ds_read_b128 v[174:177], v144 offset:3072
	ds_read_b128 v[178:181], v144 offset:4096
	ds_read_b128 v[182:185], v144 offset:5120
	ds_read_b128 v[186:189], v144 offset:6144
	ds_read_b128 v[196:199], v144 offset:7168
	global_load_lds_dwordx4 v[190:191], off
	v_lshl_add_u64 v[190:191], s[44:45], 0, v[138:139]
	s_add_i32 m0, s43, 0xe000
	s_nop 0
	global_load_lds_dwordx4 v[190:191], off
	s_waitcnt lgkmcnt(8)
	s_barrier
	s_waitcnt lgkmcnt(0)
	v_mfma_f32_16x16x32_bf16 v[124:127], v[146:149], v[162:165], v[124:127]
	v_mfma_f32_16x16x32_bf16 v[120:123], v[154:157], v[162:165], v[120:123]
	v_mfma_f32_16x16x32_bf16 v[108:111], v[146:149], v[170:173], v[108:111]
	v_mfma_f32_16x16x32_bf16 v[104:107], v[154:157], v[170:173], v[104:107]
	v_mfma_f32_16x16x32_bf16 v[92:95], v[146:149], v[178:181], v[92:95]
	v_mfma_f32_16x16x32_bf16 v[88:91], v[154:157], v[178:181], v[88:91]
	v_mfma_f32_16x16x32_bf16 v[76:79], v[146:149], v[186:189], v[76:79]
	v_mfma_f32_16x16x32_bf16 v[72:75], v[154:157], v[186:189], v[72:75]
	v_mfma_f32_16x16x32_bf16 v[124:127], v[150:153], v[166:169], v[124:127]
	v_mfma_f32_16x16x32_bf16 v[120:123], v[158:161], v[166:169], v[120:123]
	v_mfma_f32_16x16x32_bf16 v[108:111], v[150:153], v[174:177], v[108:111]
	v_mfma_f32_16x16x32_bf16 v[104:107], v[158:161], v[174:177], v[104:107]
	v_mfma_f32_16x16x32_bf16 v[92:95], v[150:153], v[182:185], v[92:95]
	v_mfma_f32_16x16x32_bf16 v[88:91], v[158:161], v[182:185], v[88:91]
	v_mfma_f32_16x16x32_bf16 v[76:79], v[150:153], v[196:199], v[76:79]
	v_mfma_f32_16x16x32_bf16 v[72:75], v[158:161], v[196:199], v[72:75]
	s_barrier
	s_add_i32 s84, s60, s50
	v_lshl_add_u64 v[190:191], s[46:47], 0, v[132:133]
	s_mov_b32 m0, s84
	ds_read_b128 v[200:203], v145
	ds_read_b128 v[204:207], v145 offset:1024
	ds_read_b128 v[208:211], v145 offset:2048
	ds_read_b128 v[212:215], v145 offset:3072
	global_load_lds_dwordx4 v[190:191], off
	v_lshl_add_u64 v[216:217], s[46:47], 0, v[128:129]
	s_add_i32 m0, s84, 0x2000
	s_nop 0
	global_load_lds_dwordx4 v[216:217], off
	s_barrier
	s_waitcnt lgkmcnt(0)
	v_mfma_f32_16x16x32_bf16 v[116:119], v[200:203], v[162:165], v[116:119]
	v_mfma_f32_16x16x32_bf16 v[112:115], v[208:211], v[162:165], v[112:115]
	v_mfma_f32_16x16x32_bf16 v[100:103], v[200:203], v[170:173], v[100:103]
	v_mfma_f32_16x16x32_bf16 v[96:99], v[208:211], v[170:173], v[96:99]
	v_mfma_f32_16x16x32_bf16 v[84:87], v[200:203], v[178:181], v[84:87]
	v_mfma_f32_16x16x32_bf16 v[80:83], v[208:211], v[178:181], v[80:83]
	v_mfma_f32_16x16x32_bf16 v[68:71], v[200:203], v[186:189], v[68:71]
	v_mfma_f32_16x16x32_bf16 v[64:67], v[208:211], v[186:189], v[64:67]
	v_mfma_f32_16x16x32_bf16 v[116:119], v[204:207], v[166:169], v[116:119]
	v_mfma_f32_16x16x32_bf16 v[112:115], v[212:215], v[166:169], v[112:115]
	v_mfma_f32_16x16x32_bf16 v[100:103], v[204:207], v[174:177], v[100:103]
	v_mfma_f32_16x16x32_bf16 v[96:99], v[212:215], v[174:177], v[96:99]
	v_mfma_f32_16x16x32_bf16 v[84:87], v[204:207], v[182:185], v[84:87]
	v_mfma_f32_16x16x32_bf16 v[80:83], v[212:215], v[182:185], v[80:83]
	v_mfma_f32_16x16x32_bf16 v[68:71], v[204:207], v[196:199], v[68:71]
	v_mfma_f32_16x16x32_bf16 v[64:67], v[212:215], v[196:199], v[64:67]
	s_mov_b32 m0, s43
	v_lshl_add_u64 v[218:219], s[48:49], 0, v[134:135]
	s_barrier
	ds_read_b128 v[162:165], v144 offset:16384
	ds_read_b128 v[166:169], v144 offset:17408
	ds_read_b128 v[170:173], v144 offset:18432
	ds_read_b128 v[174:177], v144 offset:19456
	ds_read_b128 v[178:181], v144 offset:20480
	ds_read_b128 v[182:185], v144 offset:21504
	ds_read_b128 v[186:189], v144 offset:22528
	ds_read_b128 v[196:199], v144 offset:23552
	global_load_lds_dwordx4 v[218:219], off
	v_lshl_add_u64 v[220:221], s[48:49], 0, v[130:131]
	s_mov_b32 m0, s52
	s_nop 0
	global_load_lds_dwordx4 v[220:221], off
	s_barrier
	s_waitcnt lgkmcnt(0)
	v_mfma_f32_16x16x32_bf16 v[60:63], v[146:149], v[162:165], v[60:63]
	v_mfma_f32_16x16x32_bf16 v[56:59], v[154:157], v[162:165], v[56:59]
	v_mfma_f32_16x16x32_bf16 v[44:47], v[146:149], v[170:173], v[44:47]
	v_mfma_f32_16x16x32_bf16 v[40:43], v[154:157], v[170:173], v[40:43]
	v_mfma_f32_16x16x32_bf16 v[28:31], v[146:149], v[178:181], v[28:31]
	v_mfma_f32_16x16x32_bf16 v[24:27], v[154:157], v[178:181], v[24:27]
	v_mfma_f32_16x16x32_bf16 v[12:15], v[146:149], v[186:189], v[12:15]
	v_mfma_f32_16x16x32_bf16 v[8:11], v[154:157], v[186:189], v[8:11]
	v_mfma_f32_16x16x32_bf16 v[60:63], v[150:153], v[166:169], v[60:63]
	v_mfma_f32_16x16x32_bf16 v[56:59], v[158:161], v[166:169], v[56:59]
	v_mfma_f32_16x16x32_bf16 v[44:47], v[150:153], v[174:177], v[44:47]
	v_mfma_f32_16x16x32_bf16 v[40:43], v[158:161], v[174:177], v[40:43]
	v_mfma_f32_16x16x32_bf16 v[28:31], v[150:153], v[182:185], v[28:31]
	v_mfma_f32_16x16x32_bf16 v[24:27], v[158:161], v[182:185], v[24:27]
	v_mfma_f32_16x16x32_bf16 v[12:15], v[150:153], v[196:199], v[12:15]
	v_mfma_f32_16x16x32_bf16 v[8:11], v[158:161], v[196:199], v[8:11]
	s_barrier
	s_add_u32 s84, s46, 0x10000
	s_addc_u32 s85, s47, 0
	s_add_i32 s89, s61, s50
	v_lshl_add_u64 v[146:147], s[84:85], 0, v[132:133]
	s_mov_b32 m0, s89
	s_nop 0
	global_load_lds_dwordx4 v[146:147], off
	v_lshl_add_u64 v[146:147], s[84:85], 0, v[128:129]
	s_add_i32 m0, s89, 0x2000
	s_nop 0
	global_load_lds_dwordx4 v[146:147], off
	s_waitcnt vmcnt(6)
	s_barrier
	v_mfma_f32_16x16x32_bf16 v[52:55], v[200:203], v[162:165], v[52:55]
	v_mfma_f32_16x16x32_bf16 v[48:51], v[208:211], v[162:165], v[48:51]
	v_mfma_f32_16x16x32_bf16 v[36:39], v[200:203], v[170:173], v[36:39]
	v_mfma_f32_16x16x32_bf16 v[32:35], v[208:211], v[170:173], v[32:35]
	v_mfma_f32_16x16x32_bf16 v[20:23], v[200:203], v[178:181], v[20:23]
	v_mfma_f32_16x16x32_bf16 v[16:19], v[208:211], v[178:181], v[16:19]
	v_mfma_f32_16x16x32_bf16 v[4:7], v[200:203], v[186:189], v[4:7]
	v_mfma_f32_16x16x32_bf16 v[0:3], v[208:211], v[186:189], v[0:3]
	v_mfma_f32_16x16x32_bf16 v[52:55], v[204:207], v[166:169], v[52:55]
	v_mfma_f32_16x16x32_bf16 v[48:51], v[212:215], v[166:169], v[48:51]
	v_mfma_f32_16x16x32_bf16 v[36:39], v[204:207], v[174:177], v[36:39]
	v_mfma_f32_16x16x32_bf16 v[32:35], v[212:215], v[174:177], v[32:35]
	v_mfma_f32_16x16x32_bf16 v[20:23], v[204:207], v[182:185], v[20:23]
	v_mfma_f32_16x16x32_bf16 v[16:19], v[212:215], v[182:185], v[16:19]
	v_mfma_f32_16x16x32_bf16 v[4:7], v[204:207], v[196:199], v[4:7]
	v_mfma_f32_16x16x32_bf16 v[0:3], v[212:215], v[196:199], v[0:3]
	s_add_i32 s84, 0, 0x18000
	v_add_u32_e32 v158, s84, v141
	s_barrier
	ds_read_b128 v[146:149], v158
	ds_read_b128 v[150:153], v158 offset:1024
	ds_read_b128 v[154:157], v158 offset:2048
	ds_read_b128 v[158:161], v158 offset:3072
	s_add_u32 s48, s48, 0x40000
	s_addc_u32 s49, s49, 0
	s_mov_b32 m0, s53
	v_lshl_add_u64 v[200:201], s[48:49], 0, v[134:135]
	ds_read_b128 v[162:165], v144 offset:32768
	ds_read_b128 v[166:169], v144 offset:33792
	ds_read_b128 v[170:173], v144 offset:34816
	ds_read_b128 v[174:177], v144 offset:35840
	ds_read_b128 v[178:181], v144 offset:36864
	ds_read_b128 v[182:185], v144 offset:37888
	ds_read_b128 v[186:189], v144 offset:38912
	ds_read_b128 v[196:199], v144 offset:39936
	global_load_lds_dwordx4 v[200:201], off
	v_lshl_add_u64 v[200:201], s[48:49], 0, v[130:131]
	s_mov_b32 m0, s54
	s_nop 0
	global_load_lds_dwordx4 v[200:201], off
	s_waitcnt lgkmcnt(8)
	s_barrier
	s_waitcnt lgkmcnt(0)
	v_mfma_f32_16x16x32_bf16 v[124:127], v[146:149], v[162:165], v[124:127]
	v_mfma_f32_16x16x32_bf16 v[120:123], v[154:157], v[162:165], v[120:123]
	v_mfma_f32_16x16x32_bf16 v[108:111], v[146:149], v[170:173], v[108:111]
	v_mfma_f32_16x16x32_bf16 v[104:107], v[154:157], v[170:173], v[104:107]
	v_mfma_f32_16x16x32_bf16 v[92:95], v[146:149], v[178:181], v[92:95]
	v_mfma_f32_16x16x32_bf16 v[88:91], v[154:157], v[178:181], v[88:91]
	v_mfma_f32_16x16x32_bf16 v[76:79], v[146:149], v[186:189], v[76:79]
	v_mfma_f32_16x16x32_bf16 v[72:75], v[154:157], v[186:189], v[72:75]
	v_mfma_f32_16x16x32_bf16 v[124:127], v[150:153], v[166:169], v[124:127]
	v_mfma_f32_16x16x32_bf16 v[120:123], v[158:161], v[166:169], v[120:123]
	v_mfma_f32_16x16x32_bf16 v[108:111], v[150:153], v[174:177], v[108:111]
	v_mfma_f32_16x16x32_bf16 v[104:107], v[158:161], v[174:177], v[104:107]
	v_mfma_f32_16x16x32_bf16 v[92:95], v[150:153], v[182:185], v[92:95]
	v_mfma_f32_16x16x32_bf16 v[88:91], v[158:161], v[182:185], v[88:91]
	v_mfma_f32_16x16x32_bf16 v[76:79], v[150:153], v[196:199], v[76:79]
	v_mfma_f32_16x16x32_bf16 v[72:75], v[158:161], v[196:199], v[72:75]
	s_barrier
	s_add_i32 s48, 0, 0x1c000
	s_add_i32 s49, s84, s50
	v_add_u32_e32 v195, s48, v141
	v_lshl_add_u64 v[190:191], v[190:191], 0, s[0:1]
	s_mov_b32 m0, s49
	ds_read_b128 v[200:203], v195
	ds_read_b128 v[204:207], v195 offset:1024
	ds_read_b128 v[208:211], v195 offset:2048
	ds_read_b128 v[212:215], v195 offset:3072
	global_load_lds_dwordx4 v[190:191], off
	v_lshl_add_u64 v[190:191], v[216:217], 0, s[0:1]
	s_add_i32 m0, s49, 0x2000
	s_nop 0
	global_load_lds_dwordx4 v[190:191], off
	s_barrier
	s_waitcnt lgkmcnt(0)
	v_mfma_f32_16x16x32_bf16 v[116:119], v[200:203], v[162:165], v[116:119]
	v_mfma_f32_16x16x32_bf16 v[112:115], v[208:211], v[162:165], v[112:115]
	v_mfma_f32_16x16x32_bf16 v[100:103], v[200:203], v[170:173], v[100:103]
	v_mfma_f32_16x16x32_bf16 v[96:99], v[208:211], v[170:173], v[96:99]
	v_mfma_f32_16x16x32_bf16 v[84:87], v[200:203], v[178:181], v[84:87]
	v_mfma_f32_16x16x32_bf16 v[80:83], v[208:211], v[178:181], v[80:83]
	v_mfma_f32_16x16x32_bf16 v[68:71], v[200:203], v[186:189], v[68:71]
	v_mfma_f32_16x16x32_bf16 v[64:67], v[208:211], v[186:189], v[64:67]
	v_mfma_f32_16x16x32_bf16 v[116:119], v[204:207], v[166:169], v[116:119]
	v_mfma_f32_16x16x32_bf16 v[112:115], v[212:215], v[166:169], v[112:115]
	v_mfma_f32_16x16x32_bf16 v[100:103], v[204:207], v[174:177], v[100:103]
	v_mfma_f32_16x16x32_bf16 v[96:99], v[212:215], v[174:177], v[96:99]
	v_mfma_f32_16x16x32_bf16 v[84:87], v[204:207], v[182:185], v[84:87]
	v_mfma_f32_16x16x32_bf16 v[80:83], v[212:215], v[182:185], v[80:83]
	v_mfma_f32_16x16x32_bf16 v[68:71], v[204:207], v[196:199], v[68:71]
	v_mfma_f32_16x16x32_bf16 v[64:67], v[212:215], v[196:199], v[64:67]
	s_mov_b32 m0, s57
	v_lshl_add_u64 v[190:191], v[218:219], 0, s[0:1]
	s_barrier
	ds_read_b128 v[162:165], v144 offset:49152
	ds_read_b128 v[166:169], v144 offset:50176
	ds_read_b128 v[170:173], v144 offset:51200
	ds_read_b128 v[174:177], v144 offset:52224
	ds_read_b128 v[178:181], v144 offset:53248
	ds_read_b128 v[182:185], v144 offset:54272
	ds_read_b128 v[186:189], v144 offset:55296
	ds_read_b128 v[196:199], v144 offset:56320
	global_load_lds_dwordx4 v[190:191], off
	v_lshl_add_u64 v[190:191], v[220:221], 0, s[0:1]
	s_mov_b32 m0, s58
	s_nop 0
	global_load_lds_dwordx4 v[190:191], off
	s_barrier
	s_waitcnt lgkmcnt(0)
	v_mfma_f32_16x16x32_bf16 v[60:63], v[146:149], v[162:165], v[60:63]
	v_mfma_f32_16x16x32_bf16 v[56:59], v[154:157], v[162:165], v[56:59]
	v_mfma_f32_16x16x32_bf16 v[44:47], v[146:149], v[170:173], v[44:47]
	v_mfma_f32_16x16x32_bf16 v[40:43], v[154:157], v[170:173], v[40:43]
	v_mfma_f32_16x16x32_bf16 v[28:31], v[146:149], v[178:181], v[28:31]
	v_mfma_f32_16x16x32_bf16 v[24:27], v[154:157], v[178:181], v[24:27]
	v_mfma_f32_16x16x32_bf16 v[12:15], v[146:149], v[186:189], v[12:15]
	v_mfma_f32_16x16x32_bf16 v[8:11], v[154:157], v[186:189], v[8:11]
	v_mfma_f32_16x16x32_bf16 v[60:63], v[150:153], v[166:169], v[60:63]
	v_mfma_f32_16x16x32_bf16 v[56:59], v[158:161], v[166:169], v[56:59]
	v_mfma_f32_16x16x32_bf16 v[44:47], v[150:153], v[174:177], v[44:47]
	v_mfma_f32_16x16x32_bf16 v[40:43], v[158:161], v[174:177], v[40:43]
	v_mfma_f32_16x16x32_bf16 v[28:31], v[150:153], v[182:185], v[28:31]
	v_mfma_f32_16x16x32_bf16 v[24:27], v[158:161], v[182:185], v[24:27]
	v_mfma_f32_16x16x32_bf16 v[12:15], v[150:153], v[196:199], v[12:15]
	v_mfma_f32_16x16x32_bf16 v[8:11], v[158:161], v[196:199], v[8:11]
	s_barrier
	s_add_u32 s46, s46, 0x10080
	s_addc_u32 s47, s47, 0
	s_add_i32 s48, s48, s50
	v_lshl_add_u64 v[146:147], s[46:47], 0, v[132:133]
	s_mov_b32 m0, s48
	s_nop 0
	global_load_lds_dwordx4 v[146:147], off
	v_lshl_add_u64 v[146:147], s[46:47], 0, v[128:129]
	s_add_i32 m0, s48, 0x2000
	s_nop 0
	global_load_lds_dwordx4 v[146:147], off
	s_waitcnt vmcnt(6)
	s_barrier
	v_mfma_f32_16x16x32_bf16 v[52:55], v[200:203], v[162:165], v[52:55]
	v_mfma_f32_16x16x32_bf16 v[48:51], v[208:211], v[162:165], v[48:51]
	v_mfma_f32_16x16x32_bf16 v[36:39], v[200:203], v[170:173], v[36:39]
	v_mfma_f32_16x16x32_bf16 v[32:35], v[208:211], v[170:173], v[32:35]
	v_mfma_f32_16x16x32_bf16 v[20:23], v[200:203], v[178:181], v[20:23]
	v_mfma_f32_16x16x32_bf16 v[16:19], v[208:211], v[178:181], v[16:19]
	v_mfma_f32_16x16x32_bf16 v[4:7], v[200:203], v[186:189], v[4:7]
	v_mfma_f32_16x16x32_bf16 v[0:3], v[208:211], v[186:189], v[0:3]
	v_mfma_f32_16x16x32_bf16 v[52:55], v[204:207], v[166:169], v[52:55]
	v_mfma_f32_16x16x32_bf16 v[48:51], v[212:215], v[166:169], v[48:51]
	v_mfma_f32_16x16x32_bf16 v[36:39], v[204:207], v[174:177], v[36:39]
	v_mfma_f32_16x16x32_bf16 v[32:35], v[212:215], v[174:177], v[32:35]
	v_mfma_f32_16x16x32_bf16 v[20:23], v[204:207], v[182:185], v[20:23]
	v_mfma_f32_16x16x32_bf16 v[16:19], v[212:215], v[182:185], v[16:19]
	v_mfma_f32_16x16x32_bf16 v[4:7], v[204:207], v[196:199], v[4:7]
	v_mfma_f32_16x16x32_bf16 v[0:3], v[212:215], v[196:199], v[0:3]
	s_add_i32 s67, s67, 2
	s_add_u32 s44, s44, 0x100
	s_addc_u32 s45, s45, 0
	s_add_u32 s65, s65, 0x100
	s_addc_u32 s66, s66, 0
	s_cmp_gt_u32 s67, 13
	s_barrier
	s_cbranch_scc0 .LBB0_342
	v_cvt_pk_bf16_f32 v124, v124, v125
	v_cvt_pk_bf16_f32 v120, v120, v121
	v_cvt_pk_bf16_f32 v121, v122, v123
	v_cvt_pk_bf16_f32 v122, v116, v117
	v_cvt_pk_bf16_f32 v112, v112, v113
	v_cvt_pk_bf16_f32 v125, v126, v127
	v_cvt_pk_bf16_f32 v118, v118, v119
	v_cvt_pk_bf16_f32 v113, v114, v115
	v_cndmask_b32_e64 v114, v124, v122, s[2:3]
	v_mov_b32_e32 v123, 0
	v_cndmask_b32_e64 v115, v120, v112, s[2:3]
	v_mov_b32_e32 v126, 0
	v_lshl_add_u32 v148, s42, 8, v140
	v_mov_b32_dpp v123, v114 row_ror:8 row_mask:0xf bank_mask:0xf
	v_cndmask_b32_e64 v114, v125, v118, s[2:3]
	v_mov_b32_e32 v119, 0
	v_mov_b32_dpp v126, v115 row_ror:8 row_mask:0xf bank_mask:0xf
	v_mov_b32_e32 v127, 0
	v_mov_b32_dpp v119, v114 row_ror:8 row_mask:0xf bank_mask:0xf
	v_cndmask_b32_e64 v114, v121, v113, s[2:3]
	v_cndmask_b32_e64 v116, v126, v120, s[2:3]
	v_cndmask_b32_e64 v120, v112, v126, s[2:3]
	v_add_u32_e32 v112, -8, v148
	v_mov_b32_dpp v127, v114 row_ror:8 row_mask:0xf bank_mask:0xf
	v_cndmask_b32_e64 v112, v112, v148, s[2:3]
	v_lshl_or_b32 v146, s62, 8, v142
	v_cndmask_b32_e64 v117, v127, v121, s[2:3]
	v_cndmask_b32_e64 v121, v113, v127, s[2:3]
	v_ashrrev_i32_e32 v113, 31, v112
	v_ashrrev_i32_e32 v147, 31, v146
	v_lshlrev_b64 v[112:113], 11, v[112:113]
	v_cndmask_b32_e64 v115, v119, v125, s[2:3]
	v_cndmask_b32_e64 v114, v123, v124, s[2:3]
	v_cndmask_b32_e64 v119, v118, v119, s[2:3]
	v_cndmask_b32_e64 v118, v122, v123, s[2:3]
	v_lshl_add_u64 v[122:123], s[40:41], 0, v[112:113]
	v_lshlrev_b64 v[112:113], 1, v[146:147]
	v_lshl_add_u64 v[122:123], v[122:123], 0, v[112:113]
	global_store_dwordx4 v[122:123], v[114:117], off
	v_cvt_pk_bf16_f32 v108, v108, v109
	v_cvt_pk_bf16_f32 v100, v100, v101
	v_add_u32_e32 v116, 8, v148
	v_cndmask_b32_e64 v114, v148, v116, s[2:3]
	v_ashrrev_i32_e32 v115, 31, v114
	v_lshlrev_b64 v[114:115], 11, v[114:115]
	v_lshl_add_u64 v[114:115], s[40:41], 0, v[114:115]
	v_cvt_pk_bf16_f32 v109, v110, v111
	v_cvt_pk_bf16_f32 v104, v104, v105
	v_cvt_pk_bf16_f32 v105, v106, v107
	v_cvt_pk_bf16_f32 v101, v102, v103
	v_cvt_pk_bf16_f32 v102, v96, v97
	v_cndmask_b32_e64 v96, v108, v100, s[2:3]
	v_mov_b32_e32 v106, 0
	v_lshl_add_u64 v[114:115], v[114:115], 0, v[112:113]
	v_cvt_pk_bf16_f32 v103, v98, v99
	v_mov_b32_dpp v106, v96 row_ror:8 row_mask:0xf bank_mask:0xf
	v_cndmask_b32_e64 v96, v109, v101, s[2:3]
	v_mov_b32_e32 v107, 0
	v_cndmask_b32_e64 v97, v104, v102, s[2:3]
	v_mov_b32_e32 v110, 0
	global_store_dwordx4 v[114:115], v[118:121], off
	v_or_b32_e32 v114, 16, v148
	v_mov_b32_dpp v107, v96 row_ror:8 row_mask:0xf bank_mask:0xf
	v_cndmask_b32_e64 v96, v105, v103, s[2:3]
	v_mov_b32_dpp v110, v97 row_ror:8 row_mask:0xf bank_mask:0xf
	v_mov_b32_e32 v111, 0
	v_cndmask_b32_e64 v98, v110, v104, s[2:3]
	v_cndmask_b32_e64 v104, v116, v114, s[2:3]
	v_mov_b32_dpp v111, v96 row_ror:8 row_mask:0xf bank_mask:0xf
	v_cndmask_b32_e64 v99, v111, v105, s[2:3]
	v_ashrrev_i32_e32 v105, 31, v104
	v_lshlrev_b64 v[104:105], 11, v[104:105]
	v_lshl_add_u64 v[104:105], s[40:41], 0, v[104:105]
	v_cndmask_b32_e64 v97, v107, v109, s[2:3]
	v_cndmask_b32_e64 v96, v106, v108, s[2:3]
	v_lshl_add_u64 v[104:105], v[104:105], 0, v[112:113]
	global_store_dwordx4 v[104:105], v[96:99], off
	v_cvt_pk_bf16_f32 v92, v92, v93
	v_cvt_pk_bf16_f32 v84, v84, v85
	v_add_u32_e32 v98, 24, v148
	v_cndmask_b32_e64 v96, v114, v98, s[2:3]
	v_ashrrev_i32_e32 v97, 31, v96
	v_lshlrev_b64 v[96:97], 11, v[96:97]
	v_lshl_add_u64 v[96:97], s[40:41], 0, v[96:97]
	v_cvt_pk_bf16_f32 v93, v94, v95
	v_cvt_pk_bf16_f32 v88, v88, v89
	v_cvt_pk_bf16_f32 v89, v90, v91
	v_cvt_pk_bf16_f32 v85, v86, v87
	v_cvt_pk_bf16_f32 v86, v80, v81
	v_cndmask_b32_e64 v80, v92, v84, s[2:3]
	v_mov_b32_e32 v90, 0
	v_cndmask_b32_e64 v103, v103, v111, s[2:3]
	v_cndmask_b32_e64 v102, v102, v110, s[2:3]
	v_cndmask_b32_e64 v101, v101, v107, s[2:3]
	v_cndmask_b32_e64 v100, v100, v106, s[2:3]
	v_lshl_add_u64 v[96:97], v[96:97], 0, v[112:113]
	v_cvt_pk_bf16_f32 v87, v82, v83
	v_mov_b32_dpp v90, v80 row_ror:8 row_mask:0xf bank_mask:0xf
	v_cndmask_b32_e64 v80, v93, v85, s[2:3]
	v_mov_b32_e32 v91, 0
	v_cndmask_b32_e64 v81, v88, v86, s[2:3]
	v_mov_b32_e32 v94, 0
	global_store_dwordx4 v[96:97], v[100:103], off
	v_or_b32_e32 v96, 32, v148
	v_mov_b32_dpp v91, v80 row_ror:8 row_mask:0xf bank_mask:0xf
	v_cndmask_b32_e64 v80, v89, v87, s[2:3]
	v_mov_b32_dpp v94, v81 row_ror:8 row_mask:0xf bank_mask:0xf
	v_mov_b32_e32 v95, 0
	v_cndmask_b32_e64 v82, v94, v88, s[2:3]
	v_cndmask_b32_e64 v88, v98, v96, s[2:3]
	v_mov_b32_dpp v95, v80 row_ror:8 row_mask:0xf bank_mask:0xf
	v_cndmask_b32_e64 v83, v95, v89, s[2:3]
	v_ashrrev_i32_e32 v89, 31, v88
	v_lshlrev_b64 v[88:89], 11, v[88:89]
	v_lshl_add_u64 v[88:89], s[40:41], 0, v[88:89]
	v_cndmask_b32_e64 v81, v91, v93, s[2:3]
	v_cndmask_b32_e64 v80, v90, v92, s[2:3]
	v_lshl_add_u64 v[88:89], v[88:89], 0, v[112:113]
	global_store_dwordx4 v[88:89], v[80:83], off
	v_cvt_pk_bf16_f32 v76, v76, v77
	v_cvt_pk_bf16_f32 v68, v68, v69
	v_add_u32_e32 v82, 40, v148
	v_cndmask_b32_e64 v80, v96, v82, s[2:3]
	v_ashrrev_i32_e32 v81, 31, v80
	v_lshlrev_b64 v[80:81], 11, v[80:81]
	v_lshl_add_u64 v[80:81], s[40:41], 0, v[80:81]
	v_cvt_pk_bf16_f32 v77, v78, v79
	v_cvt_pk_bf16_f32 v72, v72, v73
	v_cvt_pk_bf16_f32 v73, v74, v75
	v_cvt_pk_bf16_f32 v69, v70, v71
	v_cvt_pk_bf16_f32 v70, v64, v65
	v_cndmask_b32_e64 v64, v76, v68, s[2:3]
	v_mov_b32_e32 v74, 0
	v_cndmask_b32_e64 v87, v87, v95, s[2:3]
	v_cndmask_b32_e64 v86, v86, v94, s[2:3]
	v_cndmask_b32_e64 v85, v85, v91, s[2:3]
	v_cndmask_b32_e64 v84, v84, v90, s[2:3]
	v_lshl_add_u64 v[80:81], v[80:81], 0, v[112:113]
	v_cvt_pk_bf16_f32 v71, v66, v67
	v_mov_b32_dpp v74, v64 row_ror:8 row_mask:0xf bank_mask:0xf
	v_cndmask_b32_e64 v64, v77, v69, s[2:3]
	v_mov_b32_e32 v75, 0
	v_cndmask_b32_e64 v65, v72, v70, s[2:3]
	v_mov_b32_e32 v78, 0
	global_store_dwordx4 v[80:81], v[84:87], off
	v_or_b32_e32 v80, 48, v148
	v_mov_b32_dpp v75, v64 row_ror:8 row_mask:0xf bank_mask:0xf
	v_cndmask_b32_e64 v64, v73, v71, s[2:3]
	v_mov_b32_dpp v78, v65 row_ror:8 row_mask:0xf bank_mask:0xf
	v_mov_b32_e32 v79, 0
	v_cndmask_b32_e64 v66, v78, v72, s[2:3]
	v_cndmask_b32_e64 v72, v82, v80, s[2:3]
	v_mov_b32_dpp v79, v64 row_ror:8 row_mask:0xf bank_mask:0xf
	v_cndmask_b32_e64 v67, v79, v73, s[2:3]
	v_ashrrev_i32_e32 v73, 31, v72
	v_lshlrev_b64 v[72:73], 11, v[72:73]
	v_lshl_add_u64 v[72:73], s[40:41], 0, v[72:73]
	v_cndmask_b32_e64 v65, v75, v77, s[2:3]
	v_cndmask_b32_e64 v64, v74, v76, s[2:3]
	v_lshl_add_u64 v[72:73], v[72:73], 0, v[112:113]
	global_store_dwordx4 v[72:73], v[64:67], off
	v_cvt_pk_bf16_f32 v60, v60, v61
	v_cvt_pk_bf16_f32 v56, v56, v57
	v_add_u32_e32 v64, 56, v148
	v_cndmask_b32_e64 v64, v80, v64, s[2:3]
	v_ashrrev_i32_e32 v65, 31, v64
	v_lshlrev_b64 v[64:65], 11, v[64:65]
	v_cvt_pk_bf16_f32 v52, v52, v53
	v_cvt_pk_bf16_f32 v53, v54, v55
	v_cvt_pk_bf16_f32 v54, v48, v49
	v_lshl_add_u64 v[64:65], s[40:41], 0, v[64:65]
	v_cvt_pk_bf16_f32 v61, v62, v63
	v_cvt_pk_bf16_f32 v57, v58, v59
	v_cndmask_b32_e64 v48, v60, v52, s[2:3]
	v_mov_b32_e32 v58, 0
	v_cndmask_b32_e64 v49, v56, v54, s[2:3]
	v_mov_b32_e32 v62, 0
	v_cndmask_b32_e64 v71, v71, v79, s[2:3]
	v_cndmask_b32_e64 v70, v70, v78, s[2:3]
	v_cndmask_b32_e64 v69, v69, v75, s[2:3]
	v_cndmask_b32_e64 v68, v68, v74, s[2:3]
	v_lshl_add_u64 v[64:65], v[64:65], 0, v[112:113]
	v_cvt_pk_bf16_f32 v55, v50, v51
	v_mov_b32_dpp v58, v48 row_ror:8 row_mask:0xf bank_mask:0xf
	v_cndmask_b32_e64 v48, v61, v53, s[2:3]
	v_mov_b32_e32 v59, 0
	v_mov_b32_dpp v62, v49 row_ror:8 row_mask:0xf bank_mask:0xf
	global_store_dwordx4 v[64:65], v[68:71], off
	v_add_u32_e32 v64, 0x80, v148
	v_mov_b32_dpp v59, v48 row_ror:8 row_mask:0xf bank_mask:0xf
	v_cndmask_b32_e64 v48, v57, v55, s[2:3]
	v_mov_b32_e32 v63, 0
	v_cndmask_b32_e64 v50, v62, v56, s[2:3]
	v_add_u32_e32 v56, 0x78, v148
	v_mov_b32_dpp v63, v48 row_ror:8 row_mask:0xf bank_mask:0xf
	v_cndmask_b32_e64 v56, v56, v64, s[2:3]
	v_cndmask_b32_e64 v51, v63, v57, s[2:3]
	v_ashrrev_i32_e32 v57, 31, v56
	v_lshlrev_b64 v[56:57], 11, v[56:57]
	v_lshl_add_u64 v[56:57], s[40:41], 0, v[56:57]
	v_cndmask_b32_e64 v49, v59, v61, s[2:3]
	v_cndmask_b32_e64 v48, v58, v60, s[2:3]
	v_lshl_add_u64 v[56:57], v[56:57], 0, v[112:113]
	global_store_dwordx4 v[56:57], v[48:51], off
	v_cvt_pk_bf16_f32 v44, v44, v45
	v_cvt_pk_bf16_f32 v36, v36, v37
	v_add_u32_e32 v50, 0x88, v148
	v_cndmask_b32_e64 v48, v64, v50, s[2:3]
	v_ashrrev_i32_e32 v49, 31, v48
	v_lshlrev_b64 v[48:49], 11, v[48:49]
	v_lshl_add_u64 v[48:49], s[40:41], 0, v[48:49]
	v_cvt_pk_bf16_f32 v45, v46, v47
	v_cvt_pk_bf16_f32 v40, v40, v41
	v_cvt_pk_bf16_f32 v41, v42, v43
	v_cvt_pk_bf16_f32 v37, v38, v39
	v_cvt_pk_bf16_f32 v38, v32, v33
	v_cndmask_b32_e64 v32, v44, v36, s[2:3]
	v_mov_b32_e32 v42, 0
	v_cndmask_b32_e64 v55, v55, v63, s[2:3]
	v_cndmask_b32_e64 v54, v54, v62, s[2:3]
	v_cndmask_b32_e64 v53, v53, v59, s[2:3]
	v_cndmask_b32_e64 v52, v52, v58, s[2:3]
	v_lshl_add_u64 v[48:49], v[48:49], 0, v[112:113]
	v_cvt_pk_bf16_f32 v39, v34, v35
	v_mov_b32_dpp v42, v32 row_ror:8 row_mask:0xf bank_mask:0xf
	v_cndmask_b32_e64 v32, v45, v37, s[2:3]
	v_mov_b32_e32 v43, 0
	v_cndmask_b32_e64 v33, v40, v38, s[2:3]
	v_mov_b32_e32 v46, 0
	global_store_dwordx4 v[48:49], v[52:55], off
	v_add_u32_e32 v48, 0x90, v148
	v_mov_b32_dpp v43, v32 row_ror:8 row_mask:0xf bank_mask:0xf
	v_cndmask_b32_e64 v32, v41, v39, s[2:3]
	v_mov_b32_dpp v46, v33 row_ror:8 row_mask:0xf bank_mask:0xf
	v_mov_b32_e32 v47, 0
	v_cndmask_b32_e64 v34, v46, v40, s[2:3]
	v_cndmask_b32_e64 v40, v50, v48, s[2:3]
	v_mov_b32_dpp v47, v32 row_ror:8 row_mask:0xf bank_mask:0xf
	v_cndmask_b32_e64 v35, v47, v41, s[2:3]
	v_ashrrev_i32_e32 v41, 31, v40
	v_lshlrev_b64 v[40:41], 11, v[40:41]
	v_lshl_add_u64 v[40:41], s[40:41], 0, v[40:41]
	v_cndmask_b32_e64 v33, v43, v45, s[2:3]
	v_cndmask_b32_e64 v32, v42, v44, s[2:3]
	v_lshl_add_u64 v[40:41], v[40:41], 0, v[112:113]
	global_store_dwordx4 v[40:41], v[32:35], off
	v_cvt_pk_bf16_f32 v28, v28, v29
	v_cvt_pk_bf16_f32 v20, v20, v21
	v_add_u32_e32 v34, 0x98, v148
	v_cndmask_b32_e64 v32, v48, v34, s[2:3]
	v_ashrrev_i32_e32 v33, 31, v32
	v_lshlrev_b64 v[32:33], 11, v[32:33]
	v_lshl_add_u64 v[32:33], s[40:41], 0, v[32:33]
	v_cvt_pk_bf16_f32 v29, v30, v31
	v_cvt_pk_bf16_f32 v24, v24, v25
	v_cvt_pk_bf16_f32 v25, v26, v27
	v_cvt_pk_bf16_f32 v21, v22, v23
	v_cvt_pk_bf16_f32 v22, v16, v17
	v_cndmask_b32_e64 v16, v28, v20, s[2:3]
	v_mov_b32_e32 v26, 0
	v_cndmask_b32_e64 v39, v39, v47, s[2:3]
	v_cndmask_b32_e64 v38, v38, v46, s[2:3]
	v_cndmask_b32_e64 v37, v37, v43, s[2:3]
	v_cndmask_b32_e64 v36, v36, v42, s[2:3]
	v_lshl_add_u64 v[32:33], v[32:33], 0, v[112:113]
	v_cvt_pk_bf16_f32 v23, v18, v19
	v_mov_b32_dpp v26, v16 row_ror:8 row_mask:0xf bank_mask:0xf
	v_cndmask_b32_e64 v16, v29, v21, s[2:3]
	v_mov_b32_e32 v27, 0
	v_cndmask_b32_e64 v17, v24, v22, s[2:3]
	v_mov_b32_e32 v30, 0
	global_store_dwordx4 v[32:33], v[36:39], off
	v_add_u32_e32 v32, 0xa0, v148
	v_mov_b32_dpp v27, v16 row_ror:8 row_mask:0xf bank_mask:0xf
	v_cndmask_b32_e64 v16, v25, v23, s[2:3]
	v_mov_b32_dpp v30, v17 row_ror:8 row_mask:0xf bank_mask:0xf
	v_mov_b32_e32 v31, 0
	v_cndmask_b32_e64 v18, v30, v24, s[2:3]
	v_cndmask_b32_e64 v24, v34, v32, s[2:3]
	v_mov_b32_dpp v31, v16 row_ror:8 row_mask:0xf bank_mask:0xf
	v_cndmask_b32_e64 v19, v31, v25, s[2:3]
	v_ashrrev_i32_e32 v25, 31, v24
	v_lshlrev_b64 v[24:25], 11, v[24:25]
	v_lshl_add_u64 v[24:25], s[40:41], 0, v[24:25]
	v_cndmask_b32_e64 v17, v27, v29, s[2:3]
	v_cndmask_b32_e64 v16, v26, v28, s[2:3]
	v_lshl_add_u64 v[24:25], v[24:25], 0, v[112:113]
	global_store_dwordx4 v[24:25], v[16:19], off
	v_cndmask_b32_e64 v23, v23, v31, s[2:3]
	v_cndmask_b32_e64 v22, v22, v30, s[2:3]
	v_add_u32_e32 v18, 0xa8, v148
	v_cndmask_b32_e64 v16, v32, v18, s[2:3]
	v_ashrrev_i32_e32 v17, 31, v16
	v_lshlrev_b64 v[16:17], 11, v[16:17]
	v_lshl_add_u64 v[16:17], s[40:41], 0, v[16:17]
	v_cndmask_b32_e64 v21, v21, v27, s[2:3]
	v_cndmask_b32_e64 v20, v20, v26, s[2:3]
	v_lshl_add_u64 v[16:17], v[16:17], 0, v[112:113]
	global_store_dwordx4 v[16:17], v[20:23], off
	v_add_u32_e32 v16, 0xb0, v148
	v_cvt_pk_bf16_f32 v12, v12, v13
	v_cvt_pk_bf16_f32 v8, v8, v9
	v_cvt_pk_bf16_f32 v9, v10, v11
	v_cvt_pk_bf16_f32 v10, v4, v5
	v_cvt_pk_bf16_f32 v13, v14, v15
	v_cvt_pk_bf16_f32 v6, v6, v7
	v_cvt_pk_bf16_f32 v7, v0, v1
	v_cndmask_b32_e64 v0, v12, v10, s[2:3]
	v_mov_b32_e32 v14, 0
	v_cndmask_b32_e64 v4, v18, v16, s[2:3]
	v_cvt_pk_bf16_f32 v11, v2, v3
	v_mov_b32_dpp v14, v0 row_ror:8 row_mask:0xf bank_mask:0xf
	v_cndmask_b32_e64 v0, v13, v6, s[2:3]
	v_mov_b32_e32 v15, 0
	v_ashrrev_i32_e32 v5, 31, v4
	v_cndmask_b32_e64 v1, v8, v7, s[2:3]
	v_mov_b32_dpp v15, v0 row_ror:8 row_mask:0xf bank_mask:0xf
	v_cndmask_b32_e64 v0, v9, v11, s[2:3]
	v_mov_b32_e32 v17, 0
	v_mov_b32_e32 v19, 0
	v_lshlrev_b64 v[4:5], 11, v[4:5]
	v_mov_b32_dpp v17, v1 row_ror:8 row_mask:0xf bank_mask:0xf
	v_mov_b32_dpp v19, v0 row_ror:8 row_mask:0xf bank_mask:0xf
	v_lshl_add_u64 v[4:5], s[40:41], 0, v[4:5]
	v_cndmask_b32_e64 v3, v19, v9, s[2:3]
	v_cndmask_b32_e64 v2, v17, v8, s[2:3]
	v_cndmask_b32_e64 v1, v15, v13, s[2:3]
	v_cndmask_b32_e64 v0, v14, v12, s[2:3]
	v_lshl_add_u64 v[4:5], v[4:5], 0, v[112:113]
	global_store_dwordx4 v[4:5], v[0:3], off
	s_and_b64 vcc, exec, s[4:5]
	s_mov_b32 s62, s6
	v_add_u32_e32 v0, 0xb8, v148
	v_cndmask_b32_e64 v0, v16, v0, s[2:3]
	v_ashrrev_i32_e32 v1, 31, v0
	v_lshlrev_b64 v[0:1], 11, v[0:1]
	v_lshl_add_u64 v[0:1], s[40:41], 0, v[0:1]
	v_lshl_add_u64 v[4:5], v[0:1], 0, v[112:113]
	v_cndmask_b32_e64 v3, v11, v19, s[2:3]
	v_cndmask_b32_e64 v2, v7, v17, s[2:3]
	v_cndmask_b32_e64 v1, v6, v15, s[2:3]
	v_cndmask_b32_e64 v0, v10, v14, s[2:3]
	s_mov_b32 s42, s8
	s_mov_b64 s[46:47], s[12:13]
	s_mov_b64 s[44:45], s[10:11]
	global_store_dwordx4 v[4:5], v[0:3], off
	s_cbranch_vccz .LBB0_335
	s_waitcnt vmcnt(0)
	s_cmpk_gt_u32 s17, 0xff
	s_cbranch_scc1 .LBB0_346
	s_barrier

.LBB0_667:
	s_add_u32 s56, s52, s54
	s_addc_u32 s57, s53, s55
	s_add_u32 s56, s56, 0x100
	s_addc_u32 s57, s57, 0
	s_add_u32 vcc_lo, s96, s54
	s_addc_u32 vcc_hi, s97, s55
	s_cmpk_eq_i32 s54, 0x700
	s_cselect_b32 s59, s47, s57
	s_cselect_b32 s58, s94, s56
	s_cselect_b32 s57, s45, vcc_hi
	s_cselect_b32 s56, s95, vcc_lo
	s_add_i32 vcc_lo, 0, 0x10000
	v_add_u32_e32 v1, vcc_lo, v196
	ds_read_b128 v[132:135], v1
	ds_read_b128 v[136:139], v1 offset:1024
	ds_read_b128 v[140:143], v1 offset:2048
	ds_read_b128 v[144:147], v1 offset:3072
	v_lshl_add_u64 v[2:3], v[188:189], 0, s[54:55]
	s_add_i32 m0, s63, 0xc000
	ds_read_b128 v[148:151], v199
	ds_read_b128 v[152:155], v199 offset:1024
	ds_read_b128 v[156:159], v199 offset:2048
	ds_read_b128 v[160:163], v199 offset:3072
	ds_read_b128 v[164:167], v199 offset:4096
	ds_read_b128 v[200:203], v199 offset:5120
	ds_read_b128 v[204:207], v199 offset:6144
	ds_read_b128 v[208:211], v199 offset:7168
	global_load_lds_dwordx4 v[2:3], off
	v_lshl_add_u64 v[2:3], v[190:191], 0, s[54:55]
	s_add_i32 m0, s63, 0xe000
	s_nop 0
	global_load_lds_dwordx4 v[2:3], off
	s_waitcnt lgkmcnt(8)
	s_barrier
	s_waitcnt lgkmcnt(0)
	v_mfma_f32_16x16x32_bf16 v[128:131], v[132:135], v[148:151], v[128:131]
	v_mfma_f32_16x16x32_bf16 v[124:127], v[140:143], v[148:151], v[124:127]
	v_mfma_f32_16x16x32_bf16 v[112:115], v[132:135], v[156:159], v[112:115]
	v_mfma_f32_16x16x32_bf16 v[108:111], v[140:143], v[156:159], v[108:111]
	v_mfma_f32_16x16x32_bf16 v[96:99], v[132:135], v[164:167], v[96:99]
	v_mfma_f32_16x16x32_bf16 v[92:95], v[140:143], v[164:167], v[92:95]
	v_mfma_f32_16x16x32_bf16 v[80:83], v[132:135], v[204:207], v[80:83]
	v_mfma_f32_16x16x32_bf16 v[76:79], v[140:143], v[204:207], v[76:79]
	v_mfma_f32_16x16x32_bf16 v[128:131], v[136:139], v[152:155], v[128:131]
	v_mfma_f32_16x16x32_bf16 v[124:127], v[144:147], v[152:155], v[124:127]
	v_mfma_f32_16x16x32_bf16 v[112:115], v[136:139], v[160:163], v[112:115]
	v_mfma_f32_16x16x32_bf16 v[108:111], v[144:147], v[160:163], v[108:111]
	v_mfma_f32_16x16x32_bf16 v[96:99], v[136:139], v[200:203], v[96:99]
	v_mfma_f32_16x16x32_bf16 v[92:95], v[144:147], v[200:203], v[92:95]
	v_mfma_f32_16x16x32_bf16 v[80:83], v[136:139], v[208:211], v[80:83]
	v_mfma_f32_16x16x32_bf16 v[76:79], v[144:147], v[208:211], v[76:79]
	s_barrier
	s_add_i32 vcc_lo, vcc_lo, s61
	v_add_u32_e32 v1, s93, v196
	v_lshl_add_u64 v[228:229], s[56:57], 0, v[172:173]
	s_mov_b32 m0, vcc_lo
	ds_read_b128 v[212:215], v1
	ds_read_b128 v[216:219], v1 offset:1024
	ds_read_b128 v[220:223], v1 offset:2048
	ds_read_b128 v[224:227], v1 offset:3072
	global_load_lds_dwordx4 v[228:229], off
	v_lshl_add_u64 v[230:231], s[56:57], 0, v[168:169]
	s_add_i32 m0, vcc_lo, 0x2000
	s_nop 0
	global_load_lds_dwordx4 v[230:231], off
	s_barrier
	s_waitcnt lgkmcnt(0)
	v_mfma_f32_16x16x32_bf16 v[120:123], v[212:215], v[148:151], v[120:123]
	v_mfma_f32_16x16x32_bf16 v[116:119], v[220:223], v[148:151], v[116:119]
	v_mfma_f32_16x16x32_bf16 v[104:107], v[212:215], v[156:159], v[104:107]
	v_mfma_f32_16x16x32_bf16 v[100:103], v[220:223], v[156:159], v[100:103]
	v_mfma_f32_16x16x32_bf16 v[88:91], v[212:215], v[164:167], v[88:91]
	v_mfma_f32_16x16x32_bf16 v[84:87], v[220:223], v[164:167], v[84:87]
	v_mfma_f32_16x16x32_bf16 v[72:75], v[212:215], v[204:207], v[72:75]
	v_mfma_f32_16x16x32_bf16 v[68:71], v[220:223], v[204:207], v[68:71]
	v_mfma_f32_16x16x32_bf16 v[120:123], v[216:219], v[152:155], v[120:123]
	v_mfma_f32_16x16x32_bf16 v[116:119], v[224:227], v[152:155], v[116:119]
	v_mfma_f32_16x16x32_bf16 v[104:107], v[216:219], v[160:163], v[104:107]
	v_mfma_f32_16x16x32_bf16 v[100:103], v[224:227], v[160:163], v[100:103]
	v_mfma_f32_16x16x32_bf16 v[88:91], v[216:219], v[200:203], v[88:91]
	v_mfma_f32_16x16x32_bf16 v[84:87], v[224:227], v[200:203], v[84:87]
	v_mfma_f32_16x16x32_bf16 v[72:75], v[216:219], v[208:211], v[72:75]
	v_mfma_f32_16x16x32_bf16 v[68:71], v[224:227], v[208:211], v[68:71]
	s_mov_b32 m0, s63
	v_lshl_add_u64 v[232:233], s[58:59], 0, v[174:175]
	s_barrier
	ds_read_b128 v[148:151], v199 offset:16384
	ds_read_b128 v[152:155], v199 offset:17408
	ds_read_b128 v[156:159], v199 offset:18432
	ds_read_b128 v[160:163], v199 offset:19456
	ds_read_b128 v[164:167], v199 offset:20480
	ds_read_b128 v[200:203], v199 offset:21504
	ds_read_b128 v[204:207], v199 offset:22528
	ds_read_b128 v[208:211], v199 offset:23552
	global_load_lds_dwordx4 v[232:233], off
	v_lshl_add_u64 v[234:235], s[58:59], 0, v[170:171]
	s_mov_b32 m0, s64
	s_nop 0
	global_load_lds_dwordx4 v[234:235], off
	s_barrier
	s_waitcnt lgkmcnt(0)
	v_mfma_f32_16x16x32_bf16 v[64:67], v[132:135], v[148:151], v[64:67]
	v_mfma_f32_16x16x32_bf16 v[60:63], v[140:143], v[148:151], v[60:63]
	v_mfma_f32_16x16x32_bf16 v[48:51], v[132:135], v[156:159], v[48:51]
	v_mfma_f32_16x16x32_bf16 v[44:47], v[140:143], v[156:159], v[44:47]
	v_mfma_f32_16x16x32_bf16 v[32:35], v[132:135], v[164:167], v[32:35]
	v_mfma_f32_16x16x32_bf16 v[28:31], v[140:143], v[164:167], v[28:31]
	v_mfma_f32_16x16x32_bf16 v[16:19], v[132:135], v[204:207], v[16:19]
	v_mfma_f32_16x16x32_bf16 v[12:15], v[140:143], v[204:207], v[12:15]
	v_mfma_f32_16x16x32_bf16 v[64:67], v[136:139], v[152:155], v[64:67]
	v_mfma_f32_16x16x32_bf16 v[60:63], v[144:147], v[152:155], v[60:63]
	v_mfma_f32_16x16x32_bf16 v[48:51], v[136:139], v[160:163], v[48:51]
	v_mfma_f32_16x16x32_bf16 v[44:47], v[144:147], v[160:163], v[44:47]
	v_mfma_f32_16x16x32_bf16 v[32:35], v[136:139], v[200:203], v[32:35]
	v_mfma_f32_16x16x32_bf16 v[28:31], v[144:147], v[200:203], v[28:31]
	v_mfma_f32_16x16x32_bf16 v[16:19], v[136:139], v[208:211], v[16:19]
	v_mfma_f32_16x16x32_bf16 v[12:15], v[144:147], v[208:211], v[12:15]
	s_barrier
	s_add_u32 vcc_lo, s56, 0x10000
	s_addc_u32 vcc_hi, s57, 0
	s_add_i32 s28, s93, s61
	v_lshl_add_u64 v[2:3], vcc, 0, v[172:173]
	s_mov_b32 m0, s28
	s_nop 0
	global_load_lds_dwordx4 v[2:3], off
	v_lshl_add_u64 v[2:3], vcc, 0, v[168:169]
	s_add_i32 m0, s28, 0x2000
	s_nop 0
	global_load_lds_dwordx4 v[2:3], off
	s_waitcnt vmcnt(6)
	s_barrier
	v_mfma_f32_16x16x32_bf16 v[56:59], v[212:215], v[148:151], v[56:59]
	v_mfma_f32_16x16x32_bf16 v[52:55], v[220:223], v[148:151], v[52:55]
	v_mfma_f32_16x16x32_bf16 v[40:43], v[212:215], v[156:159], v[40:43]
	v_mfma_f32_16x16x32_bf16 v[36:39], v[220:223], v[156:159], v[36:39]
	v_mfma_f32_16x16x32_bf16 v[24:27], v[212:215], v[164:167], v[24:27]
	v_mfma_f32_16x16x32_bf16 v[20:23], v[220:223], v[164:167], v[20:23]
	v_mfma_f32_16x16x32_bf16 v[8:11], v[212:215], v[204:207], v[8:11]
	v_mfma_f32_16x16x32_bf16 v[2:5], v[220:223], v[204:207], v[4:7]
	v_mfma_f32_16x16x32_bf16 v[56:59], v[216:219], v[152:155], v[56:59]
	v_mfma_f32_16x16x32_bf16 v[52:55], v[224:227], v[152:155], v[52:55]
	v_mfma_f32_16x16x32_bf16 v[40:43], v[216:219], v[160:163], v[40:43]
	v_mfma_f32_16x16x32_bf16 v[36:39], v[224:227], v[160:163], v[36:39]
	v_mfma_f32_16x16x32_bf16 v[24:27], v[216:219], v[200:203], v[24:27]
	v_mfma_f32_16x16x32_bf16 v[20:23], v[224:227], v[200:203], v[20:23]
	v_mfma_f32_16x16x32_bf16 v[8:11], v[216:219], v[208:211], v[8:11]
	v_mfma_f32_16x16x32_bf16 v[2:5], v[224:227], v[208:211], v[2:5]
	s_add_i32 s28, 0, 0x18000
	v_add_u32_e32 v1, s28, v196
	s_barrier
	ds_read_b128 v[132:135], v1
	ds_read_b128 v[136:139], v1 offset:1024
	ds_read_b128 v[140:143], v1 offset:2048
	ds_read_b128 v[144:147], v1 offset:3072
	s_add_u32 s58, s58, 0x40000
	s_addc_u32 s59, s59, 0
	s_mov_b32 m0, s65
	v_lshl_add_u64 v[6:7], s[58:59], 0, v[174:175]
	ds_read_b128 v[148:151], v199 offset:32768
	ds_read_b128 v[152:155], v199 offset:33792
	ds_read_b128 v[156:159], v199 offset:34816
	ds_read_b128 v[160:163], v199 offset:35840
	ds_read_b128 v[164:167], v199 offset:36864
	ds_read_b128 v[200:203], v199 offset:37888
	ds_read_b128 v[204:207], v199 offset:38912
	ds_read_b128 v[208:211], v199 offset:39936
	global_load_lds_dwordx4 v[6:7], off
	v_lshl_add_u64 v[6:7], s[58:59], 0, v[170:171]
	s_mov_b32 m0, s66
	s_nop 0
	global_load_lds_dwordx4 v[6:7], off
	s_waitcnt lgkmcnt(8)
	s_barrier
	s_waitcnt lgkmcnt(0)
	v_mfma_f32_16x16x32_bf16 v[128:131], v[132:135], v[148:151], v[128:131]
	v_mfma_f32_16x16x32_bf16 v[124:127], v[140:143], v[148:151], v[124:127]
	v_mfma_f32_16x16x32_bf16 v[112:115], v[132:135], v[156:159], v[112:115]
	v_mfma_f32_16x16x32_bf16 v[108:111], v[140:143], v[156:159], v[108:111]
	v_mfma_f32_16x16x32_bf16 v[96:99], v[132:135], v[164:167], v[96:99]
	v_mfma_f32_16x16x32_bf16 v[92:95], v[140:143], v[164:167], v[92:95]
	v_mfma_f32_16x16x32_bf16 v[80:83], v[132:135], v[204:207], v[80:83]
	v_mfma_f32_16x16x32_bf16 v[76:79], v[140:143], v[204:207], v[76:79]
	v_mfma_f32_16x16x32_bf16 v[128:131], v[136:139], v[152:155], v[128:131]
	v_mfma_f32_16x16x32_bf16 v[124:127], v[144:147], v[152:155], v[124:127]
	v_mfma_f32_16x16x32_bf16 v[112:115], v[136:139], v[160:163], v[112:115]
	v_mfma_f32_16x16x32_bf16 v[108:111], v[144:147], v[160:163], v[108:111]
	v_mfma_f32_16x16x32_bf16 v[96:99], v[136:139], v[200:203], v[96:99]
	v_mfma_f32_16x16x32_bf16 v[92:95], v[144:147], v[200:203], v[92:95]
	v_mfma_f32_16x16x32_bf16 v[80:83], v[136:139], v[208:211], v[80:83]
	v_mfma_f32_16x16x32_bf16 v[76:79], v[144:147], v[208:211], v[76:79]
	s_barrier
	s_add_i32 s29, 0, 0x1c000
	s_add_i32 s28, s28, s61
	v_add_u32_e32 v1, s29, v196
	v_lshl_add_u64 v[6:7], v[228:229], 0, s[0:1]
	s_mov_b32 m0, s28
	ds_read_b128 v[212:215], v1
	ds_read_b128 v[216:219], v1 offset:1024
	ds_read_b128 v[220:223], v1 offset:2048
	ds_read_b128 v[224:227], v1 offset:3072
	global_load_lds_dwordx4 v[6:7], off
	v_lshl_add_u64 v[6:7], v[230:231], 0, s[0:1]
	s_add_i32 m0, s28, 0x2000
	s_nop 0
	global_load_lds_dwordx4 v[6:7], off
	s_barrier
	s_waitcnt lgkmcnt(0)
	v_mfma_f32_16x16x32_bf16 v[120:123], v[212:215], v[148:151], v[120:123]
	v_mfma_f32_16x16x32_bf16 v[116:119], v[220:223], v[148:151], v[116:119]
	v_mfma_f32_16x16x32_bf16 v[104:107], v[212:215], v[156:159], v[104:107]
	v_mfma_f32_16x16x32_bf16 v[100:103], v[220:223], v[156:159], v[100:103]
	v_mfma_f32_16x16x32_bf16 v[88:91], v[212:215], v[164:167], v[88:91]
	v_mfma_f32_16x16x32_bf16 v[84:87], v[220:223], v[164:167], v[84:87]
	v_mfma_f32_16x16x32_bf16 v[72:75], v[212:215], v[204:207], v[72:75]
	v_mfma_f32_16x16x32_bf16 v[68:71], v[220:223], v[204:207], v[68:71]
	v_mfma_f32_16x16x32_bf16 v[120:123], v[216:219], v[152:155], v[120:123]
	v_mfma_f32_16x16x32_bf16 v[116:119], v[224:227], v[152:155], v[116:119]
	v_mfma_f32_16x16x32_bf16 v[104:107], v[216:219], v[160:163], v[104:107]
	v_mfma_f32_16x16x32_bf16 v[100:103], v[224:227], v[160:163], v[100:103]
	v_mfma_f32_16x16x32_bf16 v[88:91], v[216:219], v[200:203], v[88:91]
	v_mfma_f32_16x16x32_bf16 v[84:87], v[224:227], v[200:203], v[84:87]
	v_mfma_f32_16x16x32_bf16 v[72:75], v[216:219], v[208:211], v[72:75]
	v_mfma_f32_16x16x32_bf16 v[68:71], v[224:227], v[208:211], v[68:71]
	s_mov_b32 m0, s81
	v_lshl_add_u64 v[6:7], v[232:233], 0, s[0:1]
	s_barrier
	ds_read_b128 v[148:151], v199 offset:49152
	ds_read_b128 v[152:155], v199 offset:50176
	ds_read_b128 v[156:159], v199 offset:51200
	ds_read_b128 v[160:163], v199 offset:52224
	ds_read_b128 v[164:167], v199 offset:53248
	ds_read_b128 v[200:203], v199 offset:54272
	ds_read_b128 v[204:207], v199 offset:55296
	ds_read_b128 v[208:211], v199 offset:56320
	global_load_lds_dwordx4 v[6:7], off
	v_lshl_add_u64 v[6:7], v[234:235], 0, s[0:1]
	s_mov_b32 m0, s82
	s_nop 0
	global_load_lds_dwordx4 v[6:7], off
	s_barrier
	s_waitcnt lgkmcnt(0)
	v_mfma_f32_16x16x32_bf16 v[64:67], v[132:135], v[148:151], v[64:67]
	v_mfma_f32_16x16x32_bf16 v[60:63], v[140:143], v[148:151], v[60:63]
	v_mfma_f32_16x16x32_bf16 v[48:51], v[132:135], v[156:159], v[48:51]
	v_mfma_f32_16x16x32_bf16 v[44:47], v[140:143], v[156:159], v[44:47]
	v_mfma_f32_16x16x32_bf16 v[32:35], v[132:135], v[164:167], v[32:35]
	v_mfma_f32_16x16x32_bf16 v[28:31], v[140:143], v[164:167], v[28:31]
	v_mfma_f32_16x16x32_bf16 v[16:19], v[132:135], v[204:207], v[16:19]
	v_mfma_f32_16x16x32_bf16 v[12:15], v[140:143], v[204:207], v[12:15]
	v_mfma_f32_16x16x32_bf16 v[64:67], v[136:139], v[152:155], v[64:67]
	v_mfma_f32_16x16x32_bf16 v[60:63], v[144:147], v[152:155], v[60:63]
	v_mfma_f32_16x16x32_bf16 v[48:51], v[136:139], v[160:163], v[48:51]
	v_mfma_f32_16x16x32_bf16 v[44:47], v[144:147], v[160:163], v[44:47]
	v_mfma_f32_16x16x32_bf16 v[32:35], v[136:139], v[200:203], v[32:35]
	v_mfma_f32_16x16x32_bf16 v[28:31], v[144:147], v[200:203], v[28:31]
	v_mfma_f32_16x16x32_bf16 v[16:19], v[136:139], v[208:211], v[16:19]
	v_mfma_f32_16x16x32_bf16 v[12:15], v[144:147], v[208:211], v[12:15]
	s_barrier
	s_add_u32 s56, s56, 0x10080
	s_addc_u32 s57, s57, 0
	s_add_i32 s28, s29, s61
	v_lshl_add_u64 v[6:7], s[56:57], 0, v[172:173]
	s_mov_b32 m0, s28
	s_nop 0
	global_load_lds_dwordx4 v[6:7], off
	v_lshl_add_u64 v[6:7], s[56:57], 0, v[168:169]
	s_add_i32 m0, s28, 0x2000
	s_nop 0
	global_load_lds_dwordx4 v[6:7], off
	s_waitcnt vmcnt(6)
	s_barrier
	v_mfma_f32_16x16x32_bf16 v[56:59], v[212:215], v[148:151], v[56:59]
	v_mfma_f32_16x16x32_bf16 v[52:55], v[220:223], v[148:151], v[52:55]
	v_mfma_f32_16x16x32_bf16 v[40:43], v[212:215], v[156:159], v[40:43]
	v_mfma_f32_16x16x32_bf16 v[36:39], v[220:223], v[156:159], v[36:39]
	v_mfma_f32_16x16x32_bf16 v[24:27], v[212:215], v[164:167], v[24:27]
	v_mfma_f32_16x16x32_bf16 v[20:23], v[220:223], v[164:167], v[20:23]
	v_mfma_f32_16x16x32_bf16 v[6:9], v[212:215], v[204:207], v[8:11]
	v_mfma_f32_16x16x32_bf16 v[2:5], v[220:223], v[204:207], v[2:5]
	v_mfma_f32_16x16x32_bf16 v[56:59], v[216:219], v[152:155], v[56:59]
	v_mfma_f32_16x16x32_bf16 v[52:55], v[224:227], v[152:155], v[52:55]
	v_mfma_f32_16x16x32_bf16 v[40:43], v[216:219], v[160:163], v[40:43]
	v_mfma_f32_16x16x32_bf16 v[36:39], v[224:227], v[160:163], v[36:39]
	v_mfma_f32_16x16x32_bf16 v[24:27], v[216:219], v[200:203], v[24:27]
	v_mfma_f32_16x16x32_bf16 v[20:23], v[224:227], v[200:203], v[20:23]
	v_mfma_f32_16x16x32_bf16 v[8:11], v[216:219], v[208:211], v[6:9]
	v_mfma_f32_16x16x32_bf16 v[4:7], v[224:227], v[208:211], v[2:5]
	s_add_i32 s17, s17, 2
	s_add_u32 s54, s54, 0x100
	s_addc_u32 s55, s55, 0
	s_cmp_gt_u32 s17, 13
	s_barrier
	s_cbranch_scc1 .LBB0_659

.LBB0_740:
	ds_read_b128 v[64:67], v221
	ds_read_b128 v[68:71], v221 offset:1024
	ds_read_b128 v[84:87], v221 offset:2048
	ds_read_b128 v[92:95], v221 offset:3072
	s_add_u32 s28, s10, 0xfffc0080
	s_addc_u32 s29, s11, -1
	s_cmp_eq_u32 s92, 12
	s_cselect_b32 s65, s9, s29
	s_cselect_b32 s64, s13, s28
	s_cselect_b32 s63, s17, s57
	s_cselect_b32 s62, s44, s55
	v_lshl_add_u64 v[176:177], s[10:11], 0, v[204:205]
	s_add_i32 m0, s78, 0xc000
	ds_read_b128 v[144:147], v222
	ds_read_b128 v[148:151], v222 offset:1024
	ds_read_b128 v[152:155], v222 offset:2048
	ds_read_b128 v[156:159], v222 offset:3072
	ds_read_b128 v[160:163], v222 offset:4096
	ds_read_b128 v[164:167], v222 offset:5120
	ds_read_b128 v[168:171], v222 offset:6144
	ds_read_b128 v[172:175], v222 offset:7168
	global_load_lds_dwordx4 v[176:177], off
	v_lshl_add_u64 v[176:177], s[10:11], 0, v[206:207]
	s_add_i32 m0, s78, 0xe000
	s_nop 0
	global_load_lds_dwordx4 v[176:177], off
	s_waitcnt lgkmcnt(8)
	s_barrier
	s_waitcnt lgkmcnt(0)
	v_mfma_f32_16x16x32_bf16 v[140:143], v[64:67], v[144:147], v[140:143]
	v_mfma_f32_16x16x32_bf16 v[136:139], v[84:87], v[144:147], v[136:139]
	v_mfma_f32_16x16x32_bf16 v[124:127], v[64:67], v[152:155], v[124:127]
	v_mfma_f32_16x16x32_bf16 v[120:123], v[84:87], v[152:155], v[120:123]
	v_mfma_f32_16x16x32_bf16 v[108:111], v[64:67], v[160:163], v[108:111]
	v_mfma_f32_16x16x32_bf16 v[104:107], v[84:87], v[160:163], v[104:107]
	v_mfma_f32_16x16x32_bf16 v[88:91], v[64:67], v[168:171], v[88:91]
	v_mfma_f32_16x16x32_bf16 v[80:83], v[84:87], v[168:171], v[80:83]
	v_mfma_f32_16x16x32_bf16 v[140:143], v[68:71], v[148:151], v[140:143]
	v_mfma_f32_16x16x32_bf16 v[136:139], v[92:95], v[148:151], v[136:139]
	v_mfma_f32_16x16x32_bf16 v[124:127], v[68:71], v[156:159], v[124:127]
	v_mfma_f32_16x16x32_bf16 v[120:123], v[92:95], v[156:159], v[120:123]
	v_mfma_f32_16x16x32_bf16 v[108:111], v[68:71], v[164:167], v[108:111]
	v_mfma_f32_16x16x32_bf16 v[104:107], v[92:95], v[164:167], v[104:107]
	v_mfma_f32_16x16x32_bf16 v[88:91], v[68:71], v[172:175], v[88:91]
	v_mfma_f32_16x16x32_bf16 v[80:83], v[92:95], v[172:175], v[80:83]
	s_barrier
	s_add_i32 s28, s89, s67
	v_lshl_add_u64 v[212:213], s[62:63], 0, v[198:199]
	s_mov_b32 m0, s28
	ds_read_b128 v[176:179], v223
	ds_read_b128 v[180:183], v223 offset:1024
	ds_read_b128 v[184:187], v223 offset:2048
	ds_read_b128 v[188:191], v223 offset:3072
	global_load_lds_dwordx4 v[212:213], off
	v_lshl_add_u64 v[214:215], s[62:63], 0, v[202:203]
	s_add_i32 m0, s28, 0x2000
	s_nop 0
	global_load_lds_dwordx4 v[214:215], off
	s_barrier
	s_waitcnt lgkmcnt(0)
	v_mfma_f32_16x16x32_bf16 v[132:135], v[176:179], v[144:147], v[132:135]
	v_mfma_f32_16x16x32_bf16 v[128:131], v[184:187], v[144:147], v[128:131]
	v_mfma_f32_16x16x32_bf16 v[116:119], v[176:179], v[152:155], v[116:119]
	v_mfma_f32_16x16x32_bf16 v[112:115], v[184:187], v[152:155], v[112:115]
	v_mfma_f32_16x16x32_bf16 v[100:103], v[176:179], v[160:163], v[100:103]
	v_mfma_f32_16x16x32_bf16 v[96:99], v[184:187], v[160:163], v[96:99]
	v_mfma_f32_16x16x32_bf16 v[76:79], v[176:179], v[168:171], v[76:79]
	v_mfma_f32_16x16x32_bf16 v[72:75], v[184:187], v[168:171], v[72:75]
	v_mfma_f32_16x16x32_bf16 v[132:135], v[180:183], v[148:151], v[132:135]
	v_mfma_f32_16x16x32_bf16 v[128:131], v[188:191], v[148:151], v[128:131]
	v_mfma_f32_16x16x32_bf16 v[116:119], v[180:183], v[156:159], v[116:119]
	v_mfma_f32_16x16x32_bf16 v[112:115], v[188:191], v[156:159], v[112:115]
	v_mfma_f32_16x16x32_bf16 v[100:103], v[180:183], v[164:167], v[100:103]
	v_mfma_f32_16x16x32_bf16 v[96:99], v[188:191], v[164:167], v[96:99]
	v_mfma_f32_16x16x32_bf16 v[76:79], v[180:183], v[172:175], v[76:79]
	v_mfma_f32_16x16x32_bf16 v[72:75], v[188:191], v[172:175], v[72:75]
	s_mov_b32 m0, s78
	v_lshl_add_u64 v[216:217], s[64:65], 0, v[196:197]
	s_barrier
	ds_read_b128 v[144:147], v222 offset:16384
	ds_read_b128 v[148:151], v222 offset:17408
	ds_read_b128 v[152:155], v222 offset:18432
	ds_read_b128 v[156:159], v222 offset:19456
	ds_read_b128 v[160:163], v222 offset:20480
	ds_read_b128 v[164:167], v222 offset:21504
	ds_read_b128 v[168:171], v222 offset:22528
	ds_read_b128 v[172:175], v222 offset:23552
	global_load_lds_dwordx4 v[216:217], off
	v_lshl_add_u64 v[226:227], s[64:65], 0, v[200:201]
	s_mov_b32 m0, s79
	s_nop 0
	global_load_lds_dwordx4 v[226:227], off
	s_barrier
	s_waitcnt lgkmcnt(0)
	v_mfma_f32_16x16x32_bf16 v[60:63], v[64:67], v[144:147], v[60:63]
	v_mfma_f32_16x16x32_bf16 v[56:59], v[84:87], v[144:147], v[56:59]
	v_mfma_f32_16x16x32_bf16 v[44:47], v[64:67], v[152:155], v[44:47]
	v_mfma_f32_16x16x32_bf16 v[40:43], v[84:87], v[152:155], v[40:43]
	v_mfma_f32_16x16x32_bf16 v[28:31], v[64:67], v[160:163], v[28:31]
	v_mfma_f32_16x16x32_bf16 v[24:27], v[84:87], v[160:163], v[24:27]
	v_mfma_f32_16x16x32_bf16 v[12:15], v[64:67], v[168:171], v[12:15]
	v_mfma_f32_16x16x32_bf16 v[8:11], v[84:87], v[168:171], v[8:11]
	v_mfma_f32_16x16x32_bf16 v[60:63], v[68:71], v[148:151], v[60:63]
	v_mfma_f32_16x16x32_bf16 v[56:59], v[92:95], v[148:151], v[56:59]
	v_mfma_f32_16x16x32_bf16 v[44:47], v[68:71], v[156:159], v[44:47]
	v_mfma_f32_16x16x32_bf16 v[40:43], v[92:95], v[156:159], v[40:43]
	v_mfma_f32_16x16x32_bf16 v[28:31], v[68:71], v[164:167], v[28:31]
	v_mfma_f32_16x16x32_bf16 v[24:27], v[92:95], v[164:167], v[24:27]
	v_mfma_f32_16x16x32_bf16 v[12:15], v[68:71], v[172:175], v[12:15]
	v_mfma_f32_16x16x32_bf16 v[8:11], v[92:95], v[172:175], v[8:11]
	s_barrier
	s_add_u32 s94, s62, 0x10000
	s_addc_u32 s95, s63, 0
	s_add_i32 s28, s90, s67
	v_lshl_add_u64 v[64:65], s[94:95], 0, v[198:199]
	s_mov_b32 m0, s28
	s_nop 0
	global_load_lds_dwordx4 v[64:65], off
	v_lshl_add_u64 v[64:65], s[94:95], 0, v[202:203]
	s_add_i32 m0, s28, 0x2000
	s_nop 0
	global_load_lds_dwordx4 v[64:65], off
	s_waitcnt vmcnt(6)
	s_barrier
	v_mfma_f32_16x16x32_bf16 v[52:55], v[176:179], v[144:147], v[52:55]
	v_mfma_f32_16x16x32_bf16 v[48:51], v[184:187], v[144:147], v[48:51]
	v_mfma_f32_16x16x32_bf16 v[36:39], v[176:179], v[152:155], v[36:39]
	v_mfma_f32_16x16x32_bf16 v[32:35], v[184:187], v[152:155], v[32:35]
	v_mfma_f32_16x16x32_bf16 v[20:23], v[176:179], v[160:163], v[20:23]
	v_mfma_f32_16x16x32_bf16 v[16:19], v[184:187], v[160:163], v[16:19]
	v_mfma_f32_16x16x32_bf16 v[4:7], v[176:179], v[168:171], v[4:7]
	v_mfma_f32_16x16x32_bf16 v[0:3], v[184:187], v[168:171], v[0:3]
	v_mfma_f32_16x16x32_bf16 v[52:55], v[180:183], v[148:151], v[52:55]
	v_mfma_f32_16x16x32_bf16 v[48:51], v[188:191], v[148:151], v[48:51]
	v_mfma_f32_16x16x32_bf16 v[36:39], v[180:183], v[156:159], v[36:39]
	v_mfma_f32_16x16x32_bf16 v[32:35], v[188:191], v[156:159], v[32:35]
	v_mfma_f32_16x16x32_bf16 v[20:23], v[180:183], v[164:167], v[20:23]
	v_mfma_f32_16x16x32_bf16 v[16:19], v[188:191], v[164:167], v[16:19]
	v_mfma_f32_16x16x32_bf16 v[4:7], v[180:183], v[172:175], v[4:7]
	v_mfma_f32_16x16x32_bf16 v[0:3], v[188:191], v[172:175], v[0:3]
	s_add_i32 s28, 0, 0x18000
	v_add_u32_e32 v92, s28, v218
	s_barrier
	ds_read_b128 v[64:67], v92
	ds_read_b128 v[68:71], v92 offset:1024
	ds_read_b128 v[84:87], v92 offset:2048
	ds_read_b128 v[92:95], v92 offset:3072
	s_add_u32 s64, s64, 0x40000
	s_addc_u32 s65, s65, 0
	s_mov_b32 m0, s80
	v_lshl_add_u64 v[176:177], s[64:65], 0, v[196:197]
	ds_read_b128 v[144:147], v222 offset:32768
	ds_read_b128 v[148:151], v222 offset:33792
	ds_read_b128 v[152:155], v222 offset:34816
	ds_read_b128 v[156:159], v222 offset:35840
	ds_read_b128 v[160:163], v222 offset:36864
	ds_read_b128 v[164:167], v222 offset:37888
	ds_read_b128 v[168:171], v222 offset:38912
	ds_read_b128 v[172:175], v222 offset:39936
	global_load_lds_dwordx4 v[176:177], off
	v_lshl_add_u64 v[176:177], s[64:65], 0, v[200:201]
	s_mov_b32 m0, s81
	s_nop 0
	global_load_lds_dwordx4 v[176:177], off
	s_waitcnt lgkmcnt(8)
	s_barrier
	s_waitcnt lgkmcnt(0)
	v_mfma_f32_16x16x32_bf16 v[140:143], v[64:67], v[144:147], v[140:143]
	v_mfma_f32_16x16x32_bf16 v[136:139], v[84:87], v[144:147], v[136:139]
	v_mfma_f32_16x16x32_bf16 v[124:127], v[64:67], v[152:155], v[124:127]
	v_mfma_f32_16x16x32_bf16 v[120:123], v[84:87], v[152:155], v[120:123]
	v_mfma_f32_16x16x32_bf16 v[108:111], v[64:67], v[160:163], v[108:111]
	v_mfma_f32_16x16x32_bf16 v[104:107], v[84:87], v[160:163], v[104:107]
	v_mfma_f32_16x16x32_bf16 v[88:91], v[64:67], v[168:171], v[88:91]
	v_mfma_f32_16x16x32_bf16 v[80:83], v[84:87], v[168:171], v[80:83]
	v_mfma_f32_16x16x32_bf16 v[140:143], v[68:71], v[148:151], v[140:143]
	v_mfma_f32_16x16x32_bf16 v[136:139], v[92:95], v[148:151], v[136:139]
	v_mfma_f32_16x16x32_bf16 v[124:127], v[68:71], v[156:159], v[124:127]
	v_mfma_f32_16x16x32_bf16 v[120:123], v[92:95], v[156:159], v[120:123]
	v_mfma_f32_16x16x32_bf16 v[108:111], v[68:71], v[164:167], v[108:111]
	v_mfma_f32_16x16x32_bf16 v[104:107], v[92:95], v[164:167], v[104:107]
	v_mfma_f32_16x16x32_bf16 v[88:91], v[68:71], v[172:175], v[88:91]
	v_mfma_f32_16x16x32_bf16 v[80:83], v[92:95], v[172:175], v[80:83]
	s_barrier
	s_add_i32 s29, 0, 0x1c000
	s_add_i32 s28, s28, s67
	v_add_u32_e32 v188, s29, v218
	v_lshl_add_u64 v[212:213], v[212:213], 0, s[52:53]
	s_mov_b32 m0, s28
	ds_read_b128 v[176:179], v188
	ds_read_b128 v[180:183], v188 offset:1024
	ds_read_b128 v[184:187], v188 offset:2048
	ds_read_b128 v[188:191], v188 offset:3072
	global_load_lds_dwordx4 v[212:213], off
	v_lshl_add_u64 v[212:213], v[214:215], 0, s[52:53]
	s_add_i32 m0, s28, 0x2000
	s_nop 0
	global_load_lds_dwordx4 v[212:213], off
	s_barrier
	s_waitcnt lgkmcnt(0)
	v_mfma_f32_16x16x32_bf16 v[132:135], v[176:179], v[144:147], v[132:135]
	v_mfma_f32_16x16x32_bf16 v[128:131], v[184:187], v[144:147], v[128:131]
	v_mfma_f32_16x16x32_bf16 v[116:119], v[176:179], v[152:155], v[116:119]
	v_mfma_f32_16x16x32_bf16 v[112:115], v[184:187], v[152:155], v[112:115]
	v_mfma_f32_16x16x32_bf16 v[100:103], v[176:179], v[160:163], v[100:103]
	v_mfma_f32_16x16x32_bf16 v[96:99], v[184:187], v[160:163], v[96:99]
	v_mfma_f32_16x16x32_bf16 v[76:79], v[176:179], v[168:171], v[76:79]
	v_mfma_f32_16x16x32_bf16 v[72:75], v[184:187], v[168:171], v[72:75]
	v_mfma_f32_16x16x32_bf16 v[132:135], v[180:183], v[148:151], v[132:135]
	v_mfma_f32_16x16x32_bf16 v[128:131], v[188:191], v[148:151], v[128:131]
	v_mfma_f32_16x16x32_bf16 v[116:119], v[180:183], v[156:159], v[116:119]
	v_mfma_f32_16x16x32_bf16 v[112:115], v[188:191], v[156:159], v[112:115]
	v_mfma_f32_16x16x32_bf16 v[100:103], v[180:183], v[164:167], v[100:103]
	v_mfma_f32_16x16x32_bf16 v[96:99], v[188:191], v[164:167], v[96:99]
	v_mfma_f32_16x16x32_bf16 v[76:79], v[180:183], v[172:175], v[76:79]
	v_mfma_f32_16x16x32_bf16 v[72:75], v[188:191], v[172:175], v[72:75]
	s_mov_b32 m0, s85
	v_lshl_add_u64 v[212:213], v[216:217], 0, s[52:53]
	s_barrier
	ds_read_b128 v[144:147], v222 offset:49152
	ds_read_b128 v[148:151], v222 offset:50176
	ds_read_b128 v[152:155], v222 offset:51200
	ds_read_b128 v[156:159], v222 offset:52224
	ds_read_b128 v[160:163], v222 offset:53248
	ds_read_b128 v[164:167], v222 offset:54272
	ds_read_b128 v[168:171], v222 offset:55296
	ds_read_b128 v[172:175], v222 offset:56320
	global_load_lds_dwordx4 v[212:213], off
	v_lshl_add_u64 v[212:213], v[226:227], 0, s[52:53]
	s_mov_b32 m0, s87
	s_nop 0
	global_load_lds_dwordx4 v[212:213], off
	s_barrier
	s_waitcnt lgkmcnt(0)
	v_mfma_f32_16x16x32_bf16 v[60:63], v[64:67], v[144:147], v[60:63]
	v_mfma_f32_16x16x32_bf16 v[56:59], v[84:87], v[144:147], v[56:59]
	v_mfma_f32_16x16x32_bf16 v[44:47], v[64:67], v[152:155], v[44:47]
	v_mfma_f32_16x16x32_bf16 v[40:43], v[84:87], v[152:155], v[40:43]
	v_mfma_f32_16x16x32_bf16 v[28:31], v[64:67], v[160:163], v[28:31]
	v_mfma_f32_16x16x32_bf16 v[24:27], v[84:87], v[160:163], v[24:27]
	v_mfma_f32_16x16x32_bf16 v[12:15], v[64:67], v[168:171], v[12:15]
	v_mfma_f32_16x16x32_bf16 v[8:11], v[84:87], v[168:171], v[8:11]
	v_mfma_f32_16x16x32_bf16 v[60:63], v[68:71], v[148:151], v[60:63]
	v_mfma_f32_16x16x32_bf16 v[56:59], v[92:95], v[148:151], v[56:59]
	v_mfma_f32_16x16x32_bf16 v[44:47], v[68:71], v[156:159], v[44:47]
	v_mfma_f32_16x16x32_bf16 v[40:43], v[92:95], v[156:159], v[40:43]
	v_mfma_f32_16x16x32_bf16 v[28:31], v[68:71], v[164:167], v[28:31]
	v_mfma_f32_16x16x32_bf16 v[24:27], v[92:95], v[164:167], v[24:27]
	v_mfma_f32_16x16x32_bf16 v[12:15], v[68:71], v[172:175], v[12:15]
	v_mfma_f32_16x16x32_bf16 v[8:11], v[92:95], v[172:175], v[8:11]
	s_barrier
	s_add_u32 s62, s62, 0x10080
	s_addc_u32 s63, s63, 0
	s_add_i32 s28, s29, s67
	v_lshl_add_u64 v[64:65], s[62:63], 0, v[198:199]
	s_mov_b32 m0, s28
	s_nop 0
	global_load_lds_dwordx4 v[64:65], off
	v_lshl_add_u64 v[64:65], s[62:63], 0, v[202:203]
	s_add_i32 m0, s28, 0x2000
	s_nop 0
	global_load_lds_dwordx4 v[64:65], off
	s_waitcnt vmcnt(6)
	s_barrier
	v_mfma_f32_16x16x32_bf16 v[52:55], v[176:179], v[144:147], v[52:55]
	v_mfma_f32_16x16x32_bf16 v[48:51], v[184:187], v[144:147], v[48:51]
	v_mfma_f32_16x16x32_bf16 v[36:39], v[176:179], v[152:155], v[36:39]
	v_mfma_f32_16x16x32_bf16 v[32:35], v[184:187], v[152:155], v[32:35]
	v_mfma_f32_16x16x32_bf16 v[20:23], v[176:179], v[160:163], v[20:23]
	v_mfma_f32_16x16x32_bf16 v[16:19], v[184:187], v[160:163], v[16:19]
	v_mfma_f32_16x16x32_bf16 v[4:7], v[176:179], v[168:171], v[4:7]
	v_mfma_f32_16x16x32_bf16 v[0:3], v[184:187], v[168:171], v[0:3]
	v_mfma_f32_16x16x32_bf16 v[52:55], v[180:183], v[148:151], v[52:55]
	v_mfma_f32_16x16x32_bf16 v[48:51], v[188:191], v[148:151], v[48:51]
	v_mfma_f32_16x16x32_bf16 v[36:39], v[180:183], v[156:159], v[36:39]
	v_mfma_f32_16x16x32_bf16 v[32:35], v[188:191], v[156:159], v[32:35]
	v_mfma_f32_16x16x32_bf16 v[20:23], v[180:183], v[164:167], v[20:23]
	v_mfma_f32_16x16x32_bf16 v[16:19], v[188:191], v[164:167], v[16:19]
	v_mfma_f32_16x16x32_bf16 v[4:7], v[180:183], v[172:175], v[4:7]
	v_mfma_f32_16x16x32_bf16 v[0:3], v[188:191], v[172:175], v[0:3]
	s_add_i32 s92, s92, 2
	s_add_u32 s10, s10, 0x100
	s_addc_u32 s11, s11, 0
	s_add_u32 s55, s55, 0x100
	s_addc_u32 s57, s57, 0
	s_cmp_gt_u32 s92, 13
	s_barrier
	s_cbranch_scc0 .LBB0_740
	v_lshl_add_u32 v212, s8, 8, v195
	v_lshl_or_b32 v214, s12, 8, v219
	v_ashrrev_i32_e32 v213, 31, v212
	v_ashrrev_i32_e32 v215, 31, v214
	s_mov_b64 s[8:9], -1
	s_and_b64 vcc, exec, s[48:49]
	s_cbranch_vccz .LBB0_743
	v_lshlrev_b64 v[64:65], 12, v[212:213]
	v_lshl_add_u64 v[64:65], s[36:37], 0, v[64:65]
	v_lshl_add_u64 v[64:65], v[214:215], 2, v[64:65]
	global_load_dwordx4 v[160:163], v[64:65], off offset:16
	global_load_dwordx4 v[164:167], v[64:65], off
	global_load_dwordx4 v[168:171], v[64:65], off offset:144
	global_load_dwordx4 v[172:175], v[64:65], off offset:128
	s_mov_b64 s[8:9], 0

.LBB0_904:
	ds_read_b128 v[146:149], v169
	ds_read_b128 v[150:153], v169 offset:1024
	ds_read_b128 v[154:157], v169 offset:2048
	ds_read_b128 v[174:177], v169 offset:3072
	s_add_u32 s28, s0, 0xfffc0080
	s_addc_u32 s29, s1, -1
	s_cmp_eq_u32 s78, 12
	s_cselect_b32 s53, s7, s29
	s_cselect_b32 s52, s45, s28
	s_cselect_b32 s51, s37, s77
	s_cselect_b32 s50, s67, s76
	v_lshl_add_u64 v[158:159], s[0:1], 0, v[138:139]
	s_add_i32 m0, s54, 0xc000
	ds_read_b128 v[178:181], v171
	ds_read_b128 v[182:185], v171 offset:1024
	ds_read_b128 v[186:189], v171 offset:2048
	ds_read_b128 v[196:199], v171 offset:3072
	ds_read_b128 v[200:203], v171 offset:4096
	ds_read_b128 v[204:207], v171 offset:5120
	ds_read_b128 v[208:211], v171 offset:6144
	ds_read_b128 v[212:215], v171 offset:7168
	global_load_lds_dwordx4 v[158:159], off
	v_lshl_add_u64 v[158:159], s[0:1], 0, v[140:141]
	s_add_i32 m0, s54, 0xe000
	s_nop 0
	global_load_lds_dwordx4 v[158:159], off
	s_waitcnt lgkmcnt(8)
	s_barrier
	s_waitcnt lgkmcnt(0)
	v_mfma_f32_16x16x32_bf16 v[124:127], v[146:149], v[178:181], v[124:127]
	v_mfma_f32_16x16x32_bf16 v[120:123], v[154:157], v[178:181], v[120:123]
	v_mfma_f32_16x16x32_bf16 v[108:111], v[146:149], v[186:189], v[108:111]
	v_mfma_f32_16x16x32_bf16 v[104:107], v[154:157], v[186:189], v[104:107]
	v_mfma_f32_16x16x32_bf16 v[92:95], v[146:149], v[200:203], v[92:95]
	v_mfma_f32_16x16x32_bf16 v[88:91], v[154:157], v[200:203], v[88:91]
	v_mfma_f32_16x16x32_bf16 v[76:79], v[146:149], v[208:211], v[76:79]
	v_mfma_f32_16x16x32_bf16 v[72:75], v[154:157], v[208:211], v[72:75]
	v_mfma_f32_16x16x32_bf16 v[124:127], v[150:153], v[182:185], v[124:127]
	v_mfma_f32_16x16x32_bf16 v[120:123], v[174:177], v[182:185], v[120:123]
	v_mfma_f32_16x16x32_bf16 v[108:111], v[150:153], v[196:199], v[108:111]
	v_mfma_f32_16x16x32_bf16 v[104:107], v[174:177], v[196:199], v[104:107]
	v_mfma_f32_16x16x32_bf16 v[92:95], v[150:153], v[204:207], v[92:95]
	v_mfma_f32_16x16x32_bf16 v[88:91], v[174:177], v[204:207], v[88:91]
	v_mfma_f32_16x16x32_bf16 v[76:79], v[150:153], v[212:215], v[76:79]
	v_mfma_f32_16x16x32_bf16 v[72:75], v[174:177], v[212:215], v[72:75]
	s_barrier
	s_add_i32 s28, s63, s13
	v_lshl_add_u64 v[158:159], s[50:51], 0, v[132:133]
	s_mov_b32 m0, s28
	ds_read_b128 v[216:219], v172
	ds_read_b128 v[220:223], v172 offset:1024
	ds_read_b128 v[224:227], v172 offset:2048
	ds_read_b128 v[228:231], v172 offset:3072
	global_load_lds_dwordx4 v[158:159], off
	v_lshl_add_u64 v[164:165], s[50:51], 0, v[128:129]
	s_add_i32 m0, s28, 0x2000
	s_nop 0
	global_load_lds_dwordx4 v[164:165], off
	s_barrier
	s_waitcnt lgkmcnt(0)
	v_mfma_f32_16x16x32_bf16 v[116:119], v[216:219], v[178:181], v[116:119]
	v_mfma_f32_16x16x32_bf16 v[112:115], v[224:227], v[178:181], v[112:115]
	v_mfma_f32_16x16x32_bf16 v[100:103], v[216:219], v[186:189], v[100:103]
	v_mfma_f32_16x16x32_bf16 v[96:99], v[224:227], v[186:189], v[96:99]
	v_mfma_f32_16x16x32_bf16 v[84:87], v[216:219], v[200:203], v[84:87]
	v_mfma_f32_16x16x32_bf16 v[80:83], v[224:227], v[200:203], v[80:83]
	v_mfma_f32_16x16x32_bf16 v[68:71], v[216:219], v[208:211], v[68:71]
	v_mfma_f32_16x16x32_bf16 v[64:67], v[224:227], v[208:211], v[64:67]
	v_mfma_f32_16x16x32_bf16 v[116:119], v[220:223], v[182:185], v[116:119]
	v_mfma_f32_16x16x32_bf16 v[112:115], v[228:231], v[182:185], v[112:115]
	v_mfma_f32_16x16x32_bf16 v[100:103], v[220:223], v[196:199], v[100:103]
	v_mfma_f32_16x16x32_bf16 v[96:99], v[228:231], v[196:199], v[96:99]
	v_mfma_f32_16x16x32_bf16 v[84:87], v[220:223], v[204:207], v[84:87]
	v_mfma_f32_16x16x32_bf16 v[80:83], v[228:231], v[204:207], v[80:83]
	v_mfma_f32_16x16x32_bf16 v[68:71], v[220:223], v[212:215], v[68:71]
	v_mfma_f32_16x16x32_bf16 v[64:67], v[228:231], v[212:215], v[64:67]
	s_mov_b32 m0, s54
	v_lshl_add_u64 v[190:191], s[52:53], 0, v[134:135]
	s_barrier
	ds_read_b128 v[178:181], v171 offset:16384
	ds_read_b128 v[182:185], v171 offset:17408
	ds_read_b128 v[186:189], v171 offset:18432
	ds_read_b128 v[196:199], v171 offset:19456
	ds_read_b128 v[200:203], v171 offset:20480
	ds_read_b128 v[204:207], v171 offset:21504
	ds_read_b128 v[208:211], v171 offset:22528
	ds_read_b128 v[212:215], v171 offset:23552
	global_load_lds_dwordx4 v[190:191], off
	v_lshl_add_u64 v[232:233], s[52:53], 0, v[130:131]
	s_mov_b32 m0, s55
	s_nop 0
	global_load_lds_dwordx4 v[232:233], off
	s_barrier
	s_waitcnt lgkmcnt(0)
	v_mfma_f32_16x16x32_bf16 v[60:63], v[146:149], v[178:181], v[60:63]
	v_mfma_f32_16x16x32_bf16 v[56:59], v[154:157], v[178:181], v[56:59]
	v_mfma_f32_16x16x32_bf16 v[44:47], v[146:149], v[186:189], v[44:47]
	v_mfma_f32_16x16x32_bf16 v[40:43], v[154:157], v[186:189], v[40:43]
	v_mfma_f32_16x16x32_bf16 v[28:31], v[146:149], v[200:203], v[28:31]
	v_mfma_f32_16x16x32_bf16 v[24:27], v[154:157], v[200:203], v[24:27]
	v_mfma_f32_16x16x32_bf16 v[12:15], v[146:149], v[208:211], v[12:15]
	v_mfma_f32_16x16x32_bf16 v[8:11], v[154:157], v[208:211], v[8:11]
	v_mfma_f32_16x16x32_bf16 v[60:63], v[150:153], v[182:185], v[60:63]
	v_mfma_f32_16x16x32_bf16 v[56:59], v[174:177], v[182:185], v[56:59]
	v_mfma_f32_16x16x32_bf16 v[44:47], v[150:153], v[196:199], v[44:47]
	v_mfma_f32_16x16x32_bf16 v[40:43], v[174:177], v[196:199], v[40:43]
	v_mfma_f32_16x16x32_bf16 v[28:31], v[150:153], v[204:207], v[28:31]
	v_mfma_f32_16x16x32_bf16 v[24:27], v[174:177], v[204:207], v[24:27]
	v_mfma_f32_16x16x32_bf16 v[12:15], v[150:153], v[212:215], v[12:15]
	v_mfma_f32_16x16x32_bf16 v[8:11], v[174:177], v[212:215], v[8:11]
	s_barrier
	s_add_u32 s80, s50, 0x10000
	s_addc_u32 s81, s51, 0
	s_add_i32 s28, s64, s13
	v_lshl_add_u64 v[146:147], s[80:81], 0, v[132:133]
	s_mov_b32 m0, s28
	s_nop 0
	global_load_lds_dwordx4 v[146:147], off
	v_lshl_add_u64 v[146:147], s[80:81], 0, v[128:129]
	s_add_i32 m0, s28, 0x2000
	s_nop 0
	global_load_lds_dwordx4 v[146:147], off
	s_waitcnt vmcnt(6)
	s_barrier
	v_mfma_f32_16x16x32_bf16 v[52:55], v[216:219], v[178:181], v[52:55]
	v_mfma_f32_16x16x32_bf16 v[48:51], v[224:227], v[178:181], v[48:51]
	v_mfma_f32_16x16x32_bf16 v[36:39], v[216:219], v[186:189], v[36:39]
	v_mfma_f32_16x16x32_bf16 v[32:35], v[224:227], v[186:189], v[32:35]
	v_mfma_f32_16x16x32_bf16 v[20:23], v[216:219], v[200:203], v[20:23]
	v_mfma_f32_16x16x32_bf16 v[16:19], v[224:227], v[200:203], v[16:19]
	v_mfma_f32_16x16x32_bf16 v[4:7], v[216:219], v[208:211], v[4:7]
	v_mfma_f32_16x16x32_bf16 v[0:3], v[224:227], v[208:211], v[0:3]
	v_mfma_f32_16x16x32_bf16 v[52:55], v[220:223], v[182:185], v[52:55]
	v_mfma_f32_16x16x32_bf16 v[48:51], v[228:231], v[182:185], v[48:51]
	v_mfma_f32_16x16x32_bf16 v[36:39], v[220:223], v[196:199], v[36:39]
	v_mfma_f32_16x16x32_bf16 v[32:35], v[228:231], v[196:199], v[32:35]
	v_mfma_f32_16x16x32_bf16 v[20:23], v[220:223], v[204:207], v[20:23]
	v_mfma_f32_16x16x32_bf16 v[16:19], v[228:231], v[204:207], v[16:19]
	v_mfma_f32_16x16x32_bf16 v[4:7], v[220:223], v[212:215], v[4:7]
	v_mfma_f32_16x16x32_bf16 v[0:3], v[228:231], v[212:215], v[0:3]
	s_add_i32 s28, 0, 0x18000
	v_add_u32_e32 v160, s28, v163
	s_barrier
	ds_read_b128 v[146:149], v160
	ds_read_b128 v[150:153], v160 offset:1024
	ds_read_b128 v[154:157], v160 offset:2048
	ds_read_b128 v[174:177], v160 offset:3072
	s_add_u32 s52, s52, 0x40000
	s_addc_u32 s53, s53, 0
	s_mov_b32 m0, s56
	v_lshl_add_u64 v[216:217], s[52:53], 0, v[134:135]
	ds_read_b128 v[178:181], v171 offset:32768
	ds_read_b128 v[182:185], v171 offset:33792
	ds_read_b128 v[186:189], v171 offset:34816
	ds_read_b128 v[196:199], v171 offset:35840
	ds_read_b128 v[200:203], v171 offset:36864
	ds_read_b128 v[204:207], v171 offset:37888
	ds_read_b128 v[208:211], v171 offset:38912
	ds_read_b128 v[212:215], v171 offset:39936
	global_load_lds_dwordx4 v[216:217], off
	v_lshl_add_u64 v[216:217], s[52:53], 0, v[130:131]
	s_mov_b32 m0, s57
	s_nop 0
	global_load_lds_dwordx4 v[216:217], off
	s_waitcnt lgkmcnt(8)
	s_barrier
	s_waitcnt lgkmcnt(0)
	v_mfma_f32_16x16x32_bf16 v[124:127], v[146:149], v[178:181], v[124:127]
	v_mfma_f32_16x16x32_bf16 v[120:123], v[154:157], v[178:181], v[120:123]
	v_mfma_f32_16x16x32_bf16 v[108:111], v[146:149], v[186:189], v[108:111]
	v_mfma_f32_16x16x32_bf16 v[104:107], v[154:157], v[186:189], v[104:107]
	v_mfma_f32_16x16x32_bf16 v[92:95], v[146:149], v[200:203], v[92:95]
	v_mfma_f32_16x16x32_bf16 v[88:91], v[154:157], v[200:203], v[88:91]
	v_mfma_f32_16x16x32_bf16 v[76:79], v[146:149], v[208:211], v[76:79]
	v_mfma_f32_16x16x32_bf16 v[72:75], v[154:157], v[208:211], v[72:75]
	v_mfma_f32_16x16x32_bf16 v[124:127], v[150:153], v[182:185], v[124:127]
	v_mfma_f32_16x16x32_bf16 v[120:123], v[174:177], v[182:185], v[120:123]
	v_mfma_f32_16x16x32_bf16 v[108:111], v[150:153], v[196:199], v[108:111]
	v_mfma_f32_16x16x32_bf16 v[104:107], v[174:177], v[196:199], v[104:107]
	v_mfma_f32_16x16x32_bf16 v[92:95], v[150:153], v[204:207], v[92:95]
	v_mfma_f32_16x16x32_bf16 v[88:91], v[174:177], v[204:207], v[88:91]
	v_mfma_f32_16x16x32_bf16 v[76:79], v[150:153], v[212:215], v[76:79]
	v_mfma_f32_16x16x32_bf16 v[72:75], v[174:177], v[212:215], v[72:75]
	s_barrier
	s_add_i32 s29, 0, 0x1c000
	s_add_i32 s28, s28, s13
	v_add_u32_e32 v160, s29, v163
	v_lshl_add_u64 v[158:159], v[158:159], 0, s[8:9]
	s_mov_b32 m0, s28
	ds_read_b128 v[216:219], v160
	ds_read_b128 v[220:223], v160 offset:1024
	ds_read_b128 v[224:227], v160 offset:2048
	ds_read_b128 v[228:231], v160 offset:3072
	global_load_lds_dwordx4 v[158:159], off
	v_lshl_add_u64 v[158:159], v[164:165], 0, s[8:9]
	s_add_i32 m0, s28, 0x2000
	s_nop 0
	global_load_lds_dwordx4 v[158:159], off
	s_barrier
	s_waitcnt lgkmcnt(0)
	v_mfma_f32_16x16x32_bf16 v[116:119], v[216:219], v[178:181], v[116:119]
	v_mfma_f32_16x16x32_bf16 v[112:115], v[224:227], v[178:181], v[112:115]
	v_mfma_f32_16x16x32_bf16 v[100:103], v[216:219], v[186:189], v[100:103]
	v_mfma_f32_16x16x32_bf16 v[96:99], v[224:227], v[186:189], v[96:99]
	v_mfma_f32_16x16x32_bf16 v[84:87], v[216:219], v[200:203], v[84:87]
	v_mfma_f32_16x16x32_bf16 v[80:83], v[224:227], v[200:203], v[80:83]
	v_mfma_f32_16x16x32_bf16 v[68:71], v[216:219], v[208:211], v[68:71]
	v_mfma_f32_16x16x32_bf16 v[64:67], v[224:227], v[208:211], v[64:67]
	v_mfma_f32_16x16x32_bf16 v[116:119], v[220:223], v[182:185], v[116:119]
	v_mfma_f32_16x16x32_bf16 v[112:115], v[228:231], v[182:185], v[112:115]
	v_mfma_f32_16x16x32_bf16 v[100:103], v[220:223], v[196:199], v[100:103]
	v_mfma_f32_16x16x32_bf16 v[96:99], v[228:231], v[196:199], v[96:99]
	v_mfma_f32_16x16x32_bf16 v[84:87], v[220:223], v[204:207], v[84:87]
	v_mfma_f32_16x16x32_bf16 v[80:83], v[228:231], v[204:207], v[80:83]
	v_mfma_f32_16x16x32_bf16 v[68:71], v[220:223], v[212:215], v[68:71]
	v_mfma_f32_16x16x32_bf16 v[64:67], v[228:231], v[212:215], v[64:67]
	s_mov_b32 m0, s60
	v_lshl_add_u64 v[158:159], v[190:191], 0, s[8:9]
	s_barrier
	ds_read_b128 v[178:181], v171 offset:49152
	ds_read_b128 v[182:185], v171 offset:50176
	ds_read_b128 v[186:189], v171 offset:51200
	ds_read_b128 v[196:199], v171 offset:52224
	ds_read_b128 v[200:203], v171 offset:53248
	ds_read_b128 v[204:207], v171 offset:54272
	ds_read_b128 v[208:211], v171 offset:55296
	ds_read_b128 v[212:215], v171 offset:56320
	global_load_lds_dwordx4 v[158:159], off
	v_lshl_add_u64 v[158:159], v[232:233], 0, s[8:9]
	s_mov_b32 m0, s61
	s_nop 0
	global_load_lds_dwordx4 v[158:159], off
	s_barrier
	s_waitcnt lgkmcnt(0)
	v_mfma_f32_16x16x32_bf16 v[60:63], v[146:149], v[178:181], v[60:63]
	v_mfma_f32_16x16x32_bf16 v[56:59], v[154:157], v[178:181], v[56:59]
	v_mfma_f32_16x16x32_bf16 v[44:47], v[146:149], v[186:189], v[44:47]
	v_mfma_f32_16x16x32_bf16 v[40:43], v[154:157], v[186:189], v[40:43]
	v_mfma_f32_16x16x32_bf16 v[28:31], v[146:149], v[200:203], v[28:31]
	v_mfma_f32_16x16x32_bf16 v[24:27], v[154:157], v[200:203], v[24:27]
	v_mfma_f32_16x16x32_bf16 v[12:15], v[146:149], v[208:211], v[12:15]
	v_mfma_f32_16x16x32_bf16 v[8:11], v[154:157], v[208:211], v[8:11]
	v_mfma_f32_16x16x32_bf16 v[60:63], v[150:153], v[182:185], v[60:63]
	v_mfma_f32_16x16x32_bf16 v[56:59], v[174:177], v[182:185], v[56:59]
	v_mfma_f32_16x16x32_bf16 v[44:47], v[150:153], v[196:199], v[44:47]
	v_mfma_f32_16x16x32_bf16 v[40:43], v[174:177], v[196:199], v[40:43]
	v_mfma_f32_16x16x32_bf16 v[28:31], v[150:153], v[204:207], v[28:31]
	v_mfma_f32_16x16x32_bf16 v[24:27], v[174:177], v[204:207], v[24:27]
	v_mfma_f32_16x16x32_bf16 v[12:15], v[150:153], v[212:215], v[12:15]
	v_mfma_f32_16x16x32_bf16 v[8:11], v[174:177], v[212:215], v[8:11]
	s_barrier
	s_add_u32 s50, s50, 0x10080
	s_addc_u32 s51, s51, 0
	s_add_i32 s28, s29, s13
	v_lshl_add_u64 v[146:147], s[50:51], 0, v[132:133]
	s_mov_b32 m0, s28
	s_nop 0
	global_load_lds_dwordx4 v[146:147], off
	v_lshl_add_u64 v[146:147], s[50:51], 0, v[128:129]
	s_add_i32 m0, s28, 0x2000
	s_nop 0
	global_load_lds_dwordx4 v[146:147], off
	s_waitcnt vmcnt(6)
	s_barrier
	v_mfma_f32_16x16x32_bf16 v[52:55], v[216:219], v[178:181], v[52:55]
	v_mfma_f32_16x16x32_bf16 v[48:51], v[224:227], v[178:181], v[48:51]
	v_mfma_f32_16x16x32_bf16 v[36:39], v[216:219], v[186:189], v[36:39]
	v_mfma_f32_16x16x32_bf16 v[32:35], v[224:227], v[186:189], v[32:35]
	v_mfma_f32_16x16x32_bf16 v[20:23], v[216:219], v[200:203], v[20:23]
	v_mfma_f32_16x16x32_bf16 v[16:19], v[224:227], v[200:203], v[16:19]
	v_mfma_f32_16x16x32_bf16 v[4:7], v[216:219], v[208:211], v[4:7]
	v_mfma_f32_16x16x32_bf16 v[0:3], v[224:227], v[208:211], v[0:3]
	v_mfma_f32_16x16x32_bf16 v[52:55], v[220:223], v[182:185], v[52:55]
	v_mfma_f32_16x16x32_bf16 v[48:51], v[228:231], v[182:185], v[48:51]
	v_mfma_f32_16x16x32_bf16 v[36:39], v[220:223], v[196:199], v[36:39]
	v_mfma_f32_16x16x32_bf16 v[32:35], v[228:231], v[196:199], v[32:35]
	v_mfma_f32_16x16x32_bf16 v[20:23], v[220:223], v[204:207], v[20:23]
	v_mfma_f32_16x16x32_bf16 v[16:19], v[228:231], v[204:207], v[16:19]
	v_mfma_f32_16x16x32_bf16 v[4:7], v[220:223], v[212:215], v[4:7]
	v_mfma_f32_16x16x32_bf16 v[0:3], v[228:231], v[212:215], v[0:3]
	s_add_i32 s78, s78, 2
	s_add_u32 s0, s0, 0x100
	s_addc_u32 s1, s1, 0
	s_add_u32 s76, s76, 0x100
	s_addc_u32 s77, s77, 0
	s_cmp_gt_u32 s78, 13
	s_barrier
	s_cbranch_scc0 .LBB0_904
	v_lshl_add_u32 v146, s6, 8, v161
	v_or_b32_e32 v164, 16, v146
	v_ashrrev_i32_e32 v165, 31, v164
	v_lshlrev_b64 v[148:149], 6, v[164:165]
	v_or_b32_e32 v158, 32, v146
	v_lshl_add_u64 v[148:149], v[136:137], 0, v[148:149]
	v_ashrrev_i32_e32 v159, 31, v158
	v_or_b32_e32 v156, 48, v146
	global_load_dwordx4 v[174:177], v[148:149], off
	v_lshlrev_b64 v[148:149], 6, v[158:159]
	v_ashrrev_i32_e32 v157, 31, v156
	v_add_u32_e32 v154, 0x80, v146
	v_lshl_add_u64 v[148:149], v[136:137], 0, v[148:149]
	v_lshlrev_b64 v[150:151], 6, v[156:157]
	v_ashrrev_i32_e32 v155, 31, v154
	v_lshl_add_u64 v[150:151], v[136:137], 0, v[150:151]
	global_load_dwordx4 v[178:181], v[148:149], off
	global_load_dwordx4 v[182:185], v[150:151], off
	v_lshlrev_b64 v[148:149], 6, v[154:155]
	v_lshl_add_u64 v[148:149], v[136:137], 0, v[148:149]
	global_load_dwordx4 v[186:189], v[148:149], off
	v_ashrrev_i32_e32 v147, 31, v146
	v_lshlrev_b64 v[148:149], 6, v[146:147]
	v_add_u32_e32 v152, 0x90, v146
	v_lshl_add_u64 v[148:149], v[136:137], 0, v[148:149]
	v_ashrrev_i32_e32 v153, 31, v152
	global_load_dwordx4 v[196:199], v[148:149], off
	v_lshlrev_b64 v[148:149], 6, v[152:153]
	v_lshl_add_u64 v[148:149], v[136:137], 0, v[148:149]
	global_load_dwordx4 v[200:203], v[148:149], off
	v_add_u32_e32 v148, 0xa0, v146
	v_ashrrev_i32_e32 v149, 31, v148
	v_lshlrev_b64 v[150:151], 6, v[148:149]
	v_lshl_add_u64 v[150:151], v[136:137], 0, v[150:151]
	global_load_dwordx4 v[204:207], v[150:151], off
	v_add_u32_e32 v150, 0xb0, v146
	v_ashrrev_i32_e32 v151, 31, v150
	v_lshlrev_b64 v[208:209], 6, v[150:151]
	v_lshl_add_u64 v[208:209], v[136:137], 0, v[208:209]
	global_load_dwordx4 v[208:211], v[208:209], off
	v_and_b32_e32 v149, 64, v173
	v_xor_b32_e32 v147, 16, v173
	v_add_u32_e32 v149, 64, v149
	v_cmp_lt_i32_e32 vcc, v147, v149
	v_xor_b32_e32 v153, 32, v173
	v_mov_b64_e32 v[190:191], s[12:13]
	v_cndmask_b32_e32 v147, v173, v147, vcc
	v_lshlrev_b32_e32 v147, 2, v147
	v_cmp_lt_i32_e32 vcc, v153, v149
	s_waitcnt vmcnt(0)
	v_mov_b32_e32 v212, v175
	v_mov_b32_e32 v213, v176
	v_mov_b32_e32 v175, v177
	v_pk_add_f32 v[174:175], v[212:213], v[174:175]
	v_cndmask_b32_e32 v149, v173, v153, vcc
	v_lshlrev_b32_e32 v149, 2, v149
	v_mov_b32_e32 v176, v179
	v_mov_b32_e32 v177, v180
	v_mov_b32_e32 v179, v181
	v_mov_b32_e32 v180, v183
	v_mov_b32_e32 v181, v184
	v_mov_b32_e32 v183, v185
	v_mov_b32_e32 v184, v187
	v_mov_b32_e32 v185, v188
	v_mov_b32_e32 v187, v189
	v_pk_add_f32 v[176:177], v[176:177], v[178:179]
	v_pk_add_f32 v[178:179], v[180:181], v[182:183]
	v_pk_add_f32 v[180:181], v[184:185], v[186:187]
	v_mov_b32_e32 v182, v176
	v_mov_b32_e32 v183, v174
	v_mov_b32_e32 v174, v177
	v_mov_b32_e32 v176, v180
	v_mov_b32_e32 v177, v178
	v_mov_b32_e32 v178, v181
	v_pk_add_f32 v[174:175], v[182:183], v[174:175]
	v_pk_add_f32 v[176:177], v[176:177], v[178:179]
	ds_bpermute_b32 v179, v147, v175
	ds_bpermute_b32 v178, v147, v174
	ds_bpermute_b32 v181, v147, v177
	ds_bpermute_b32 v180, v147, v176
	v_mov_b32_e32 v184, v201
	v_mov_b32_e32 v185, v202
	s_waitcnt lgkmcnt(0)
	v_pk_add_f32 v[174:175], v[174:175], v[178:179]
	ds_bpermute_b32 v179, v149, v175
	v_pk_add_f32 v[176:177], v[176:177], v[180:181]
	ds_bpermute_b32 v178, v149, v174
	ds_bpermute_b32 v181, v149, v177
	ds_bpermute_b32 v180, v149, v176
	v_mov_b32_e32 v201, v203
	v_mov_b32_e32 v182, v197
	s_waitcnt lgkmcnt(2)
	v_pk_add_f32 v[174:175], v[174:175], v[178:179]
	v_pk_add_f32 v[178:179], v[184:185], v[200:201]
	s_waitcnt lgkmcnt(0)
	v_pk_add_f32 v[176:177], v[176:177], v[180:181]
	v_pk_fma_f32 v[174:175], v[174:175], s[10:11], v[190:191] op_sel_hi:[1,0,0]
	v_mov_b32_e32 v180, v205
	v_mov_b32_e32 v181, v206
	v_mov_b32_e32 v205, v207
	v_mul_f32_e32 v151, 0x4b800000, v175
	v_cmp_gt_f32_e32 vcc, s65, v175
	v_pk_add_f32 v[180:181], v[180:181], v[204:205]
	v_mov_b32_e32 v185, v178
	v_cndmask_b32_e32 v151, v175, v151, vcc
	v_mov_b32_e32 v184, v180
	v_mov_b32_e32 v178, v181
	v_rsq_f32_e32 v151, v151
	v_pk_add_f32 v[178:179], v[184:185], v[178:179]
	ds_bpermute_b32 v181, v147, v179
	ds_bpermute_b32 v180, v147, v178
	v_pk_fma_f32 v[176:177], v[176:177], s[10:11], v[190:191] op_sel_hi:[1,0,0]
	v_mul_f32_e32 v153, 0x4b800000, v174
	v_cmp_gt_f32_e64 s[0:1], s65, v174
	v_mul_f32_e32 v157, 0x45800000, v151
	v_mul_f32_e32 v155, 0x4b800000, v177
	v_cndmask_b32_e64 v153, v174, v153, s[0:1]
	v_cmp_gt_f32_e64 s[6:7], s65, v177
	v_cndmask_b32_e32 v174, v151, v157, vcc
	v_mul_f32_e32 v151, 0x4b800000, v176
	v_cmp_gt_f32_e32 vcc, s65, v176
	v_cndmask_b32_e64 v155, v177, v155, s[6:7]
	v_rsq_f32_e32 v153, v153
	v_cndmask_b32_e32 v151, v176, v151, vcc
	s_waitcnt lgkmcnt(0)
	v_pk_add_f32 v[176:177], v[178:179], v[180:181]
	ds_bpermute_b32 v179, v149, v177
	ds_bpermute_b32 v178, v149, v176
	v_rsq_f32_e32 v155, v155
	v_mul_f32_e32 v159, 0x45800000, v153
	v_cndmask_b32_e64 v180, v153, v159, s[0:1]
	v_rsq_f32_e32 v151, v151
	s_waitcnt lgkmcnt(0)
	v_pk_add_f32 v[176:177], v[176:177], v[178:179]
	v_mul_f32_e32 v153, 0x45800000, v155
	v_pk_fma_f32 v[176:177], v[176:177], s[10:11], v[190:191] op_sel_hi:[1,0,0]
	v_cndmask_b32_e64 v170, v155, v153, s[6:7]
	v_mul_f32_e32 v155, 0x4b800000, v177
	v_cmp_gt_f32_e64 s[0:1], s65, v177
	v_mul_f32_e32 v157, 0x4b800000, v176
	v_cmp_gt_f32_e64 s[6:7], s65, v176
	v_cndmask_b32_e64 v155, v177, v155, s[0:1]
	v_rsq_f32_e32 v155, v155
	v_cndmask_b32_e64 v157, v176, v157, s[6:7]
	v_rsq_f32_e32 v157, v157
	v_mul_f32_e32 v153, 0x45800000, v151
	v_cndmask_b32_e32 v168, v151, v153, vcc
	v_mul_f32_e32 v151, 0x45800000, v155
	v_mov_b32_e32 v183, v198
	v_mov_b32_e32 v197, v199
	v_cndmask_b32_e64 v166, v155, v151, s[0:1]
	v_mul_f32_e32 v151, 0x45800000, v157
	v_mov_b32_e32 v176, v209
	v_mov_b32_e32 v177, v210
	v_mov_b32_e32 v209, v211
	v_pk_add_f32 v[182:183], v[182:183], v[196:197]
	v_cndmask_b32_e64 v162, v157, v151, s[6:7]
	v_pk_add_f32 v[176:177], v[176:177], v[208:209]
	v_mov_b32_e32 v178, v182
	v_mov_b32_e32 v179, v176
	v_mov_b32_e32 v176, v183
	v_pk_add_f32 v[176:177], v[178:179], v[176:177]
	ds_bpermute_b32 v178, v147, v176
	ds_bpermute_b32 v179, v147, v177
	v_lshl_or_b32 v182, s66, 8, v167
	v_pk_mul_f32 v[100:101], v[100:101], v[174:175] op_sel_hi:[1,0]
	v_pk_mul_f32 v[108:109], v[108:109], v[174:175] op_sel_hi:[1,0]
	v_ashrrev_i32_e32 v183, 31, v182
	s_waitcnt lgkmcnt(0)
	v_pk_add_f32 v[176:177], v[176:177], v[178:179]
	ds_bpermute_b32 v178, v149, v176
	ds_bpermute_b32 v179, v149, v177
	v_pk_mul_f32 v[96:97], v[96:97], v[174:175] op_sel_hi:[1,0]
	v_pk_mul_f32 v[102:103], v[102:103], v[174:175] op_sel_hi:[1,0]
	v_pk_mul_f32 v[110:111], v[110:111], v[174:175] op_sel_hi:[1,0]
	v_cvt_pk_bf16_f32 v108, v108, v109
	s_waitcnt lgkmcnt(0)
	v_pk_add_f32 v[176:177], v[176:177], v[178:179]
	v_pk_mul_f32 v[106:107], v[106:107], v[174:175] op_sel_hi:[1,0]
	v_pk_fma_f32 v[176:177], v[176:177], s[10:11], v[190:191] op_sel_hi:[1,0,0]
	v_pk_mul_f32 v[104:105], v[104:105], v[174:175] op_sel_hi:[1,0]
	v_mul_f32_e32 v147, 0x4b800000, v177
	v_cmp_gt_f32_e32 vcc, s65, v177
	v_mul_f32_e32 v149, 0x4b800000, v176
	v_cmp_gt_f32_e64 s[0:1], s65, v176
	v_cndmask_b32_e32 v147, v177, v147, vcc
	v_rsq_f32_e32 v147, v147
	v_cndmask_b32_e64 v149, v176, v149, s[0:1]
	v_rsq_f32_e32 v149, v149
	v_cvt_pk_bf16_f32 v100, v100, v101
	v_mul_f32_e32 v151, 0x45800000, v147
	v_cndmask_b32_e32 v160, v147, v151, vcc
	v_mul_f32_e32 v147, 0x45800000, v149
	v_cndmask_b32_e64 v176, v149, v147, s[0:1]
	v_pk_mul_f32 v[112:113], v[112:113], v[176:177] op_sel_hi:[1,0]
	v_pk_mul_f32 v[116:117], v[116:117], v[176:177] op_sel_hi:[1,0]
	v_pk_mul_f32 v[124:125], v[124:125], v[176:177] op_sel_hi:[1,0]
	v_pk_mul_f32 v[122:123], v[122:123], v[176:177] op_sel_hi:[1,0]
	v_pk_mul_f32 v[120:121], v[120:121], v[176:177] op_sel_hi:[1,0]
	v_pk_mul_f32 v[114:115], v[114:115], v[176:177] op_sel_hi:[1,0]
	v_pk_mul_f32 v[118:119], v[118:119], v[176:177] op_sel_hi:[1,0]
	v_pk_mul_f32 v[126:127], v[126:127], v[176:177] op_sel_hi:[1,0]
	v_cvt_pk_bf16_f32 v124, v124, v125
	v_cvt_pk_bf16_f32 v120, v120, v121
	v_cvt_pk_bf16_f32 v121, v122, v123
	v_cvt_pk_bf16_f32 v122, v116, v117
	v_cvt_pk_bf16_f32 v112, v112, v113
	v_cvt_pk_bf16_f32 v125, v126, v127
	v_cvt_pk_bf16_f32 v118, v118, v119
	v_cvt_pk_bf16_f32 v113, v114, v115
	v_cndmask_b32_e64 v114, v124, v122, s[2:3]
	v_mov_b32_e32 v123, 0
	v_cndmask_b32_e64 v115, v120, v112, s[2:3]
	v_mov_b32_e32 v126, 0
	v_mov_b32_dpp v123, v114 row_ror:8 row_mask:0xf bank_mask:0xf
	v_cndmask_b32_e64 v114, v125, v118, s[2:3]
	v_mov_b32_e32 v119, 0
	v_mov_b32_dpp v126, v115 row_ror:8 row_mask:0xf bank_mask:0xf
	v_mov_b32_e32 v127, 0
	v_mov_b32_dpp v119, v114 row_ror:8 row_mask:0xf bank_mask:0xf
	v_cndmask_b32_e64 v114, v121, v113, s[2:3]
	v_cndmask_b32_e64 v116, v126, v120, s[2:3]
	v_cndmask_b32_e64 v120, v112, v126, s[2:3]
	v_add_u32_e32 v112, -8, v146
	v_mov_b32_dpp v127, v114 row_ror:8 row_mask:0xf bank_mask:0xf
	v_cndmask_b32_e64 v112, v112, v146, s[2:3]
	v_cndmask_b32_e64 v117, v127, v121, s[2:3]
	v_cndmask_b32_e64 v121, v113, v127, s[2:3]
	v_ashrrev_i32_e32 v113, 31, v112
	v_lshlrev_b64 v[112:113], 10, v[112:113]
	v_cndmask_b32_e64 v115, v119, v125, s[2:3]
	v_cndmask_b32_e64 v114, v123, v124, s[2:3]
	v_cndmask_b32_e64 v119, v118, v119, s[2:3]
	v_cndmask_b32_e64 v118, v122, v123, s[2:3]
	v_lshl_add_u64 v[122:123], s[38:39], 0, v[112:113]
	v_lshlrev_b64 v[112:113], 1, v[182:183]
	v_pk_mul_f32 v[98:99], v[98:99], v[174:175] op_sel_hi:[1,0]
	v_cvt_pk_bf16_f32 v109, v110, v111
	v_cvt_pk_bf16_f32 v104, v104, v105
	v_cvt_pk_bf16_f32 v105, v106, v107
	v_cvt_pk_bf16_f32 v101, v102, v103
	v_cvt_pk_bf16_f32 v102, v96, v97
	v_cndmask_b32_e64 v96, v108, v100, s[2:3]
	v_mov_b32_e32 v106, 0
	v_lshl_add_u64 v[122:123], v[122:123], 0, v[112:113]
	v_cvt_pk_bf16_f32 v103, v98, v99
	v_mov_b32_dpp v106, v96 row_ror:8 row_mask:0xf bank_mask:0xf
	v_cndmask_b32_e64 v96, v109, v101, s[2:3]
	v_mov_b32_e32 v107, 0
	v_cndmask_b32_e64 v97, v104, v102, s[2:3]
	v_mov_b32_e32 v110, 0
	global_store_dwordx4 v[122:123], v[114:117], off
	v_mov_b32_dpp v107, v96 row_ror:8 row_mask:0xf bank_mask:0xf
	v_cndmask_b32_e64 v96, v105, v103, s[2:3]
	v_add_u32_e32 v116, 8, v146
	v_mov_b32_dpp v110, v97 row_ror:8 row_mask:0xf bank_mask:0xf
	v_mov_b32_e32 v111, 0
	v_cndmask_b32_e64 v114, v146, v116, s[2:3]
	v_cndmask_b32_e64 v98, v110, v104, s[2:3]
	v_mov_b32_dpp v111, v96 row_ror:8 row_mask:0xf bank_mask:0xf
	v_cndmask_b32_e64 v104, v116, v164, s[2:3]
	v_ashrrev_i32_e32 v115, 31, v114
	v_cndmask_b32_e64 v99, v111, v105, s[2:3]
	v_ashrrev_i32_e32 v105, 31, v104
	v_pk_mul_f32 v[84:85], v[84:85], v[180:181] op_sel_hi:[1,0]
	v_pk_mul_f32 v[92:93], v[92:93], v[180:181] op_sel_hi:[1,0]
	v_lshlrev_b64 v[114:115], 10, v[114:115]
	v_lshlrev_b64 v[104:105], 10, v[104:105]
	v_pk_mul_f32 v[80:81], v[80:81], v[180:181] op_sel_hi:[1,0]
	v_pk_mul_f32 v[86:87], v[86:87], v[180:181] op_sel_hi:[1,0]
	v_pk_mul_f32 v[94:95], v[94:95], v[180:181] op_sel_hi:[1,0]
	v_cvt_pk_bf16_f32 v92, v92, v93
	v_pk_mul_f32 v[90:91], v[90:91], v[180:181] op_sel_hi:[1,0]
	v_pk_mul_f32 v[88:89], v[88:89], v[180:181] op_sel_hi:[1,0]
	v_cvt_pk_bf16_f32 v84, v84, v85
	v_lshl_add_u64 v[114:115], s[38:39], 0, v[114:115]
	v_lshl_add_u64 v[104:105], s[38:39], 0, v[104:105]
	v_pk_mul_f32 v[82:83], v[82:83], v[180:181] op_sel_hi:[1,0]
	v_cvt_pk_bf16_f32 v93, v94, v95
	v_cvt_pk_bf16_f32 v88, v88, v89
	v_cvt_pk_bf16_f32 v89, v90, v91
	v_cvt_pk_bf16_f32 v85, v86, v87
	v_cvt_pk_bf16_f32 v86, v80, v81
	v_cndmask_b32_e64 v80, v92, v84, s[2:3]
	v_mov_b32_e32 v90, 0
	v_lshl_add_u64 v[114:115], v[114:115], 0, v[112:113]
	v_cndmask_b32_e64 v97, v107, v109, s[2:3]
	v_cndmask_b32_e64 v96, v106, v108, s[2:3]
	v_lshl_add_u64 v[104:105], v[104:105], 0, v[112:113]
	v_cvt_pk_bf16_f32 v87, v82, v83
	v_mov_b32_dpp v90, v80 row_ror:8 row_mask:0xf bank_mask:0xf
	v_cndmask_b32_e64 v80, v93, v85, s[2:3]
	v_mov_b32_e32 v91, 0
	v_cndmask_b32_e64 v81, v88, v86, s[2:3]
	v_mov_b32_e32 v94, 0
	global_store_dwordx4 v[114:115], v[118:121], off
	global_store_dwordx4 v[104:105], v[96:99], off
	v_mov_b32_dpp v91, v80 row_ror:8 row_mask:0xf bank_mask:0xf
	v_cndmask_b32_e64 v80, v89, v87, s[2:3]
	v_add_u32_e32 v98, 24, v146
	v_mov_b32_dpp v94, v81 row_ror:8 row_mask:0xf bank_mask:0xf
	v_mov_b32_e32 v95, 0
	v_cndmask_b32_e64 v96, v164, v98, s[2:3]
	v_cndmask_b32_e64 v82, v94, v88, s[2:3]
	v_mov_b32_dpp v95, v80 row_ror:8 row_mask:0xf bank_mask:0xf
	v_cndmask_b32_e64 v88, v98, v158, s[2:3]
	v_ashrrev_i32_e32 v97, 31, v96
	v_cndmask_b32_e64 v83, v95, v89, s[2:3]
	v_ashrrev_i32_e32 v89, 31, v88
	v_pk_mul_f32 v[68:69], v[68:69], v[170:171] op_sel_hi:[1,0]
	v_pk_mul_f32 v[76:77], v[76:77], v[170:171] op_sel_hi:[1,0]
	v_lshlrev_b64 v[96:97], 10, v[96:97]
	v_lshlrev_b64 v[88:89], 10, v[88:89]
	v_pk_mul_f32 v[64:65], v[64:65], v[170:171] op_sel_hi:[1,0]
	v_pk_mul_f32 v[70:71], v[70:71], v[170:171] op_sel_hi:[1,0]
	v_pk_mul_f32 v[78:79], v[78:79], v[170:171] op_sel_hi:[1,0]
	v_cvt_pk_bf16_f32 v76, v76, v77
	v_pk_mul_f32 v[74:75], v[74:75], v[170:171] op_sel_hi:[1,0]
	v_pk_mul_f32 v[72:73], v[72:73], v[170:171] op_sel_hi:[1,0]
	v_cvt_pk_bf16_f32 v68, v68, v69
	v_lshl_add_u64 v[96:97], s[38:39], 0, v[96:97]
	v_lshl_add_u64 v[88:89], s[38:39], 0, v[88:89]
	v_pk_mul_f32 v[66:67], v[66:67], v[170:171] op_sel_hi:[1,0]
	v_cvt_pk_bf16_f32 v77, v78, v79
	v_cvt_pk_bf16_f32 v72, v72, v73
	v_cvt_pk_bf16_f32 v73, v74, v75
	v_cvt_pk_bf16_f32 v69, v70, v71
	v_cvt_pk_bf16_f32 v70, v64, v65
	v_cndmask_b32_e64 v64, v76, v68, s[2:3]
	v_mov_b32_e32 v74, 0
	v_cndmask_b32_e64 v103, v103, v111, s[2:3]
	v_cndmask_b32_e64 v102, v102, v110, s[2:3]
	v_cndmask_b32_e64 v101, v101, v107, s[2:3]
	v_cndmask_b32_e64 v100, v100, v106, s[2:3]
	v_lshl_add_u64 v[96:97], v[96:97], 0, v[112:113]
	v_cndmask_b32_e64 v81, v91, v93, s[2:3]
	v_cndmask_b32_e64 v80, v90, v92, s[2:3]
	v_lshl_add_u64 v[88:89], v[88:89], 0, v[112:113]
	v_cvt_pk_bf16_f32 v71, v66, v67
	v_mov_b32_dpp v74, v64 row_ror:8 row_mask:0xf bank_mask:0xf
	v_cndmask_b32_e64 v64, v77, v69, s[2:3]
	v_mov_b32_e32 v75, 0
	v_cndmask_b32_e64 v65, v72, v70, s[2:3]
	v_mov_b32_e32 v78, 0
	global_store_dwordx4 v[96:97], v[100:103], off
	global_store_dwordx4 v[88:89], v[80:83], off
	v_mov_b32_dpp v75, v64 row_ror:8 row_mask:0xf bank_mask:0xf
	v_cndmask_b32_e64 v64, v73, v71, s[2:3]
	v_add_u32_e32 v82, 40, v146
	v_mov_b32_dpp v78, v65 row_ror:8 row_mask:0xf bank_mask:0xf
	v_mov_b32_e32 v79, 0
	v_cndmask_b32_e64 v80, v158, v82, s[2:3]
	v_cndmask_b32_e64 v66, v78, v72, s[2:3]
	v_mov_b32_dpp v79, v64 row_ror:8 row_mask:0xf bank_mask:0xf
	v_cndmask_b32_e64 v72, v82, v156, s[2:3]
	v_ashrrev_i32_e32 v81, 31, v80
	v_cndmask_b32_e64 v67, v79, v73, s[2:3]
	v_ashrrev_i32_e32 v73, 31, v72
	v_pk_mul_f32 v[48:49], v[48:49], v[168:169] op_sel_hi:[1,0]
	v_pk_mul_f32 v[54:55], v[54:55], v[168:169] op_sel_hi:[1,0]
	v_pk_mul_f32 v[52:53], v[52:53], v[168:169] op_sel_hi:[1,0]
	v_pk_mul_f32 v[60:61], v[60:61], v[168:169] op_sel_hi:[1,0]
	v_pk_mul_f32 v[56:57], v[56:57], v[168:169] op_sel_hi:[1,0]
	v_lshlrev_b64 v[80:81], 10, v[80:81]
	v_lshlrev_b64 v[72:73], 10, v[72:73]
	v_pk_mul_f32 v[62:63], v[62:63], v[168:169] op_sel_hi:[1,0]
	v_cvt_pk_bf16_f32 v60, v60, v61
	v_pk_mul_f32 v[58:59], v[58:59], v[168:169] op_sel_hi:[1,0]
	v_cvt_pk_bf16_f32 v56, v56, v57
	v_cvt_pk_bf16_f32 v52, v52, v53
	v_cvt_pk_bf16_f32 v53, v54, v55
	v_cvt_pk_bf16_f32 v54, v48, v49
	v_lshl_add_u64 v[80:81], s[38:39], 0, v[80:81]
	v_lshl_add_u64 v[72:73], s[38:39], 0, v[72:73]
	v_pk_mul_f32 v[50:51], v[50:51], v[168:169] op_sel_hi:[1,0]
	v_cvt_pk_bf16_f32 v61, v62, v63
	v_cvt_pk_bf16_f32 v57, v58, v59
	v_cndmask_b32_e64 v48, v60, v52, s[2:3]
	v_mov_b32_e32 v58, 0
	v_cndmask_b32_e64 v49, v56, v54, s[2:3]
	v_mov_b32_e32 v62, 0
	v_cndmask_b32_e64 v87, v87, v95, s[2:3]
	v_cndmask_b32_e64 v86, v86, v94, s[2:3]
	v_cndmask_b32_e64 v85, v85, v91, s[2:3]
	v_cndmask_b32_e64 v84, v84, v90, s[2:3]
	v_lshl_add_u64 v[80:81], v[80:81], 0, v[112:113]
	v_cndmask_b32_e64 v65, v75, v77, s[2:3]
	v_cndmask_b32_e64 v64, v74, v76, s[2:3]
	v_lshl_add_u64 v[72:73], v[72:73], 0, v[112:113]
	v_cvt_pk_bf16_f32 v55, v50, v51
	v_mov_b32_dpp v58, v48 row_ror:8 row_mask:0xf bank_mask:0xf
	v_cndmask_b32_e64 v48, v61, v53, s[2:3]
	v_mov_b32_e32 v59, 0
	v_mov_b32_dpp v62, v49 row_ror:8 row_mask:0xf bank_mask:0xf
	global_store_dwordx4 v[80:81], v[84:87], off
	global_store_dwordx4 v[72:73], v[64:67], off
	v_mov_b32_dpp v59, v48 row_ror:8 row_mask:0xf bank_mask:0xf
	v_cndmask_b32_e64 v48, v57, v55, s[2:3]
	v_add_u32_e32 v64, 56, v146
	v_mov_b32_e32 v63, 0
	v_cndmask_b32_e64 v50, v62, v56, s[2:3]
	v_add_u32_e32 v56, 0x78, v146
	v_cndmask_b32_e64 v64, v156, v64, s[2:3]
	v_mov_b32_dpp v63, v48 row_ror:8 row_mask:0xf bank_mask:0xf
	v_cndmask_b32_e64 v56, v56, v154, s[2:3]
	v_ashrrev_i32_e32 v65, 31, v64
	v_cndmask_b32_e64 v51, v63, v57, s[2:3]
	v_ashrrev_i32_e32 v57, 31, v56
	v_pk_mul_f32 v[36:37], v[36:37], v[166:167] op_sel_hi:[1,0]
	v_pk_mul_f32 v[44:45], v[44:45], v[166:167] op_sel_hi:[1,0]
	v_lshlrev_b64 v[64:65], 10, v[64:65]
	v_lshlrev_b64 v[56:57], 10, v[56:57]
	v_pk_mul_f32 v[32:33], v[32:33], v[166:167] op_sel_hi:[1,0]
	v_pk_mul_f32 v[38:39], v[38:39], v[166:167] op_sel_hi:[1,0]
	v_pk_mul_f32 v[46:47], v[46:47], v[166:167] op_sel_hi:[1,0]
	v_cvt_pk_bf16_f32 v44, v44, v45
	v_pk_mul_f32 v[42:43], v[42:43], v[166:167] op_sel_hi:[1,0]
	v_pk_mul_f32 v[40:41], v[40:41], v[166:167] op_sel_hi:[1,0]
	v_cvt_pk_bf16_f32 v36, v36, v37
	v_lshl_add_u64 v[64:65], s[38:39], 0, v[64:65]
	v_lshl_add_u64 v[56:57], s[38:39], 0, v[56:57]
	v_pk_mul_f32 v[34:35], v[34:35], v[166:167] op_sel_hi:[1,0]
	v_cvt_pk_bf16_f32 v45, v46, v47
	v_cvt_pk_bf16_f32 v40, v40, v41
	v_cvt_pk_bf16_f32 v41, v42, v43
	v_cvt_pk_bf16_f32 v37, v38, v39
	v_cvt_pk_bf16_f32 v38, v32, v33
	v_cndmask_b32_e64 v32, v44, v36, s[2:3]
	v_mov_b32_e32 v42, 0
	v_cndmask_b32_e64 v71, v71, v79, s[2:3]
	v_cndmask_b32_e64 v70, v70, v78, s[2:3]
	v_cndmask_b32_e64 v69, v69, v75, s[2:3]
	v_cndmask_b32_e64 v68, v68, v74, s[2:3]
	v_lshl_add_u64 v[64:65], v[64:65], 0, v[112:113]
	v_cndmask_b32_e64 v49, v59, v61, s[2:3]
	v_cndmask_b32_e64 v48, v58, v60, s[2:3]
	v_lshl_add_u64 v[56:57], v[56:57], 0, v[112:113]
	v_cvt_pk_bf16_f32 v39, v34, v35
	v_mov_b32_dpp v42, v32 row_ror:8 row_mask:0xf bank_mask:0xf
	v_cndmask_b32_e64 v32, v45, v37, s[2:3]
	v_mov_b32_e32 v43, 0
	v_cndmask_b32_e64 v33, v40, v38, s[2:3]
	v_mov_b32_e32 v46, 0
	global_store_dwordx4 v[64:65], v[68:71], off
	global_store_dwordx4 v[56:57], v[48:51], off
	v_mov_b32_dpp v43, v32 row_ror:8 row_mask:0xf bank_mask:0xf
	v_cndmask_b32_e64 v32, v41, v39, s[2:3]
	v_add_u32_e32 v50, 0x88, v146
	v_mov_b32_dpp v46, v33 row_ror:8 row_mask:0xf bank_mask:0xf
	v_mov_b32_e32 v47, 0
	v_cndmask_b32_e64 v34, v46, v40, s[2:3]
	v_cndmask_b32_e64 v40, v50, v152, s[2:3]
	v_mov_b32_dpp v47, v32 row_ror:8 row_mask:0xf bank_mask:0xf
	v_cndmask_b32_e64 v35, v47, v41, s[2:3]
	v_ashrrev_i32_e32 v41, 31, v40
	v_pk_mul_f32 v[20:21], v[20:21], v[162:163] op_sel_hi:[1,0]
	v_pk_mul_f32 v[28:29], v[28:29], v[162:163] op_sel_hi:[1,0]
	v_lshlrev_b64 v[40:41], 10, v[40:41]
	v_pk_mul_f32 v[16:17], v[16:17], v[162:163] op_sel_hi:[1,0]
	v_pk_mul_f32 v[22:23], v[22:23], v[162:163] op_sel_hi:[1,0]
	v_pk_mul_f32 v[30:31], v[30:31], v[162:163] op_sel_hi:[1,0]
	v_cvt_pk_bf16_f32 v28, v28, v29
	v_pk_mul_f32 v[26:27], v[26:27], v[162:163] op_sel_hi:[1,0]
	v_pk_mul_f32 v[24:25], v[24:25], v[162:163] op_sel_hi:[1,0]
	v_cvt_pk_bf16_f32 v20, v20, v21
	v_lshl_add_u64 v[40:41], s[38:39], 0, v[40:41]
	v_pk_mul_f32 v[18:19], v[18:19], v[162:163] op_sel_hi:[1,0]
	v_cvt_pk_bf16_f32 v29, v30, v31
	v_cvt_pk_bf16_f32 v24, v24, v25
	v_cvt_pk_bf16_f32 v25, v26, v27
	v_cvt_pk_bf16_f32 v21, v22, v23
	v_cvt_pk_bf16_f32 v22, v16, v17
	v_cndmask_b32_e64 v16, v28, v20, s[2:3]
	v_mov_b32_e32 v26, 0
	v_cndmask_b32_e64 v33, v43, v45, s[2:3]
	v_cndmask_b32_e64 v32, v42, v44, s[2:3]
	v_lshl_add_u64 v[40:41], v[40:41], 0, v[112:113]
	v_cvt_pk_bf16_f32 v23, v18, v19
	v_mov_b32_dpp v26, v16 row_ror:8 row_mask:0xf bank_mask:0xf
	v_cndmask_b32_e64 v16, v29, v21, s[2:3]
	v_mov_b32_e32 v27, 0
	v_cndmask_b32_e64 v17, v24, v22, s[2:3]
	v_mov_b32_e32 v30, 0
	global_store_dwordx4 v[40:41], v[32:35], off
	v_mov_b32_dpp v27, v16 row_ror:8 row_mask:0xf bank_mask:0xf
	v_cndmask_b32_e64 v16, v25, v23, s[2:3]
	v_add_u32_e32 v34, 0x98, v146
	v_mov_b32_dpp v30, v17 row_ror:8 row_mask:0xf bank_mask:0xf
	v_mov_b32_e32 v31, 0
	v_cndmask_b32_e64 v18, v30, v24, s[2:3]
	v_cndmask_b32_e64 v24, v34, v148, s[2:3]
	v_mov_b32_dpp v31, v16 row_ror:8 row_mask:0xf bank_mask:0xf
	v_cndmask_b32_e64 v19, v31, v25, s[2:3]
	v_ashrrev_i32_e32 v25, 31, v24
	v_lshlrev_b64 v[24:25], 10, v[24:25]
	v_lshl_add_u64 v[24:25], s[38:39], 0, v[24:25]
	v_cndmask_b32_e64 v17, v27, v29, s[2:3]
	v_cndmask_b32_e64 v16, v26, v28, s[2:3]
	v_lshl_add_u64 v[24:25], v[24:25], 0, v[112:113]
	global_store_dwordx4 v[24:25], v[16:19], off
	v_pk_mul_f32 v[4:5], v[4:5], v[160:161] op_sel_hi:[1,0]
	v_pk_mul_f32 v[12:13], v[12:13], v[160:161] op_sel_hi:[1,0]
	v_add_u32_e32 v18, 0xa8, v146
	v_cndmask_b32_e64 v16, v148, v18, s[2:3]
	v_ashrrev_i32_e32 v17, 31, v16
	v_pk_mul_f32 v[10:11], v[10:11], v[160:161] op_sel_hi:[1,0]
	v_pk_mul_f32 v[8:9], v[8:9], v[160:161] op_sel_hi:[1,0]
	v_lshlrev_b64 v[16:17], 10, v[16:17]
	v_pk_mul_f32 v[0:1], v[0:1], v[160:161] op_sel_hi:[1,0]
	v_pk_mul_f32 v[6:7], v[6:7], v[160:161] op_sel_hi:[1,0]
	v_pk_mul_f32 v[14:15], v[14:15], v[160:161] op_sel_hi:[1,0]
	v_cvt_pk_bf16_f32 v12, v12, v13
	v_cvt_pk_bf16_f32 v8, v8, v9
	v_cvt_pk_bf16_f32 v9, v10, v11
	v_cvt_pk_bf16_f32 v10, v4, v5
	v_lshl_add_u64 v[16:17], s[38:39], 0, v[16:17]
	v_pk_mul_f32 v[2:3], v[2:3], v[160:161] op_sel_hi:[1,0]
	v_cvt_pk_bf16_f32 v13, v14, v15
	v_cvt_pk_bf16_f32 v6, v6, v7
	v_cvt_pk_bf16_f32 v7, v0, v1
	v_cndmask_b32_e64 v0, v12, v10, s[2:3]
	v_mov_b32_e32 v14, 0
	v_cndmask_b32_e64 v4, v18, v150, s[2:3]
	v_cndmask_b32_e64 v23, v23, v31, s[2:3]
	v_cndmask_b32_e64 v22, v22, v30, s[2:3]
	v_cndmask_b32_e64 v21, v21, v27, s[2:3]
	v_cndmask_b32_e64 v20, v20, v26, s[2:3]
	v_lshl_add_u64 v[16:17], v[16:17], 0, v[112:113]
	v_cvt_pk_bf16_f32 v11, v2, v3
	v_mov_b32_dpp v14, v0 row_ror:8 row_mask:0xf bank_mask:0xf
	v_cndmask_b32_e64 v0, v13, v6, s[2:3]
	v_mov_b32_e32 v15, 0
	v_ashrrev_i32_e32 v5, 31, v4
	global_store_dwordx4 v[16:17], v[20:23], off
	v_mov_b32_dpp v15, v0 row_ror:8 row_mask:0xf bank_mask:0xf
	v_cndmask_b32_e64 v0, v9, v11, s[2:3]
	v_cndmask_b32_e64 v1, v8, v7, s[2:3]
	v_mov_b32_e32 v16, 0
	v_mov_b32_e32 v17, 0
	v_lshlrev_b64 v[4:5], 10, v[4:5]
	v_mov_b32_dpp v16, v1 row_ror:8 row_mask:0xf bank_mask:0xf
	v_mov_b32_dpp v17, v0 row_ror:8 row_mask:0xf bank_mask:0xf
	v_lshl_add_u64 v[4:5], s[38:39], 0, v[4:5]
	v_cndmask_b32_e64 v3, v17, v9, s[2:3]
	v_cndmask_b32_e64 v2, v16, v8, s[2:3]
	v_cndmask_b32_e64 v1, v15, v13, s[2:3]
	v_cndmask_b32_e64 v0, v14, v12, s[2:3]
	v_lshl_add_u64 v[4:5], v[4:5], 0, v[112:113]
	global_store_dwordx4 v[4:5], v[0:3], off
	v_cndmask_b32_e64 v48, v154, v50, s[2:3]
	v_cndmask_b32_e64 v32, v152, v34, s[2:3]
	v_add_u32_e32 v0, 0xb8, v146
	v_cndmask_b32_e64 v0, v150, v0, s[2:3]
	v_ashrrev_i32_e32 v49, 31, v48
	v_ashrrev_i32_e32 v33, 31, v32
	v_ashrrev_i32_e32 v1, 31, v0
	v_lshlrev_b64 v[48:49], 10, v[48:49]
	v_lshlrev_b64 v[32:33], 10, v[32:33]
	v_lshlrev_b64 v[0:1], 10, v[0:1]
	v_lshl_add_u64 v[48:49], s[38:39], 0, v[48:49]
	v_lshl_add_u64 v[32:33], s[38:39], 0, v[32:33]
	v_lshl_add_u64 v[0:1], s[38:39], 0, v[0:1]
	v_cndmask_b32_e64 v55, v55, v63, s[2:3]
	v_cndmask_b32_e64 v54, v54, v62, s[2:3]
	v_cndmask_b32_e64 v53, v53, v59, s[2:3]
	v_cndmask_b32_e64 v52, v52, v58, s[2:3]
	v_lshl_add_u64 v[48:49], v[48:49], 0, v[112:113]
	v_cndmask_b32_e64 v39, v39, v47, s[2:3]
	v_cndmask_b32_e64 v38, v38, v46, s[2:3]
	v_cndmask_b32_e64 v37, v37, v43, s[2:3]
	v_cndmask_b32_e64 v36, v36, v42, s[2:3]
	v_lshl_add_u64 v[32:33], v[32:33], 0, v[112:113]
	v_lshl_add_u64 v[4:5], v[0:1], 0, v[112:113]
	v_cndmask_b32_e64 v3, v11, v17, s[2:3]
	v_cndmask_b32_e64 v2, v7, v16, s[2:3]
	v_cndmask_b32_e64 v1, v6, v15, s[2:3]
	v_cndmask_b32_e64 v0, v10, v14, s[2:3]
	s_and_b64 vcc, exec, s[4:5]
	s_mov_b32 s66, s36
	s_mov_b32 s6, s44
	s_mov_b64 s[50:51], s[48:49]
	s_mov_b64 s[52:53], s[46:47]
	global_store_dwordx4 v[48:49], v[52:55], off
	global_store_dwordx4 v[32:33], v[36:39], off
	global_store_dwordx4 v[4:5], v[0:3], off
	s_cbranch_vccz .LBB0_897
	s_waitcnt vmcnt(0)
	s_cmpk_gt_u32 s11, 0xff
	s_cbranch_scc1 .LBB0_908
	s_barrier

.LBB0_997:
	ds_read_b128 v[128:131], v164
	ds_read_b128 v[132:135], v164 offset:1024
	ds_read_b128 v[152:155], v164 offset:2048
	ds_read_b128 v[156:159], v164 offset:3072
	s_add_u32 s28, s48, 0xfffe0080
	s_addc_u32 s29, s49, -1
	s_cmp_eq_u32 s79, 4
	s_cselect_b32 s53, s9, s29
	s_cselect_b32 s52, s41, s28
	s_cselect_b32 s51, s39, s78
	s_cselect_b32 s50, s76, s77
	v_lshl_add_u64 v[204:205], s[48:49], 0, v[144:145]
	s_add_i32 m0, s55, 0xc000
	ds_read_b128 v[168:171], v165
	ds_read_b128 v[172:175], v165 offset:1024
	ds_read_b128 v[176:179], v165 offset:2048
	ds_read_b128 v[180:183], v165 offset:3072
	ds_read_b128 v[184:187], v165 offset:4096
	ds_read_b128 v[188:191], v165 offset:5120
	ds_read_b128 v[196:199], v165 offset:6144
	ds_read_b128 v[200:203], v165 offset:7168
	global_load_lds_dwordx4 v[204:205], off
	v_lshl_add_u64 v[204:205], s[48:49], 0, v[146:147]
	s_add_i32 m0, s55, 0xe000
	s_nop 0
	global_load_lds_dwordx4 v[204:205], off
	s_waitcnt lgkmcnt(8)
	s_barrier
	s_waitcnt lgkmcnt(0)
	v_mfma_f32_16x16x32_bf16 v[124:127], v[128:131], v[168:171], v[124:127]
	v_mfma_f32_16x16x32_bf16 v[120:123], v[152:155], v[168:171], v[120:123]
	v_mfma_f32_16x16x32_bf16 v[108:111], v[128:131], v[176:179], v[108:111]
	v_mfma_f32_16x16x32_bf16 v[104:107], v[152:155], v[176:179], v[104:107]
	v_mfma_f32_16x16x32_bf16 v[92:95], v[128:131], v[184:187], v[92:95]
	v_mfma_f32_16x16x32_bf16 v[88:91], v[152:155], v[184:187], v[88:91]
	v_mfma_f32_16x16x32_bf16 v[76:79], v[128:131], v[196:199], v[76:79]
	v_mfma_f32_16x16x32_bf16 v[72:75], v[152:155], v[196:199], v[72:75]
	v_mfma_f32_16x16x32_bf16 v[124:127], v[132:135], v[172:175], v[124:127]
	v_mfma_f32_16x16x32_bf16 v[120:123], v[156:159], v[172:175], v[120:123]
	v_mfma_f32_16x16x32_bf16 v[108:111], v[132:135], v[180:183], v[108:111]
	v_mfma_f32_16x16x32_bf16 v[104:107], v[156:159], v[180:183], v[104:107]
	v_mfma_f32_16x16x32_bf16 v[92:95], v[132:135], v[188:191], v[92:95]
	v_mfma_f32_16x16x32_bf16 v[88:91], v[156:159], v[188:191], v[88:91]
	v_mfma_f32_16x16x32_bf16 v[76:79], v[132:135], v[200:203], v[76:79]
	v_mfma_f32_16x16x32_bf16 v[72:75], v[156:159], v[200:203], v[72:75]
	s_barrier
	s_add_i32 s28, s65, s54
	v_lshl_add_u64 v[220:221], s[50:51], 0, v[138:139]
	s_mov_b32 m0, s28
	ds_read_b128 v[204:207], v166
	ds_read_b128 v[208:211], v166 offset:1024
	ds_read_b128 v[212:215], v166 offset:2048
	ds_read_b128 v[216:219], v166 offset:3072
	global_load_lds_dwordx4 v[220:221], off
	v_lshl_add_u64 v[222:223], s[50:51], 0, v[142:143]
	s_add_i32 m0, s28, 0x2000
	s_nop 0
	global_load_lds_dwordx4 v[222:223], off
	s_barrier
	s_waitcnt lgkmcnt(0)
	v_mfma_f32_16x16x32_bf16 v[116:119], v[204:207], v[168:171], v[116:119]
	v_mfma_f32_16x16x32_bf16 v[112:115], v[212:215], v[168:171], v[112:115]
	v_mfma_f32_16x16x32_bf16 v[100:103], v[204:207], v[176:179], v[100:103]
	v_mfma_f32_16x16x32_bf16 v[96:99], v[212:215], v[176:179], v[96:99]
	v_mfma_f32_16x16x32_bf16 v[84:87], v[204:207], v[184:187], v[84:87]
	v_mfma_f32_16x16x32_bf16 v[80:83], v[212:215], v[184:187], v[80:83]
	v_mfma_f32_16x16x32_bf16 v[68:71], v[204:207], v[196:199], v[68:71]
	v_mfma_f32_16x16x32_bf16 v[64:67], v[212:215], v[196:199], v[64:67]
	v_mfma_f32_16x16x32_bf16 v[116:119], v[208:211], v[172:175], v[116:119]
	v_mfma_f32_16x16x32_bf16 v[112:115], v[216:219], v[172:175], v[112:115]
	v_mfma_f32_16x16x32_bf16 v[100:103], v[208:211], v[180:183], v[100:103]
	v_mfma_f32_16x16x32_bf16 v[96:99], v[216:219], v[180:183], v[96:99]
	v_mfma_f32_16x16x32_bf16 v[84:87], v[208:211], v[188:191], v[84:87]
	v_mfma_f32_16x16x32_bf16 v[80:83], v[216:219], v[188:191], v[80:83]
	v_mfma_f32_16x16x32_bf16 v[68:71], v[208:211], v[200:203], v[68:71]
	v_mfma_f32_16x16x32_bf16 v[64:67], v[216:219], v[200:203], v[64:67]
	s_mov_b32 m0, s55
	v_lshl_add_u64 v[224:225], s[52:53], 0, v[136:137]
	s_barrier
	ds_read_b128 v[168:171], v165 offset:16384
	ds_read_b128 v[172:175], v165 offset:17408
	ds_read_b128 v[176:179], v165 offset:18432
	ds_read_b128 v[180:183], v165 offset:19456
	ds_read_b128 v[184:187], v165 offset:20480
	ds_read_b128 v[188:191], v165 offset:21504
	ds_read_b128 v[196:199], v165 offset:22528
	ds_read_b128 v[200:203], v165 offset:23552
	global_load_lds_dwordx4 v[224:225], off
	v_lshl_add_u64 v[226:227], s[52:53], 0, v[140:141]
	s_mov_b32 m0, s56
	s_nop 0
	global_load_lds_dwordx4 v[226:227], off
	s_barrier
	s_waitcnt lgkmcnt(0)
	v_mfma_f32_16x16x32_bf16 v[60:63], v[128:131], v[168:171], v[60:63]
	v_mfma_f32_16x16x32_bf16 v[56:59], v[152:155], v[168:171], v[56:59]
	v_mfma_f32_16x16x32_bf16 v[44:47], v[128:131], v[176:179], v[44:47]
	v_mfma_f32_16x16x32_bf16 v[40:43], v[152:155], v[176:179], v[40:43]
	v_mfma_f32_16x16x32_bf16 v[28:31], v[128:131], v[184:187], v[28:31]
	v_mfma_f32_16x16x32_bf16 v[24:27], v[152:155], v[184:187], v[24:27]
	v_mfma_f32_16x16x32_bf16 v[12:15], v[128:131], v[196:199], v[12:15]
	v_mfma_f32_16x16x32_bf16 v[8:11], v[152:155], v[196:199], v[8:11]
	v_mfma_f32_16x16x32_bf16 v[60:63], v[132:135], v[172:175], v[60:63]
	v_mfma_f32_16x16x32_bf16 v[56:59], v[156:159], v[172:175], v[56:59]
	v_mfma_f32_16x16x32_bf16 v[44:47], v[132:135], v[180:183], v[44:47]
	v_mfma_f32_16x16x32_bf16 v[40:43], v[156:159], v[180:183], v[40:43]
	v_mfma_f32_16x16x32_bf16 v[28:31], v[132:135], v[188:191], v[28:31]
	v_mfma_f32_16x16x32_bf16 v[24:27], v[156:159], v[188:191], v[24:27]
	v_mfma_f32_16x16x32_bf16 v[12:15], v[132:135], v[200:203], v[12:15]
	v_mfma_f32_16x16x32_bf16 v[8:11], v[156:159], v[200:203], v[8:11]
	s_barrier
	s_add_u32 s80, s50, 0x8000
	s_addc_u32 s81, s51, 0
	s_add_i32 s28, s66, s54
	v_lshl_add_u64 v[128:129], s[80:81], 0, v[138:139]
	s_mov_b32 m0, s28
	s_nop 0
	global_load_lds_dwordx4 v[128:129], off
	v_lshl_add_u64 v[128:129], s[80:81], 0, v[142:143]
	s_add_i32 m0, s28, 0x2000
	s_nop 0
	global_load_lds_dwordx4 v[128:129], off
	s_waitcnt vmcnt(6)
	s_barrier
	v_mfma_f32_16x16x32_bf16 v[52:55], v[204:207], v[168:171], v[52:55]
	v_mfma_f32_16x16x32_bf16 v[48:51], v[212:215], v[168:171], v[48:51]
	v_mfma_f32_16x16x32_bf16 v[36:39], v[204:207], v[176:179], v[36:39]
	v_mfma_f32_16x16x32_bf16 v[32:35], v[212:215], v[176:179], v[32:35]
	v_mfma_f32_16x16x32_bf16 v[20:23], v[204:207], v[184:187], v[20:23]
	v_mfma_f32_16x16x32_bf16 v[16:19], v[212:215], v[184:187], v[16:19]
	v_mfma_f32_16x16x32_bf16 v[4:7], v[204:207], v[196:199], v[4:7]
	v_mfma_f32_16x16x32_bf16 v[0:3], v[212:215], v[196:199], v[0:3]
	v_mfma_f32_16x16x32_bf16 v[52:55], v[208:211], v[172:175], v[52:55]
	v_mfma_f32_16x16x32_bf16 v[48:51], v[216:219], v[172:175], v[48:51]
	v_mfma_f32_16x16x32_bf16 v[36:39], v[208:211], v[180:183], v[36:39]
	v_mfma_f32_16x16x32_bf16 v[32:35], v[216:219], v[180:183], v[32:35]
	v_mfma_f32_16x16x32_bf16 v[20:23], v[208:211], v[188:191], v[20:23]
	v_mfma_f32_16x16x32_bf16 v[16:19], v[216:219], v[188:191], v[16:19]
	v_mfma_f32_16x16x32_bf16 v[4:7], v[208:211], v[200:203], v[4:7]
	v_mfma_f32_16x16x32_bf16 v[0:3], v[216:219], v[200:203], v[0:3]
	s_add_i32 s28, 0, 0x18000
	v_add_u32_e32 v156, s28, v161
	s_barrier
	ds_read_b128 v[128:131], v156
	ds_read_b128 v[132:135], v156 offset:1024
	ds_read_b128 v[152:155], v156 offset:2048
	ds_read_b128 v[156:159], v156 offset:3072
	s_add_u32 s52, s52, 0x20000
	s_addc_u32 s53, s53, 0
	s_mov_b32 m0, s57
	v_lshl_add_u64 v[204:205], s[52:53], 0, v[136:137]
	ds_read_b128 v[168:171], v165 offset:32768
	ds_read_b128 v[172:175], v165 offset:33792
	ds_read_b128 v[176:179], v165 offset:34816
	ds_read_b128 v[180:183], v165 offset:35840
	ds_read_b128 v[184:187], v165 offset:36864
	ds_read_b128 v[188:191], v165 offset:37888
	ds_read_b128 v[196:199], v165 offset:38912
	ds_read_b128 v[200:203], v165 offset:39936
	global_load_lds_dwordx4 v[204:205], off
	v_lshl_add_u64 v[204:205], s[52:53], 0, v[140:141]
	s_mov_b32 m0, s58
	s_nop 0
	global_load_lds_dwordx4 v[204:205], off
	s_waitcnt lgkmcnt(8)
	s_barrier
	s_waitcnt lgkmcnt(0)
	v_mfma_f32_16x16x32_bf16 v[124:127], v[128:131], v[168:171], v[124:127]
	v_mfma_f32_16x16x32_bf16 v[120:123], v[152:155], v[168:171], v[120:123]
	v_mfma_f32_16x16x32_bf16 v[108:111], v[128:131], v[176:179], v[108:111]
	v_mfma_f32_16x16x32_bf16 v[104:107], v[152:155], v[176:179], v[104:107]
	v_mfma_f32_16x16x32_bf16 v[92:95], v[128:131], v[184:187], v[92:95]
	v_mfma_f32_16x16x32_bf16 v[88:91], v[152:155], v[184:187], v[88:91]
	v_mfma_f32_16x16x32_bf16 v[76:79], v[128:131], v[196:199], v[76:79]
	v_mfma_f32_16x16x32_bf16 v[72:75], v[152:155], v[196:199], v[72:75]
	v_mfma_f32_16x16x32_bf16 v[124:127], v[132:135], v[172:175], v[124:127]
	v_mfma_f32_16x16x32_bf16 v[120:123], v[156:159], v[172:175], v[120:123]
	v_mfma_f32_16x16x32_bf16 v[108:111], v[132:135], v[180:183], v[108:111]
	v_mfma_f32_16x16x32_bf16 v[104:107], v[156:159], v[180:183], v[104:107]
	v_mfma_f32_16x16x32_bf16 v[92:95], v[132:135], v[188:191], v[92:95]
	v_mfma_f32_16x16x32_bf16 v[88:91], v[156:159], v[188:191], v[88:91]
	v_mfma_f32_16x16x32_bf16 v[76:79], v[132:135], v[200:203], v[76:79]
	v_mfma_f32_16x16x32_bf16 v[72:75], v[156:159], v[200:203], v[72:75]
	s_barrier
	s_add_i32 s29, 0, 0x1c000
	s_add_i32 s28, s28, s54
	v_add_u32_e32 v195, s29, v161
	v_lshl_add_u64 v[220:221], v[220:221], 0, s[36:37]
	s_mov_b32 m0, s28
	ds_read_b128 v[204:207], v195
	ds_read_b128 v[208:211], v195 offset:1024
	ds_read_b128 v[212:215], v195 offset:2048
	ds_read_b128 v[216:219], v195 offset:3072
	global_load_lds_dwordx4 v[220:221], off
	v_lshl_add_u64 v[220:221], v[222:223], 0, s[36:37]
	s_add_i32 m0, s28, 0x2000
	s_nop 0
	global_load_lds_dwordx4 v[220:221], off
	s_barrier
	s_waitcnt lgkmcnt(0)
	v_mfma_f32_16x16x32_bf16 v[116:119], v[204:207], v[168:171], v[116:119]
	v_mfma_f32_16x16x32_bf16 v[112:115], v[212:215], v[168:171], v[112:115]
	v_mfma_f32_16x16x32_bf16 v[100:103], v[204:207], v[176:179], v[100:103]
	v_mfma_f32_16x16x32_bf16 v[96:99], v[212:215], v[176:179], v[96:99]
	v_mfma_f32_16x16x32_bf16 v[84:87], v[204:207], v[184:187], v[84:87]
	v_mfma_f32_16x16x32_bf16 v[80:83], v[212:215], v[184:187], v[80:83]
	v_mfma_f32_16x16x32_bf16 v[68:71], v[204:207], v[196:199], v[68:71]
	v_mfma_f32_16x16x32_bf16 v[64:67], v[212:215], v[196:199], v[64:67]
	v_mfma_f32_16x16x32_bf16 v[116:119], v[208:211], v[172:175], v[116:119]
	v_mfma_f32_16x16x32_bf16 v[112:115], v[216:219], v[172:175], v[112:115]
	v_mfma_f32_16x16x32_bf16 v[100:103], v[208:211], v[180:183], v[100:103]
	v_mfma_f32_16x16x32_bf16 v[96:99], v[216:219], v[180:183], v[96:99]
	v_mfma_f32_16x16x32_bf16 v[84:87], v[208:211], v[188:191], v[84:87]
	v_mfma_f32_16x16x32_bf16 v[80:83], v[216:219], v[188:191], v[80:83]
	v_mfma_f32_16x16x32_bf16 v[68:71], v[208:211], v[200:203], v[68:71]
	v_mfma_f32_16x16x32_bf16 v[64:67], v[216:219], v[200:203], v[64:67]
	s_mov_b32 m0, s62
	v_lshl_add_u64 v[220:221], v[224:225], 0, s[36:37]
	s_barrier
	ds_read_b128 v[168:171], v165 offset:49152
	ds_read_b128 v[172:175], v165 offset:50176
	ds_read_b128 v[176:179], v165 offset:51200
	ds_read_b128 v[180:183], v165 offset:52224
	ds_read_b128 v[184:187], v165 offset:53248
	ds_read_b128 v[188:191], v165 offset:54272
	ds_read_b128 v[196:199], v165 offset:55296
	ds_read_b128 v[200:203], v165 offset:56320
	global_load_lds_dwordx4 v[220:221], off
	v_lshl_add_u64 v[220:221], v[226:227], 0, s[36:37]
	s_mov_b32 m0, s63
	s_nop 0
	global_load_lds_dwordx4 v[220:221], off
	s_barrier
	s_waitcnt lgkmcnt(0)
	v_mfma_f32_16x16x32_bf16 v[60:63], v[128:131], v[168:171], v[60:63]
	v_mfma_f32_16x16x32_bf16 v[56:59], v[152:155], v[168:171], v[56:59]
	v_mfma_f32_16x16x32_bf16 v[44:47], v[128:131], v[176:179], v[44:47]
	v_mfma_f32_16x16x32_bf16 v[40:43], v[152:155], v[176:179], v[40:43]
	v_mfma_f32_16x16x32_bf16 v[28:31], v[128:131], v[184:187], v[28:31]
	v_mfma_f32_16x16x32_bf16 v[24:27], v[152:155], v[184:187], v[24:27]
	v_mfma_f32_16x16x32_bf16 v[12:15], v[128:131], v[196:199], v[12:15]
	v_mfma_f32_16x16x32_bf16 v[8:11], v[152:155], v[196:199], v[8:11]
	v_mfma_f32_16x16x32_bf16 v[60:63], v[132:135], v[172:175], v[60:63]
	v_mfma_f32_16x16x32_bf16 v[56:59], v[156:159], v[172:175], v[56:59]
	v_mfma_f32_16x16x32_bf16 v[44:47], v[132:135], v[180:183], v[44:47]
	v_mfma_f32_16x16x32_bf16 v[40:43], v[156:159], v[180:183], v[40:43]
	v_mfma_f32_16x16x32_bf16 v[28:31], v[132:135], v[188:191], v[28:31]
	v_mfma_f32_16x16x32_bf16 v[24:27], v[156:159], v[188:191], v[24:27]
	v_mfma_f32_16x16x32_bf16 v[12:15], v[132:135], v[200:203], v[12:15]
	v_mfma_f32_16x16x32_bf16 v[8:11], v[156:159], v[200:203], v[8:11]
	s_barrier
	s_add_u32 s50, s50, 0x8080
	s_addc_u32 s51, s51, 0
	s_add_i32 s28, s29, s54
	v_lshl_add_u64 v[128:129], s[50:51], 0, v[138:139]
	s_mov_b32 m0, s28
	s_nop 0
	global_load_lds_dwordx4 v[128:129], off
	v_lshl_add_u64 v[128:129], s[50:51], 0, v[142:143]
	s_add_i32 m0, s28, 0x2000
	s_nop 0
	global_load_lds_dwordx4 v[128:129], off
	s_waitcnt vmcnt(6)
	s_barrier
	v_mfma_f32_16x16x32_bf16 v[52:55], v[204:207], v[168:171], v[52:55]
	v_mfma_f32_16x16x32_bf16 v[48:51], v[212:215], v[168:171], v[48:51]
	v_mfma_f32_16x16x32_bf16 v[36:39], v[204:207], v[176:179], v[36:39]
	v_mfma_f32_16x16x32_bf16 v[32:35], v[212:215], v[176:179], v[32:35]
	v_mfma_f32_16x16x32_bf16 v[20:23], v[204:207], v[184:187], v[20:23]
	v_mfma_f32_16x16x32_bf16 v[16:19], v[212:215], v[184:187], v[16:19]
	v_mfma_f32_16x16x32_bf16 v[4:7], v[204:207], v[196:199], v[4:7]
	v_mfma_f32_16x16x32_bf16 v[0:3], v[212:215], v[196:199], v[0:3]
	v_mfma_f32_16x16x32_bf16 v[52:55], v[208:211], v[172:175], v[52:55]
	v_mfma_f32_16x16x32_bf16 v[48:51], v[216:219], v[172:175], v[48:51]
	v_mfma_f32_16x16x32_bf16 v[36:39], v[208:211], v[180:183], v[36:39]
	v_mfma_f32_16x16x32_bf16 v[32:35], v[216:219], v[180:183], v[32:35]
	v_mfma_f32_16x16x32_bf16 v[20:23], v[208:211], v[188:191], v[20:23]
	v_mfma_f32_16x16x32_bf16 v[16:19], v[216:219], v[188:191], v[16:19]
	v_mfma_f32_16x16x32_bf16 v[4:7], v[208:211], v[200:203], v[4:7]
	v_mfma_f32_16x16x32_bf16 v[0:3], v[216:219], v[200:203], v[0:3]
	s_add_i32 s79, s79, 2
	s_add_u32 s48, s48, 0x100
	s_addc_u32 s49, s49, 0
	s_add_u32 s77, s77, 0x100
	s_addc_u32 s78, s78, 0
	s_cmp_gt_u32 s79, 5
	s_barrier
	s_cbranch_scc0 .LBB0_997
	v_lshl_add_u32 v152, s8, 8, v160
	v_lshl_or_b32 v156, s10, 8, v162
	v_ashrrev_i32_e32 v153, 31, v152
	v_lshlrev_b64 v[128:129], 11, v[152:153]
	v_ashrrev_i32_e32 v157, 31, v156
	v_lshl_add_u64 v[128:129], s[42:43], 0, v[128:129]
	v_lshlrev_b64 v[130:131], 1, v[156:157]
	v_or_b32_e32 v158, 16, v152
	v_lshl_add_u64 v[128:129], v[128:129], 0, v[130:131]
	v_ashrrev_i32_e32 v159, 31, v158
	global_load_dwordx4 v[168:171], v[128:129], off
	global_load_dwordx4 v[172:175], v[128:129], off offset:64
	v_lshlrev_b64 v[128:129], 11, v[158:159]
	v_lshl_add_u64 v[128:129], s[42:43], 0, v[128:129]
	v_lshl_add_u64 v[128:129], v[128:129], 0, v[130:131]
	global_load_dwordx4 v[132:135], v[128:129], off
	s_nop 0
	global_load_dwordx4 v[128:131], v[128:129], off offset:64
	v_cndmask_b32_e64 v155, 0, 1, s[12:13]
	v_or_b32_e32 v154, v156, v163
	v_cmp_ne_u32_e64 s[8:9], 1, v155
	v_ashrrev_i32_e32 v155, 31, v154
	s_andn2_b64 vcc, exec, s[12:13]
	v_lshlrev_b64 v[154:155], 1, v[154:155]
	s_waitcnt vmcnt(0)
	v_lshlrev_b32_e32 v176, 16, v168
	v_and_b32_e32 v177, 0xffff0000, v168
	v_lshlrev_b32_e32 v168, 16, v169
	v_and_b32_e32 v169, 0xffff0000, v169
	v_lshlrev_b32_e32 v178, 16, v170
	v_and_b32_e32 v179, 0xffff0000, v170
	v_lshlrev_b32_e32 v170, 16, v171
	v_and_b32_e32 v171, 0xffff0000, v171
	v_lshlrev_b32_e32 v180, 16, v172
	v_and_b32_e32 v181, 0xffff0000, v172
	v_lshlrev_b32_e32 v172, 16, v173
	v_and_b32_e32 v173, 0xffff0000, v173
	v_lshlrev_b32_e32 v182, 16, v174
	v_and_b32_e32 v183, 0xffff0000, v174
	v_lshlrev_b32_e32 v174, 16, v175
	v_and_b32_e32 v175, 0xffff0000, v175
	v_pk_add_f32 v[126:127], v[126:127], v[168:169]
	v_pk_add_f32 v[124:125], v[124:125], v[176:177]
	v_pk_add_f32 v[122:123], v[122:123], v[170:171]
	v_pk_add_f32 v[120:121], v[120:121], v[178:179]
	v_pk_add_f32 v[118:119], v[118:119], v[172:173]
	v_pk_add_f32 v[116:117], v[116:117], v[180:181]
	v_pk_add_f32 v[114:115], v[114:115], v[174:175]
	v_pk_add_f32 v[112:113], v[112:113], v[182:183]
	v_add_u32_e32 v169, 8, v152
	s_cbranch_vccnz .LBB0_1000
	v_cvt_pk_bf16_f32 v168, v124, v125
	v_cvt_pk_bf16_f32 v174, v116, v117
	v_cvt_pk_bf16_f32 v170, v126, v127
	v_cvt_pk_bf16_f32 v171, v120, v121
	v_cvt_pk_bf16_f32 v175, v118, v119
	v_cvt_pk_bf16_f32 v176, v112, v113
	v_cndmask_b32_e64 v173, v168, v174, s[4:5]
	v_mov_b32_e32 v178, 0
	v_cvt_pk_bf16_f32 v172, v122, v123
	v_cvt_pk_bf16_f32 v177, v114, v115
	v_mov_b32_dpp v178, v173 row_ror:8 row_mask:0xf bank_mask:0xf
	v_cndmask_b32_e64 v173, v170, v175, s[4:5]
	v_mov_b32_e32 v179, 0
	v_cndmask_b32_e64 v180, v171, v176, s[4:5]
	v_mov_b32_e32 v181, 0
	v_mov_b32_dpp v179, v173 row_ror:8 row_mask:0xf bank_mask:0xf
	v_cndmask_b32_e64 v173, v172, v177, s[4:5]
	v_mov_b32_dpp v181, v180 row_ror:8 row_mask:0xf bank_mask:0xf
	v_mov_b32_e32 v180, 0
	v_cndmask_b32_e64 v174, v174, v178, s[4:5]
	v_cndmask_b32_e64 v175, v175, v179, s[4:5]
	v_mov_b32_dpp v180, v173 row_ror:8 row_mask:0xf bank_mask:0xf
	v_cndmask_b32_e64 v173, v180, v172, s[4:5]
	v_cndmask_b32_e64 v172, v181, v171, s[4:5]
	v_cndmask_b32_e64 v171, v179, v170, s[4:5]
	v_cndmask_b32_e64 v170, v178, v168, s[4:5]
	v_add_u32_e32 v168, -8, v152
	v_cndmask_b32_e64 v178, v168, v152, s[4:5]
	v_ashrrev_i32_e32 v179, 31, v178
	v_lshlrev_b64 v[178:179], 11, v[178:179]
	v_lshl_add_u64 v[178:179], s[68:69], 0, v[178:179]
	v_lshl_add_u64 v[178:179], v[178:179], 0, v[154:155]
	global_store_dwordx4 v[178:179], v[170:173], off
	v_cndmask_b32_e64 v177, v177, v180, s[4:5]
	v_cndmask_b32_e64 v176, v176, v181, s[4:5]
	v_cndmask_b32_e64 v170, v152, v169, s[4:5]
	v_ashrrev_i32_e32 v171, 31, v170
	v_lshlrev_b64 v[170:171], 11, v[170:171]
	v_lshl_add_u64 v[170:171], s[68:69], 0, v[170:171]
	v_lshl_add_u64 v[170:171], v[170:171], 0, v[154:155]
	global_store_dwordx4 v[170:171], v[174:177], off

.LBB0_1093:
	ds_read_b128 v[146:149], v167
	ds_read_b128 v[150:153], v167 offset:1024
	ds_read_b128 v[178:181], v167 offset:2048
	ds_read_b128 v[182:185], v167 offset:3072
	s_add_u32 s28, s0, 0xfffc0080
	s_addc_u32 s29, s1, -1
	s_cmp_eq_u32 s64, 12
	s_cselect_b32 s45, s37, s29
	s_cselect_b32 s44, s60, s28
	s_cselect_b32 s43, s13, s63
	s_cselect_b32 s42, s61, s62
	v_lshl_add_u64 v[156:157], s[0:1], 0, v[138:139]
	s_add_i32 m0, s47, 0xc000
	ds_read_b128 v[186:189], v171
	ds_read_b128 v[196:199], v171 offset:1024
	ds_read_b128 v[200:203], v171 offset:2048
	ds_read_b128 v[204:207], v171 offset:3072
	ds_read_b128 v[208:211], v171 offset:4096
	ds_read_b128 v[212:215], v171 offset:5120
	ds_read_b128 v[216:219], v171 offset:6144
	ds_read_b128 v[220:223], v171 offset:7168
	global_load_lds_dwordx4 v[156:157], off
	v_lshl_add_u64 v[156:157], s[0:1], 0, v[140:141]
	s_add_i32 m0, s47, 0xe000
	s_nop 0
	global_load_lds_dwordx4 v[156:157], off
	s_waitcnt lgkmcnt(8)
	s_barrier
	s_waitcnt lgkmcnt(0)
	s_cmp_eq_u32 s64, -2
	s_cbranch_scc1 .Lz10_0_first
	v_mfma_f32_16x16x32_bf16 v[124:127], v[146:149], v[186:189], v[124:127]
	v_mfma_f32_16x16x32_bf16 v[120:123], v[178:181], v[186:189], v[120:123]
	v_mfma_f32_16x16x32_bf16 v[108:111], v[146:149], v[200:203], v[108:111]
	v_mfma_f32_16x16x32_bf16 v[104:107], v[178:181], v[200:203], v[104:107]
	v_mfma_f32_16x16x32_bf16 v[92:95], v[146:149], v[208:211], v[92:95]
	v_mfma_f32_16x16x32_bf16 v[88:91], v[178:181], v[208:211], v[88:91]
	v_mfma_f32_16x16x32_bf16 v[76:79], v[146:149], v[216:219], v[76:79]
	v_mfma_f32_16x16x32_bf16 v[72:75], v[178:181], v[216:219], v[72:75]
	v_mfma_f32_16x16x32_bf16 v[124:127], v[150:153], v[196:199], v[124:127]
	v_mfma_f32_16x16x32_bf16 v[120:123], v[182:185], v[196:199], v[120:123]
	v_mfma_f32_16x16x32_bf16 v[108:111], v[150:153], v[204:207], v[108:111]
	v_mfma_f32_16x16x32_bf16 v[104:107], v[182:185], v[204:207], v[104:107]
	v_mfma_f32_16x16x32_bf16 v[92:95], v[150:153], v[212:215], v[92:95]
	v_mfma_f32_16x16x32_bf16 v[88:91], v[182:185], v[212:215], v[88:91]
	v_mfma_f32_16x16x32_bf16 v[76:79], v[150:153], v[220:223], v[76:79]
	v_mfma_f32_16x16x32_bf16 v[72:75], v[182:185], v[220:223], v[72:75]
.Lz10_0_join:
	s_barrier
	s_add_i32 s28, s56, s11
	v_lshl_add_u64 v[156:157], s[42:43], 0, v[132:133]
	s_mov_b32 m0, s28
	ds_read_b128 v[224:227], v175
	ds_read_b128 v[228:231], v175 offset:1024
	ds_read_b128 v[232:235], v175 offset:2048
	ds_read_b128 v[236:239], v175 offset:3072
	global_load_lds_dwordx4 v[156:157], off
	v_lshl_add_u64 v[160:161], s[42:43], 0, v[128:129]
	s_add_i32 m0, s28, 0x2000
	s_nop 0
	global_load_lds_dwordx4 v[160:161], off
	s_barrier
	s_waitcnt lgkmcnt(0)
	s_cmp_eq_u32 s64, -2
	s_cbranch_scc1 .Lz10_1_first
	v_mfma_f32_16x16x32_bf16 v[116:119], v[224:227], v[186:189], v[116:119]
	v_mfma_f32_16x16x32_bf16 v[112:115], v[232:235], v[186:189], v[112:115]
	v_mfma_f32_16x16x32_bf16 v[100:103], v[224:227], v[200:203], v[100:103]
	v_mfma_f32_16x16x32_bf16 v[96:99], v[232:235], v[200:203], v[96:99]
	v_mfma_f32_16x16x32_bf16 v[84:87], v[224:227], v[208:211], v[84:87]
	v_mfma_f32_16x16x32_bf16 v[80:83], v[232:235], v[208:211], v[80:83]
	v_mfma_f32_16x16x32_bf16 v[68:71], v[224:227], v[216:219], v[68:71]
	v_mfma_f32_16x16x32_bf16 v[64:67], v[232:235], v[216:219], v[64:67]
	v_mfma_f32_16x16x32_bf16 v[116:119], v[228:231], v[196:199], v[116:119]
	v_mfma_f32_16x16x32_bf16 v[112:115], v[236:239], v[196:199], v[112:115]
	v_mfma_f32_16x16x32_bf16 v[100:103], v[228:231], v[204:207], v[100:103]
	v_mfma_f32_16x16x32_bf16 v[96:99], v[236:239], v[204:207], v[96:99]
	v_mfma_f32_16x16x32_bf16 v[84:87], v[228:231], v[212:215], v[84:87]
	v_mfma_f32_16x16x32_bf16 v[80:83], v[236:239], v[212:215], v[80:83]
	v_mfma_f32_16x16x32_bf16 v[68:71], v[228:231], v[220:223], v[68:71]
	v_mfma_f32_16x16x32_bf16 v[64:67], v[236:239], v[220:223], v[64:67]
.Lz10_1_join:
	s_mov_b32 m0, s47
	v_lshl_add_u64 v[164:165], s[44:45], 0, v[134:135]
	s_barrier
	ds_read_b128 v[186:189], v171 offset:16384
	ds_read_b128 v[196:199], v171 offset:17408
	ds_read_b128 v[200:203], v171 offset:18432
	ds_read_b128 v[204:207], v171 offset:19456
	ds_read_b128 v[208:211], v171 offset:20480
	ds_read_b128 v[212:215], v171 offset:21504
	ds_read_b128 v[216:219], v171 offset:22528
	ds_read_b128 v[220:223], v171 offset:23552
	global_load_lds_dwordx4 v[164:165], off
	v_lshl_add_u64 v[168:169], s[44:45], 0, v[130:131]
	s_mov_b32 m0, s48
	s_nop 0
	global_load_lds_dwordx4 v[168:169], off
	s_barrier
	s_waitcnt lgkmcnt(0)
	s_cmp_eq_u32 s64, -2
	s_cbranch_scc1 .Lz10_2_first
	v_mfma_f32_16x16x32_bf16 v[60:63], v[146:149], v[186:189], v[60:63]
	v_mfma_f32_16x16x32_bf16 v[56:59], v[178:181], v[186:189], v[56:59]
	v_mfma_f32_16x16x32_bf16 v[44:47], v[146:149], v[200:203], v[44:47]
	v_mfma_f32_16x16x32_bf16 v[40:43], v[178:181], v[200:203], v[40:43]
	v_mfma_f32_16x16x32_bf16 v[28:31], v[146:149], v[208:211], v[28:31]
	v_mfma_f32_16x16x32_bf16 v[24:27], v[178:181], v[208:211], v[24:27]
	v_mfma_f32_16x16x32_bf16 v[12:15], v[146:149], v[216:219], v[12:15]
	v_mfma_f32_16x16x32_bf16 v[8:11], v[178:181], v[216:219], v[8:11]
	v_mfma_f32_16x16x32_bf16 v[60:63], v[150:153], v[196:199], v[60:63]
	v_mfma_f32_16x16x32_bf16 v[56:59], v[182:185], v[196:199], v[56:59]
	v_mfma_f32_16x16x32_bf16 v[44:47], v[150:153], v[204:207], v[44:47]
	v_mfma_f32_16x16x32_bf16 v[40:43], v[182:185], v[204:207], v[40:43]
	v_mfma_f32_16x16x32_bf16 v[28:31], v[150:153], v[212:215], v[28:31]
	v_mfma_f32_16x16x32_bf16 v[24:27], v[182:185], v[212:215], v[24:27]
	v_mfma_f32_16x16x32_bf16 v[12:15], v[150:153], v[220:223], v[12:15]
	v_mfma_f32_16x16x32_bf16 v[8:11], v[182:185], v[220:223], v[8:11]

.Lz10_3_join:
	s_add_i32 s28, 0, 0x18000
	v_add_u32_e32 v154, s28, v159
	s_barrier
	ds_read_b128 v[146:149], v154
	ds_read_b128 v[150:153], v154 offset:1024
	ds_read_b128 v[178:181], v154 offset:2048
	ds_read_b128 v[182:185], v154 offset:3072
	s_add_u32 s44, s44, 0x40000
	s_addc_u32 s45, s45, 0
	s_mov_b32 m0, s49
	v_lshl_add_u64 v[172:173], s[44:45], 0, v[134:135]
	ds_read_b128 v[186:189], v171 offset:32768
	ds_read_b128 v[196:199], v171 offset:33792
	ds_read_b128 v[200:203], v171 offset:34816
	ds_read_b128 v[204:207], v171 offset:35840
	ds_read_b128 v[208:211], v171 offset:36864
	ds_read_b128 v[212:215], v171 offset:37888
	ds_read_b128 v[216:219], v171 offset:38912
	ds_read_b128 v[220:223], v171 offset:39936
	global_load_lds_dwordx4 v[172:173], off
	v_lshl_add_u64 v[172:173], s[44:45], 0, v[130:131]
	s_mov_b32 m0, s50
	s_nop 0
	global_load_lds_dwordx4 v[172:173], off
	s_waitcnt lgkmcnt(8)
	s_barrier
	s_waitcnt lgkmcnt(0)
	v_mfma_f32_16x16x32_bf16 v[124:127], v[146:149], v[186:189], v[124:127]
	v_mfma_f32_16x16x32_bf16 v[120:123], v[178:181], v[186:189], v[120:123]
	v_mfma_f32_16x16x32_bf16 v[108:111], v[146:149], v[200:203], v[108:111]
	v_mfma_f32_16x16x32_bf16 v[104:107], v[178:181], v[200:203], v[104:107]
	v_mfma_f32_16x16x32_bf16 v[92:95], v[146:149], v[208:211], v[92:95]
	v_mfma_f32_16x16x32_bf16 v[88:91], v[178:181], v[208:211], v[88:91]
	v_mfma_f32_16x16x32_bf16 v[76:79], v[146:149], v[216:219], v[76:79]
	v_mfma_f32_16x16x32_bf16 v[72:75], v[178:181], v[216:219], v[72:75]
	v_mfma_f32_16x16x32_bf16 v[124:127], v[150:153], v[196:199], v[124:127]
	v_mfma_f32_16x16x32_bf16 v[120:123], v[182:185], v[196:199], v[120:123]
	v_mfma_f32_16x16x32_bf16 v[108:111], v[150:153], v[204:207], v[108:111]
	v_mfma_f32_16x16x32_bf16 v[104:107], v[182:185], v[204:207], v[104:107]
	v_mfma_f32_16x16x32_bf16 v[92:95], v[150:153], v[212:215], v[92:95]
	v_mfma_f32_16x16x32_bf16 v[88:91], v[182:185], v[212:215], v[88:91]
	v_mfma_f32_16x16x32_bf16 v[76:79], v[150:153], v[220:223], v[76:79]
	v_mfma_f32_16x16x32_bf16 v[72:75], v[182:185], v[220:223], v[72:75]
	s_barrier
	s_add_i32 s29, 0, 0x1c000
	s_add_i32 s28, s28, s11
	v_add_u32_e32 v154, s29, v159
	v_lshl_add_u64 v[156:157], v[156:157], 0, s[6:7]
	s_mov_b32 m0, s28
	ds_read_b128 v[224:227], v154
	ds_read_b128 v[228:231], v154 offset:1024
	ds_read_b128 v[232:235], v154 offset:2048
	ds_read_b128 v[236:239], v154 offset:3072
	global_load_lds_dwordx4 v[156:157], off
	v_lshl_add_u64 v[156:157], v[160:161], 0, s[6:7]
	s_add_i32 m0, s28, 0x2000
	s_nop 0
	global_load_lds_dwordx4 v[156:157], off
	s_barrier
	s_waitcnt lgkmcnt(0)
	v_mfma_f32_16x16x32_bf16 v[116:119], v[224:227], v[186:189], v[116:119]
	v_mfma_f32_16x16x32_bf16 v[112:115], v[232:235], v[186:189], v[112:115]
	v_mfma_f32_16x16x32_bf16 v[100:103], v[224:227], v[200:203], v[100:103]
	v_mfma_f32_16x16x32_bf16 v[96:99], v[232:235], v[200:203], v[96:99]
	v_mfma_f32_16x16x32_bf16 v[84:87], v[224:227], v[208:211], v[84:87]
	v_mfma_f32_16x16x32_bf16 v[80:83], v[232:235], v[208:211], v[80:83]
	v_mfma_f32_16x16x32_bf16 v[68:71], v[224:227], v[216:219], v[68:71]
	v_mfma_f32_16x16x32_bf16 v[64:67], v[232:235], v[216:219], v[64:67]
	v_mfma_f32_16x16x32_bf16 v[116:119], v[228:231], v[196:199], v[116:119]
	v_mfma_f32_16x16x32_bf16 v[112:115], v[236:239], v[196:199], v[112:115]
	v_mfma_f32_16x16x32_bf16 v[100:103], v[228:231], v[204:207], v[100:103]
	v_mfma_f32_16x16x32_bf16 v[96:99], v[236:239], v[204:207], v[96:99]
	v_mfma_f32_16x16x32_bf16 v[84:87], v[228:231], v[212:215], v[84:87]
	v_mfma_f32_16x16x32_bf16 v[80:83], v[236:239], v[212:215], v[80:83]
	v_mfma_f32_16x16x32_bf16 v[68:71], v[228:231], v[220:223], v[68:71]
	v_mfma_f32_16x16x32_bf16 v[64:67], v[236:239], v[220:223], v[64:67]
	s_mov_b32 m0, s53
	v_lshl_add_u64 v[156:157], v[164:165], 0, s[6:7]
	s_barrier
	ds_read_b128 v[186:189], v171 offset:49152
	ds_read_b128 v[196:199], v171 offset:50176
	ds_read_b128 v[200:203], v171 offset:51200
	ds_read_b128 v[204:207], v171 offset:52224
	ds_read_b128 v[208:211], v171 offset:53248
	ds_read_b128 v[212:215], v171 offset:54272
	ds_read_b128 v[216:219], v171 offset:55296
	ds_read_b128 v[220:223], v171 offset:56320
	global_load_lds_dwordx4 v[156:157], off
	v_lshl_add_u64 v[156:157], v[168:169], 0, s[6:7]
	s_mov_b32 m0, s54
	s_nop 0
	global_load_lds_dwordx4 v[156:157], off
	s_barrier
	s_waitcnt lgkmcnt(0)
	v_mfma_f32_16x16x32_bf16 v[60:63], v[146:149], v[186:189], v[60:63]
	v_mfma_f32_16x16x32_bf16 v[56:59], v[178:181], v[186:189], v[56:59]
	v_mfma_f32_16x16x32_bf16 v[44:47], v[146:149], v[200:203], v[44:47]
	v_mfma_f32_16x16x32_bf16 v[40:43], v[178:181], v[200:203], v[40:43]
	v_mfma_f32_16x16x32_bf16 v[28:31], v[146:149], v[208:211], v[28:31]
	v_mfma_f32_16x16x32_bf16 v[24:27], v[178:181], v[208:211], v[24:27]
	v_mfma_f32_16x16x32_bf16 v[12:15], v[146:149], v[216:219], v[12:15]
	v_mfma_f32_16x16x32_bf16 v[8:11], v[178:181], v[216:219], v[8:11]
	v_mfma_f32_16x16x32_bf16 v[60:63], v[150:153], v[196:199], v[60:63]
	v_mfma_f32_16x16x32_bf16 v[56:59], v[182:185], v[196:199], v[56:59]
	v_mfma_f32_16x16x32_bf16 v[44:47], v[150:153], v[204:207], v[44:47]
	v_mfma_f32_16x16x32_bf16 v[40:43], v[182:185], v[204:207], v[40:43]
	v_mfma_f32_16x16x32_bf16 v[28:31], v[150:153], v[212:215], v[28:31]
	v_mfma_f32_16x16x32_bf16 v[24:27], v[182:185], v[212:215], v[24:27]
	v_mfma_f32_16x16x32_bf16 v[12:15], v[150:153], v[220:223], v[12:15]
	v_mfma_f32_16x16x32_bf16 v[8:11], v[182:185], v[220:223], v[8:11]
	s_barrier
	s_add_u32 s42, s42, 0x40080
	s_addc_u32 s43, s43, 0
	s_add_i32 s28, s29, s11
	v_lshl_add_u64 v[146:147], s[42:43], 0, v[132:133]
	s_mov_b32 m0, s28
	s_nop 0
	global_load_lds_dwordx4 v[146:147], off
	v_lshl_add_u64 v[146:147], s[42:43], 0, v[128:129]
	s_add_i32 m0, s28, 0x2000
	s_nop 0
	global_load_lds_dwordx4 v[146:147], off
	s_waitcnt vmcnt(6)
	s_barrier
	v_mfma_f32_16x16x32_bf16 v[52:55], v[224:227], v[186:189], v[52:55]
	v_mfma_f32_16x16x32_bf16 v[48:51], v[232:235], v[186:189], v[48:51]
	v_mfma_f32_16x16x32_bf16 v[36:39], v[224:227], v[200:203], v[36:39]
	v_mfma_f32_16x16x32_bf16 v[32:35], v[232:235], v[200:203], v[32:35]
	v_mfma_f32_16x16x32_bf16 v[20:23], v[224:227], v[208:211], v[20:23]
	v_mfma_f32_16x16x32_bf16 v[16:19], v[232:235], v[208:211], v[16:19]
	v_mfma_f32_16x16x32_bf16 v[4:7], v[224:227], v[216:219], v[4:7]
	v_mfma_f32_16x16x32_bf16 v[0:3], v[232:235], v[216:219], v[0:3]
	v_mfma_f32_16x16x32_bf16 v[52:55], v[228:231], v[196:199], v[52:55]
	v_mfma_f32_16x16x32_bf16 v[48:51], v[236:239], v[196:199], v[48:51]
	v_mfma_f32_16x16x32_bf16 v[36:39], v[228:231], v[204:207], v[36:39]
	v_mfma_f32_16x16x32_bf16 v[32:35], v[236:239], v[204:207], v[32:35]
	v_mfma_f32_16x16x32_bf16 v[20:23], v[228:231], v[212:215], v[20:23]
	v_mfma_f32_16x16x32_bf16 v[16:19], v[236:239], v[212:215], v[16:19]
	v_mfma_f32_16x16x32_bf16 v[4:7], v[228:231], v[220:223], v[4:7]
	v_mfma_f32_16x16x32_bf16 v[0:3], v[236:239], v[220:223], v[0:3]
	s_add_i32 s64, s64, 2
	s_add_u32 s0, s0, 0x100
	s_addc_u32 s1, s1, 0
	s_add_u32 s62, s62, 0x100
	s_addc_u32 s63, s63, 0
	s_cmp_gt_u32 s64, 13
	s_barrier
	s_cbranch_scc0 .LBB0_1093
	s_branch .Lz10_skip

.LBB0_1169:
	ds_read_b128 v[128:131], v167
	ds_read_b128 v[132:135], v167 offset:1024
	ds_read_b128 v[136:139], v167 offset:2048
	ds_read_b128 v[156:159], v167 offset:3072
	s_add_u32 s6, s40, 0x100
	s_addc_u32 s7, s41, 0
	s_cmp_eq_u32 s65, 40
	s_cselect_b32 s45, s1, s7
	s_cselect_b32 s44, s0, s6
	s_cselect_b32 s43, s39, s64
	s_cselect_b32 s42, s38, s63
	v_lshl_add_u64 v[202:203], s[40:41], 0, v[148:149]
	s_add_i32 m0, s47, 0xc000
	ds_read_b128 v[160:163], v168
	ds_read_b128 v[172:175], v168 offset:1024
	ds_read_b128 v[176:179], v168 offset:2048
	ds_read_b128 v[180:183], v168 offset:3072
	ds_read_b128 v[184:187], v168 offset:4096
	ds_read_b128 v[188:191], v168 offset:5120
	ds_read_b128 v[194:197], v168 offset:6144
	ds_read_b128 v[198:201], v168 offset:7168
	global_load_lds_dwordx4 v[202:203], off
	v_lshl_add_u64 v[202:203], s[40:41], 0, v[150:151]
	s_add_i32 m0, s47, 0xe000
	s_nop 0
	global_load_lds_dwordx4 v[202:203], off
	s_waitcnt lgkmcnt(8)
	s_barrier
	s_waitcnt lgkmcnt(0)
	v_mfma_f32_16x16x32_bf16 v[124:127], v[128:131], v[160:163], v[124:127]
	v_mfma_f32_16x16x32_bf16 v[120:123], v[136:139], v[160:163], v[120:123]
	v_mfma_f32_16x16x32_bf16 v[108:111], v[128:131], v[176:179], v[108:111]
	v_mfma_f32_16x16x32_bf16 v[104:107], v[136:139], v[176:179], v[104:107]
	v_mfma_f32_16x16x32_bf16 v[92:95], v[128:131], v[184:187], v[92:95]
	v_mfma_f32_16x16x32_bf16 v[88:91], v[136:139], v[184:187], v[88:91]
	v_mfma_f32_16x16x32_bf16 v[76:79], v[128:131], v[194:197], v[76:79]
	v_mfma_f32_16x16x32_bf16 v[72:75], v[136:139], v[194:197], v[72:75]
	v_mfma_f32_16x16x32_bf16 v[124:127], v[132:135], v[172:175], v[124:127]
	v_mfma_f32_16x16x32_bf16 v[120:123], v[156:159], v[172:175], v[120:123]
	v_mfma_f32_16x16x32_bf16 v[108:111], v[132:135], v[180:183], v[108:111]
	v_mfma_f32_16x16x32_bf16 v[104:107], v[156:159], v[180:183], v[104:107]
	v_mfma_f32_16x16x32_bf16 v[92:95], v[132:135], v[188:191], v[92:95]
	v_mfma_f32_16x16x32_bf16 v[88:91], v[156:159], v[188:191], v[88:91]
	v_mfma_f32_16x16x32_bf16 v[76:79], v[132:135], v[198:201], v[76:79]
	v_mfma_f32_16x16x32_bf16 v[72:75], v[156:159], v[198:201], v[72:75]
	s_barrier
	s_add_i32 s28, s57, s46
	v_lshl_add_u64 v[218:219], s[42:43], 0, v[142:143]
	s_mov_b32 m0, s28
	ds_read_b128 v[202:205], v169
	ds_read_b128 v[206:209], v169 offset:1024
	ds_read_b128 v[210:213], v169 offset:2048
	ds_read_b128 v[214:217], v169 offset:3072
	global_load_lds_dwordx4 v[218:219], off
	v_lshl_add_u64 v[220:221], s[42:43], 0, v[146:147]
	s_add_i32 m0, s28, 0x2000
	s_nop 0
	global_load_lds_dwordx4 v[220:221], off
	s_barrier
	s_waitcnt lgkmcnt(0)
	v_mfma_f32_16x16x32_bf16 v[116:119], v[202:205], v[160:163], v[116:119]
	v_mfma_f32_16x16x32_bf16 v[112:115], v[210:213], v[160:163], v[112:115]
	v_mfma_f32_16x16x32_bf16 v[100:103], v[202:205], v[176:179], v[100:103]
	v_mfma_f32_16x16x32_bf16 v[96:99], v[210:213], v[176:179], v[96:99]
	v_mfma_f32_16x16x32_bf16 v[84:87], v[202:205], v[184:187], v[84:87]
	v_mfma_f32_16x16x32_bf16 v[80:83], v[210:213], v[184:187], v[80:83]
	v_mfma_f32_16x16x32_bf16 v[68:71], v[202:205], v[194:197], v[68:71]
	v_mfma_f32_16x16x32_bf16 v[64:67], v[210:213], v[194:197], v[64:67]
	v_mfma_f32_16x16x32_bf16 v[116:119], v[206:209], v[172:175], v[116:119]
	v_mfma_f32_16x16x32_bf16 v[112:115], v[214:217], v[172:175], v[112:115]
	v_mfma_f32_16x16x32_bf16 v[100:103], v[206:209], v[180:183], v[100:103]
	v_mfma_f32_16x16x32_bf16 v[96:99], v[214:217], v[180:183], v[96:99]
	v_mfma_f32_16x16x32_bf16 v[84:87], v[206:209], v[188:191], v[84:87]
	v_mfma_f32_16x16x32_bf16 v[80:83], v[214:217], v[188:191], v[80:83]
	v_mfma_f32_16x16x32_bf16 v[68:71], v[206:209], v[198:201], v[68:71]
	v_mfma_f32_16x16x32_bf16 v[64:67], v[214:217], v[198:201], v[64:67]
	s_mov_b32 m0, s47
	v_lshl_add_u64 v[222:223], s[44:45], 0, v[140:141]
	s_barrier
	ds_read_b128 v[160:163], v168 offset:16384
	ds_read_b128 v[172:175], v168 offset:17408
	ds_read_b128 v[176:179], v168 offset:18432
	ds_read_b128 v[180:183], v168 offset:19456
	ds_read_b128 v[184:187], v168 offset:20480
	ds_read_b128 v[188:191], v168 offset:21504
	ds_read_b128 v[194:197], v168 offset:22528
	ds_read_b128 v[198:201], v168 offset:23552
	global_load_lds_dwordx4 v[222:223], off
	v_lshl_add_u64 v[224:225], s[44:45], 0, v[144:145]
	s_mov_b32 m0, s48
	s_nop 0
	global_load_lds_dwordx4 v[224:225], off
	s_barrier
	s_waitcnt lgkmcnt(0)
	v_mfma_f32_16x16x32_bf16 v[60:63], v[128:131], v[160:163], v[60:63]
	v_mfma_f32_16x16x32_bf16 v[56:59], v[136:139], v[160:163], v[56:59]
	v_mfma_f32_16x16x32_bf16 v[44:47], v[128:131], v[176:179], v[44:47]
	v_mfma_f32_16x16x32_bf16 v[40:43], v[136:139], v[176:179], v[40:43]
	v_mfma_f32_16x16x32_bf16 v[28:31], v[128:131], v[184:187], v[28:31]
	v_mfma_f32_16x16x32_bf16 v[24:27], v[136:139], v[184:187], v[24:27]
	v_mfma_f32_16x16x32_bf16 v[12:15], v[128:131], v[194:197], v[12:15]
	v_mfma_f32_16x16x32_bf16 v[8:11], v[136:139], v[194:197], v[8:11]
	v_mfma_f32_16x16x32_bf16 v[60:63], v[132:135], v[172:175], v[60:63]
	v_mfma_f32_16x16x32_bf16 v[56:59], v[156:159], v[172:175], v[56:59]
	v_mfma_f32_16x16x32_bf16 v[44:47], v[132:135], v[180:183], v[44:47]
	v_mfma_f32_16x16x32_bf16 v[40:43], v[156:159], v[180:183], v[40:43]
	v_mfma_f32_16x16x32_bf16 v[28:31], v[132:135], v[188:191], v[28:31]
	v_mfma_f32_16x16x32_bf16 v[24:27], v[156:159], v[188:191], v[24:27]
	v_mfma_f32_16x16x32_bf16 v[12:15], v[132:135], v[198:201], v[12:15]
	v_mfma_f32_16x16x32_bf16 v[8:11], v[156:159], v[198:201], v[8:11]
	s_barrier
	s_add_u32 s40, s42, 0x2c000
	s_addc_u32 s41, s43, 0
	s_add_i32 s28, s58, s46
	v_lshl_add_u64 v[128:129], s[40:41], 0, v[142:143]
	s_mov_b32 m0, s28
	s_nop 0
	global_load_lds_dwordx4 v[128:129], off
	v_lshl_add_u64 v[128:129], s[40:41], 0, v[146:147]
	s_add_i32 m0, s28, 0x2000
	s_nop 0
	global_load_lds_dwordx4 v[128:129], off
	s_waitcnt vmcnt(6)
	s_barrier
	v_mfma_f32_16x16x32_bf16 v[52:55], v[202:205], v[160:163], v[52:55]
	v_mfma_f32_16x16x32_bf16 v[48:51], v[210:213], v[160:163], v[48:51]
	v_mfma_f32_16x16x32_bf16 v[36:39], v[202:205], v[176:179], v[36:39]
	v_mfma_f32_16x16x32_bf16 v[32:35], v[210:213], v[176:179], v[32:35]
	v_mfma_f32_16x16x32_bf16 v[20:23], v[202:205], v[184:187], v[20:23]
	v_mfma_f32_16x16x32_bf16 v[16:19], v[210:213], v[184:187], v[16:19]
	v_mfma_f32_16x16x32_bf16 v[4:7], v[202:205], v[194:197], v[4:7]
	v_mfma_f32_16x16x32_bf16 v[0:3], v[210:213], v[194:197], v[0:3]
	v_mfma_f32_16x16x32_bf16 v[52:55], v[206:209], v[172:175], v[52:55]
	v_mfma_f32_16x16x32_bf16 v[48:51], v[214:217], v[172:175], v[48:51]
	v_mfma_f32_16x16x32_bf16 v[36:39], v[206:209], v[180:183], v[36:39]
	v_mfma_f32_16x16x32_bf16 v[32:35], v[214:217], v[180:183], v[32:35]
	v_mfma_f32_16x16x32_bf16 v[20:23], v[206:209], v[188:191], v[20:23]
	v_mfma_f32_16x16x32_bf16 v[16:19], v[214:217], v[188:191], v[16:19]
	v_mfma_f32_16x16x32_bf16 v[4:7], v[206:209], v[198:201], v[4:7]
	v_mfma_f32_16x16x32_bf16 v[0:3], v[214:217], v[198:201], v[0:3]
	s_add_i32 s28, 0, 0x18000
	v_add_u32_e32 v156, s28, v165
	s_barrier
	ds_read_b128 v[128:131], v156
	ds_read_b128 v[132:135], v156 offset:1024
	ds_read_b128 v[136:139], v156 offset:2048
	ds_read_b128 v[156:159], v156 offset:3072
	s_add_u32 s40, s44, 0xb0000
	s_addc_u32 s41, s45, 0
	s_mov_b32 m0, s49
	v_lshl_add_u64 v[202:203], s[40:41], 0, v[140:141]
	ds_read_b128 v[160:163], v168 offset:32768
	ds_read_b128 v[172:175], v168 offset:33792
	ds_read_b128 v[176:179], v168 offset:34816
	ds_read_b128 v[180:183], v168 offset:35840
	ds_read_b128 v[184:187], v168 offset:36864
	ds_read_b128 v[188:191], v168 offset:37888
	ds_read_b128 v[194:197], v168 offset:38912
	ds_read_b128 v[198:201], v168 offset:39936
	global_load_lds_dwordx4 v[202:203], off
	v_lshl_add_u64 v[202:203], s[40:41], 0, v[144:145]
	s_mov_b32 m0, s50
	s_nop 0
	global_load_lds_dwordx4 v[202:203], off
	s_waitcnt lgkmcnt(8)
	s_barrier
	s_waitcnt lgkmcnt(0)
	v_mfma_f32_16x16x32_bf16 v[124:127], v[128:131], v[160:163], v[124:127]
	v_mfma_f32_16x16x32_bf16 v[120:123], v[136:139], v[160:163], v[120:123]
	v_mfma_f32_16x16x32_bf16 v[108:111], v[128:131], v[176:179], v[108:111]
	v_mfma_f32_16x16x32_bf16 v[104:107], v[136:139], v[176:179], v[104:107]
	v_mfma_f32_16x16x32_bf16 v[92:95], v[128:131], v[184:187], v[92:95]
	v_mfma_f32_16x16x32_bf16 v[88:91], v[136:139], v[184:187], v[88:91]
	v_mfma_f32_16x16x32_bf16 v[76:79], v[128:131], v[194:197], v[76:79]
	v_mfma_f32_16x16x32_bf16 v[72:75], v[136:139], v[194:197], v[72:75]
	v_mfma_f32_16x16x32_bf16 v[124:127], v[132:135], v[172:175], v[124:127]
	v_mfma_f32_16x16x32_bf16 v[120:123], v[156:159], v[172:175], v[120:123]
	v_mfma_f32_16x16x32_bf16 v[108:111], v[132:135], v[180:183], v[108:111]
	v_mfma_f32_16x16x32_bf16 v[104:107], v[156:159], v[180:183], v[104:107]
	v_mfma_f32_16x16x32_bf16 v[92:95], v[132:135], v[188:191], v[92:95]
	v_mfma_f32_16x16x32_bf16 v[88:91], v[156:159], v[188:191], v[88:91]
	v_mfma_f32_16x16x32_bf16 v[76:79], v[132:135], v[198:201], v[76:79]
	v_mfma_f32_16x16x32_bf16 v[72:75], v[156:159], v[198:201], v[72:75]
	s_barrier
	s_add_i32 s29, 0, 0x1c000
	s_add_i32 s28, s28, s46
	v_add_u32_e32 v171, s29, v165
	v_lshl_add_u64 v[218:219], v[218:219], 0, s[36:37]
	s_mov_b32 m0, s28
	ds_read_b128 v[202:205], v171
	ds_read_b128 v[206:209], v171 offset:1024
	ds_read_b128 v[210:213], v171 offset:2048
	ds_read_b128 v[214:217], v171 offset:3072
	global_load_lds_dwordx4 v[218:219], off
	v_lshl_add_u64 v[218:219], v[220:221], 0, s[36:37]
	s_add_i32 m0, s28, 0x2000
	s_nop 0
	global_load_lds_dwordx4 v[218:219], off
	s_barrier
	s_waitcnt lgkmcnt(0)
	v_mfma_f32_16x16x32_bf16 v[116:119], v[202:205], v[160:163], v[116:119]
	v_mfma_f32_16x16x32_bf16 v[112:115], v[210:213], v[160:163], v[112:115]
	v_mfma_f32_16x16x32_bf16 v[100:103], v[202:205], v[176:179], v[100:103]
	v_mfma_f32_16x16x32_bf16 v[96:99], v[210:213], v[176:179], v[96:99]
	v_mfma_f32_16x16x32_bf16 v[84:87], v[202:205], v[184:187], v[84:87]
	v_mfma_f32_16x16x32_bf16 v[80:83], v[210:213], v[184:187], v[80:83]
	v_mfma_f32_16x16x32_bf16 v[68:71], v[202:205], v[194:197], v[68:71]
	v_mfma_f32_16x16x32_bf16 v[64:67], v[210:213], v[194:197], v[64:67]
	v_mfma_f32_16x16x32_bf16 v[116:119], v[206:209], v[172:175], v[116:119]
	v_mfma_f32_16x16x32_bf16 v[112:115], v[214:217], v[172:175], v[112:115]
	v_mfma_f32_16x16x32_bf16 v[100:103], v[206:209], v[180:183], v[100:103]
	v_mfma_f32_16x16x32_bf16 v[96:99], v[214:217], v[180:183], v[96:99]
	v_mfma_f32_16x16x32_bf16 v[84:87], v[206:209], v[188:191], v[84:87]
	v_mfma_f32_16x16x32_bf16 v[80:83], v[214:217], v[188:191], v[80:83]
	v_mfma_f32_16x16x32_bf16 v[68:71], v[206:209], v[198:201], v[68:71]
	v_mfma_f32_16x16x32_bf16 v[64:67], v[214:217], v[198:201], v[64:67]
	s_mov_b32 m0, s54
	v_lshl_add_u64 v[218:219], v[222:223], 0, s[36:37]
	s_barrier
	ds_read_b128 v[160:163], v168 offset:49152
	ds_read_b128 v[172:175], v168 offset:50176
	ds_read_b128 v[176:179], v168 offset:51200
	ds_read_b128 v[180:183], v168 offset:52224
	ds_read_b128 v[184:187], v168 offset:53248
	ds_read_b128 v[188:191], v168 offset:54272
	ds_read_b128 v[194:197], v168 offset:55296
	ds_read_b128 v[198:201], v168 offset:56320
	global_load_lds_dwordx4 v[218:219], off
	v_lshl_add_u64 v[218:219], v[224:225], 0, s[36:37]
	s_mov_b32 m0, s55
	s_nop 0
	global_load_lds_dwordx4 v[218:219], off
	s_barrier
	s_waitcnt lgkmcnt(0)
	v_mfma_f32_16x16x32_bf16 v[60:63], v[128:131], v[160:163], v[60:63]
	v_mfma_f32_16x16x32_bf16 v[56:59], v[136:139], v[160:163], v[56:59]
	v_mfma_f32_16x16x32_bf16 v[44:47], v[128:131], v[176:179], v[44:47]
	v_mfma_f32_16x16x32_bf16 v[40:43], v[136:139], v[176:179], v[40:43]
	v_mfma_f32_16x16x32_bf16 v[28:31], v[128:131], v[184:187], v[28:31]
	v_mfma_f32_16x16x32_bf16 v[24:27], v[136:139], v[184:187], v[24:27]
	v_mfma_f32_16x16x32_bf16 v[12:15], v[128:131], v[194:197], v[12:15]
	v_mfma_f32_16x16x32_bf16 v[8:11], v[136:139], v[194:197], v[8:11]
	v_mfma_f32_16x16x32_bf16 v[60:63], v[132:135], v[172:175], v[60:63]
	v_mfma_f32_16x16x32_bf16 v[56:59], v[156:159], v[172:175], v[56:59]
	v_mfma_f32_16x16x32_bf16 v[44:47], v[132:135], v[180:183], v[44:47]
	v_mfma_f32_16x16x32_bf16 v[40:43], v[156:159], v[180:183], v[40:43]
	v_mfma_f32_16x16x32_bf16 v[28:31], v[132:135], v[188:191], v[28:31]
	v_mfma_f32_16x16x32_bf16 v[24:27], v[156:159], v[188:191], v[24:27]
	v_mfma_f32_16x16x32_bf16 v[12:15], v[132:135], v[198:201], v[12:15]
	v_mfma_f32_16x16x32_bf16 v[8:11], v[156:159], v[198:201], v[8:11]
	s_barrier
	s_add_u32 s40, s42, 0x2c080
	s_addc_u32 s41, s43, 0
	s_add_i32 s28, s29, s46
	v_lshl_add_u64 v[128:129], s[40:41], 0, v[142:143]
	s_mov_b32 m0, s28
	s_nop 0
	global_load_lds_dwordx4 v[128:129], off
	v_lshl_add_u64 v[128:129], s[40:41], 0, v[146:147]
	s_add_i32 m0, s28, 0x2000
	s_nop 0
	global_load_lds_dwordx4 v[128:129], off
	s_waitcnt vmcnt(6)
	s_barrier
	v_mfma_f32_16x16x32_bf16 v[52:55], v[202:205], v[160:163], v[52:55]
	v_mfma_f32_16x16x32_bf16 v[48:51], v[210:213], v[160:163], v[48:51]
	v_mfma_f32_16x16x32_bf16 v[36:39], v[202:205], v[176:179], v[36:39]
	v_mfma_f32_16x16x32_bf16 v[32:35], v[210:213], v[176:179], v[32:35]
	v_mfma_f32_16x16x32_bf16 v[20:23], v[202:205], v[184:187], v[20:23]
	v_mfma_f32_16x16x32_bf16 v[16:19], v[210:213], v[184:187], v[16:19]
	v_mfma_f32_16x16x32_bf16 v[4:7], v[202:205], v[194:197], v[4:7]
	v_mfma_f32_16x16x32_bf16 v[0:3], v[210:213], v[194:197], v[0:3]
	v_mfma_f32_16x16x32_bf16 v[52:55], v[206:209], v[172:175], v[52:55]
	v_mfma_f32_16x16x32_bf16 v[48:51], v[214:217], v[172:175], v[48:51]
	v_mfma_f32_16x16x32_bf16 v[36:39], v[206:209], v[180:183], v[36:39]
	v_mfma_f32_16x16x32_bf16 v[32:35], v[214:217], v[180:183], v[32:35]
	v_mfma_f32_16x16x32_bf16 v[20:23], v[206:209], v[188:191], v[20:23]
	v_mfma_f32_16x16x32_bf16 v[16:19], v[214:217], v[188:191], v[16:19]
	v_mfma_f32_16x16x32_bf16 v[4:7], v[206:209], v[198:201], v[4:7]
	v_mfma_f32_16x16x32_bf16 v[0:3], v[214:217], v[198:201], v[0:3]
	s_add_i32 s65, s65, 2
	s_add_u32 s63, s63, 0x100
	s_addc_u32 s64, s64, 0
	s_cmp_gt_u32 s65, 41
	s_mov_b64 s[40:41], s[6:7]
	s_barrier
	s_cbranch_scc0 .LBB0_1169
	v_lshl_add_u32 v171, s62, 8, v164
	v_lshl_or_b32 v188, s10, 8, v166
	s_mov_b32 s63, 0xffff0000
	v_lshlrev_b32_e32 v128, 11, v171
	v_lshl_add_u32 v128, v188, 1, v128
	v_lshlrev_b32_e32 v129, 12, v171
	v_lshl_add_u32 v129, v188, 2, v129
	v_lshlrev_b32_e32 v132, 2, v188
	s_mov_b64 s[70:71], s[68:69]
	global_load_dwordx4 v[194:197], v128, s[70:71]
	global_load_dwordx4 v[198:201], v128, s[70:71] offset:64
	s_add_u32 s70, s70, 0x8000
	s_addc_u32 s71, s71, 0
	global_load_dwordx4 v[202:205], v128, s[70:71]
	global_load_dwordx4 v[206:209], v128, s[70:71] offset:64
	s_add_u32 s70, s70, 0x8000
	s_addc_u32 s71, s71, 0
	global_load_dwordx4 v[210:213], v128, s[70:71]
	global_load_dwordx4 v[214:217], v128, s[70:71] offset:64
	s_add_u32 s70, s70, 0x8000
	s_addc_u32 s71, s71, 0
	global_load_dwordx4 v[218:221], v128, s[70:71]
	global_load_dwordx4 v[222:225], v128, s[70:71] offset:64
	s_add_u32 s70, s70, 0x28000
	s_addc_u32 s71, s71, 0
	global_load_dwordx4 v[226:229], v128, s[70:71]
	global_load_dwordx4 v[230:233], v128, s[70:71] offset:64
	s_add_u32 s70, s70, 0x8000
	s_addc_u32 s71, s71, 0
	global_load_dwordx4 v[234:237], v128, s[70:71]
	global_load_dwordx4 v[238:241], v128, s[70:71] offset:64
	s_add_u32 s70, s70, 0x8000
	s_addc_u32 s71, s71, 0
	global_load_dwordx4 v[172:175], v128, s[70:71]
	global_load_dwordx4 v[176:179], v128, s[70:71] offset:64
	s_add_u32 s70, s70, 0x8000
	s_addc_u32 s71, s71, 0
	global_load_dwordx4 v[180:183], v128, s[70:71]
	global_load_dwordx4 v[184:187], v128, s[70:71] offset:64
	s_bfe_u32 s42, s17, 0x20006
	s_lshl_b32 s43, s10, 4
	s_lshl_b32 s42, s42, 2
	s_add_i32 s43, s43, s42
	v_lshl_add_u32 v130, v171, 6, s43
	v_and_b32_e32 v131, 48, v170
	v_lshl_add_u32 v131, v171, 6, v131
	v_xor_b32_e32 v134, 16, v170
	v_xor_b32_e32 v135, 32, v170
	v_lshlrev_b32_e32 v134, 2, v134
	v_lshlrev_b32_e32 v135, 2, v135
	v_cmp_gt_u32_e64 s[64:65], 16, v170
	s_add_u32 s74, s8, 0x2000
	s_addc_u32 s75, s9, 0
	s_lshl_b32 s42, s62, 7
	s_add_u32 s78, s26, 0x3c08000
	s_addc_u32 s79, s27, 0
	s_add_u32 s78, s78, s42
	s_addc_u32 s79, s79, 0
	s_waitcnt vmcnt(14)
	v_lshlrev_b32_e32 v136, 16, v194
	v_and_b32_e32 v137, s63, v194
	v_pk_add_f32 v[124:125], v[124:125], v[136:137]
	v_lshlrev_b32_e32 v138, 16, v195
	v_and_b32_e32 v139, s63, v195
	v_pk_add_f32 v[126:127], v[126:127], v[138:139]
	v_lshlrev_b32_e32 v190, 16, v196
	v_and_b32_e32 v191, s63, v196
	v_pk_add_f32 v[120:121], v[120:121], v[190:191]
	v_lshlrev_b32_e32 v136, 16, v197
	v_and_b32_e32 v137, s63, v197
	v_pk_add_f32 v[122:123], v[122:123], v[136:137]
	v_lshlrev_b32_e32 v138, 16, v198
	v_and_b32_e32 v139, s63, v198
	v_pk_add_f32 v[116:117], v[116:117], v[138:139]
	v_lshlrev_b32_e32 v190, 16, v199
	v_and_b32_e32 v191, s63, v199
	v_pk_add_f32 v[118:119], v[118:119], v[190:191]
	v_lshlrev_b32_e32 v136, 16, v200
	v_and_b32_e32 v137, s63, v200
	v_pk_add_f32 v[112:113], v[112:113], v[136:137]
	v_lshlrev_b32_e32 v138, 16, v201
	v_and_b32_e32 v139, s63, v201
	v_pk_add_f32 v[114:115], v[114:115], v[138:139]
	v_mul_f32_e32 v156, v120, v120
	v_mul_f32_e32 v189, v112, v112
	v_fmac_f32_e32 v156, v121, v121
	v_fmac_f32_e32 v189, v113, v113
	v_fmac_f32_e32 v156, v122, v122
	v_fmac_f32_e32 v189, v114, v114
	v_fmac_f32_e32 v156, v123, v123
	v_fmac_f32_e32 v189, v115, v115
	v_fmac_f32_e32 v156, v124, v124
	v_fmac_f32_e32 v189, v116, v116
	v_fmac_f32_e32 v156, v125, v125
	v_fmac_f32_e32 v189, v117, v117
	v_fmac_f32_e32 v156, v126, v126
	v_fmac_f32_e32 v189, v118, v118
	v_fmac_f32_e32 v156, v127, v127
	v_fmac_f32_e32 v189, v119, v119
	v_add_f32_e32 v156, v156, v189
	s_waitcnt vmcnt(12)
	v_lshlrev_b32_e32 v190, 16, v202
	v_and_b32_e32 v191, s63, v202
	v_pk_add_f32 v[108:109], v[108:109], v[190:191]
	v_lshlrev_b32_e32 v136, 16, v203
	v_and_b32_e32 v137, s63, v203
	v_pk_add_f32 v[110:111], v[110:111], v[136:137]
	v_lshlrev_b32_e32 v138, 16, v204
	v_and_b32_e32 v139, s63, v204
	v_pk_add_f32 v[104:105], v[104:105], v[138:139]
	v_lshlrev_b32_e32 v190, 16, v205
	v_and_b32_e32 v191, s63, v205
	v_pk_add_f32 v[106:107], v[106:107], v[190:191]
	v_lshlrev_b32_e32 v136, 16, v206
	v_and_b32_e32 v137, s63, v206
	v_pk_add_f32 v[100:101], v[100:101], v[136:137]
	v_lshlrev_b32_e32 v138, 16, v207
	v_and_b32_e32 v139, s63, v207
	v_pk_add_f32 v[102:103], v[102:103], v[138:139]
	v_lshlrev_b32_e32 v190, 16, v208
	v_and_b32_e32 v191, s63, v208
	v_pk_add_f32 v[96:97], v[96:97], v[190:191]
	v_lshlrev_b32_e32 v136, 16, v209
	v_and_b32_e32 v137, s63, v209
	v_pk_add_f32 v[98:99], v[98:99], v[136:137]
	v_mul_f32_e32 v157, v104, v104
	v_mul_f32_e32 v189, v96, v96
	v_fmac_f32_e32 v157, v105, v105
	v_fmac_f32_e32 v189, v97, v97
	v_fmac_f32_e32 v157, v106, v106
	v_fmac_f32_e32 v189, v98, v98
	v_fmac_f32_e32 v157, v107, v107
	v_fmac_f32_e32 v189, v99, v99
	v_fmac_f32_e32 v157, v108, v108
	v_fmac_f32_e32 v189, v100, v100
	v_fmac_f32_e32 v157, v109, v109
	v_fmac_f32_e32 v189, v101, v101
	v_fmac_f32_e32 v157, v110, v110
	v_fmac_f32_e32 v189, v102, v102
	v_fmac_f32_e32 v157, v111, v111
	v_fmac_f32_e32 v189, v103, v103
	v_add_f32_e32 v157, v157, v189
	s_waitcnt vmcnt(10)
	v_lshlrev_b32_e32 v138, 16, v210
	v_and_b32_e32 v139, s63, v210
	v_pk_add_f32 v[92:93], v[92:93], v[138:139]
	v_lshlrev_b32_e32 v190, 16, v211
	v_and_b32_e32 v191, s63, v211
	v_pk_add_f32 v[94:95], v[94:95], v[190:191]
	v_lshlrev_b32_e32 v136, 16, v212
	v_and_b32_e32 v137, s63, v212
	v_pk_add_f32 v[88:89], v[88:89], v[136:137]
	v_lshlrev_b32_e32 v138, 16, v213
	v_and_b32_e32 v139, s63, v213
	v_pk_add_f32 v[90:91], v[90:91], v[138:139]
	v_lshlrev_b32_e32 v190, 16, v214
	v_and_b32_e32 v191, s63, v214
	v_pk_add_f32 v[84:85], v[84:85], v[190:191]
	v_lshlrev_b32_e32 v136, 16, v215
	v_and_b32_e32 v137, s63, v215
	v_pk_add_f32 v[86:87], v[86:87], v[136:137]
	v_lshlrev_b32_e32 v138, 16, v216
	v_and_b32_e32 v139, s63, v216
	v_pk_add_f32 v[80:81], v[80:81], v[138:139]
	v_lshlrev_b32_e32 v190, 16, v217
	v_and_b32_e32 v191, s63, v217
	v_pk_add_f32 v[82:83], v[82:83], v[190:191]
	v_mul_f32_e32 v158, v88, v88
	v_mul_f32_e32 v189, v80, v80
	v_fmac_f32_e32 v158, v89, v89
	v_fmac_f32_e32 v189, v81, v81
	v_fmac_f32_e32 v158, v90, v90
	v_fmac_f32_e32 v189, v82, v82
	v_fmac_f32_e32 v158, v91, v91
	v_fmac_f32_e32 v189, v83, v83
	v_fmac_f32_e32 v158, v92, v92
	v_fmac_f32_e32 v189, v84, v84
	v_fmac_f32_e32 v158, v93, v93
	v_fmac_f32_e32 v189, v85, v85
	v_fmac_f32_e32 v158, v94, v94
	v_fmac_f32_e32 v189, v86, v86
	v_fmac_f32_e32 v158, v95, v95
	v_fmac_f32_e32 v189, v87, v87
	v_add_f32_e32 v158, v158, v189
	s_waitcnt vmcnt(8)
	v_lshlrev_b32_e32 v136, 16, v218
	v_and_b32_e32 v137, s63, v218
	v_pk_add_f32 v[76:77], v[76:77], v[136:137]
	v_lshlrev_b32_e32 v138, 16, v219
	v_and_b32_e32 v139, s63, v219
	v_pk_add_f32 v[78:79], v[78:79], v[138:139]
	v_lshlrev_b32_e32 v190, 16, v220
	v_and_b32_e32 v191, s63, v220
	v_pk_add_f32 v[72:73], v[72:73], v[190:191]
	v_lshlrev_b32_e32 v136, 16, v221
	v_and_b32_e32 v137, s63, v221
	v_pk_add_f32 v[74:75], v[74:75], v[136:137]
	v_lshlrev_b32_e32 v138, 16, v222
	v_and_b32_e32 v139, s63, v222
	v_pk_add_f32 v[68:69], v[68:69], v[138:139]
	v_lshlrev_b32_e32 v190, 16, v223
	v_and_b32_e32 v191, s63, v223
	v_pk_add_f32 v[70:71], v[70:71], v[190:191]
	v_lshlrev_b32_e32 v136, 16, v224
	v_and_b32_e32 v137, s63, v224
	v_pk_add_f32 v[64:65], v[64:65], v[136:137]
	v_lshlrev_b32_e32 v138, 16, v225
	v_and_b32_e32 v139, s63, v225
	v_pk_add_f32 v[66:67], v[66:67], v[138:139]
	v_mul_f32_e32 v159, v72, v72
	v_mul_f32_e32 v189, v64, v64
	v_fmac_f32_e32 v159, v73, v73
	v_fmac_f32_e32 v189, v65, v65
	v_fmac_f32_e32 v159, v74, v74
	v_fmac_f32_e32 v189, v66, v66
	v_fmac_f32_e32 v159, v75, v75
	v_fmac_f32_e32 v189, v67, v67
	v_fmac_f32_e32 v159, v76, v76
	v_fmac_f32_e32 v189, v68, v68
	v_fmac_f32_e32 v159, v77, v77
	v_fmac_f32_e32 v189, v69, v69
	v_fmac_f32_e32 v159, v78, v78
	v_fmac_f32_e32 v189, v70, v70
	v_fmac_f32_e32 v159, v79, v79
	v_fmac_f32_e32 v189, v71, v71
	v_add_f32_e32 v159, v159, v189
	s_waitcnt vmcnt(6)
	v_lshlrev_b32_e32 v190, 16, v226
	v_and_b32_e32 v191, s63, v226
	v_pk_add_f32 v[60:61], v[60:61], v[190:191]
	v_lshlrev_b32_e32 v136, 16, v227
	v_and_b32_e32 v137, s63, v227
	v_pk_add_f32 v[62:63], v[62:63], v[136:137]
	v_lshlrev_b32_e32 v138, 16, v228
	v_and_b32_e32 v139, s63, v228
	v_pk_add_f32 v[56:57], v[56:57], v[138:139]
	v_lshlrev_b32_e32 v190, 16, v229
	v_and_b32_e32 v191, s63, v229
	v_pk_add_f32 v[58:59], v[58:59], v[190:191]
	v_lshlrev_b32_e32 v136, 16, v230
	v_and_b32_e32 v137, s63, v230
	v_pk_add_f32 v[52:53], v[52:53], v[136:137]
	v_lshlrev_b32_e32 v138, 16, v231
	v_and_b32_e32 v139, s63, v231
	v_pk_add_f32 v[54:55], v[54:55], v[138:139]
	v_lshlrev_b32_e32 v190, 16, v232
	v_and_b32_e32 v191, s63, v232
	v_pk_add_f32 v[48:49], v[48:49], v[190:191]
	v_lshlrev_b32_e32 v136, 16, v233
	v_and_b32_e32 v137, s63, v233
	v_pk_add_f32 v[50:51], v[50:51], v[136:137]
	v_mul_f32_e32 v160, v56, v56
	v_mul_f32_e32 v189, v48, v48
	v_fmac_f32_e32 v160, v57, v57
	v_fmac_f32_e32 v189, v49, v49
	v_fmac_f32_e32 v160, v58, v58
	v_fmac_f32_e32 v189, v50, v50
	v_fmac_f32_e32 v160, v59, v59
	v_fmac_f32_e32 v189, v51, v51
	v_fmac_f32_e32 v160, v60, v60
	v_fmac_f32_e32 v189, v52, v52
	v_fmac_f32_e32 v160, v61, v61
	v_fmac_f32_e32 v189, v53, v53
	v_fmac_f32_e32 v160, v62, v62
	v_fmac_f32_e32 v189, v54, v54
	v_fmac_f32_e32 v160, v63, v63
	v_fmac_f32_e32 v189, v55, v55
	v_add_f32_e32 v160, v160, v189
	s_waitcnt vmcnt(4)
	v_lshlrev_b32_e32 v138, 16, v234
	v_and_b32_e32 v139, s63, v234
	v_pk_add_f32 v[44:45], v[44:45], v[138:139]
	v_lshlrev_b32_e32 v190, 16, v235
	v_and_b32_e32 v191, s63, v235
	v_pk_add_f32 v[46:47], v[46:47], v[190:191]
	v_lshlrev_b32_e32 v136, 16, v236
	v_and_b32_e32 v137, s63, v236
	v_pk_add_f32 v[40:41], v[40:41], v[136:137]
	v_lshlrev_b32_e32 v138, 16, v237
	v_and_b32_e32 v139, s63, v237
	v_pk_add_f32 v[42:43], v[42:43], v[138:139]
	v_lshlrev_b32_e32 v190, 16, v238
	v_and_b32_e32 v191, s63, v238
	v_pk_add_f32 v[36:37], v[36:37], v[190:191]
	v_lshlrev_b32_e32 v136, 16, v239
	v_and_b32_e32 v137, s63, v239
	v_pk_add_f32 v[38:39], v[38:39], v[136:137]
	v_lshlrev_b32_e32 v138, 16, v240
	v_and_b32_e32 v139, s63, v240
	v_pk_add_f32 v[32:33], v[32:33], v[138:139]
	v_lshlrev_b32_e32 v190, 16, v241
	v_and_b32_e32 v191, s63, v241
	v_pk_add_f32 v[34:35], v[34:35], v[190:191]
	v_mul_f32_e32 v161, v40, v40
	v_mul_f32_e32 v189, v32, v32
	v_fmac_f32_e32 v161, v41, v41
	v_fmac_f32_e32 v189, v33, v33
	v_fmac_f32_e32 v161, v42, v42
	v_fmac_f32_e32 v189, v34, v34
	v_fmac_f32_e32 v161, v43, v43
	v_fmac_f32_e32 v189, v35, v35
	v_fmac_f32_e32 v161, v44, v44
	v_fmac_f32_e32 v189, v36, v36
	v_fmac_f32_e32 v161, v45, v45
	v_fmac_f32_e32 v189, v37, v37
	v_fmac_f32_e32 v161, v46, v46
	v_fmac_f32_e32 v189, v38, v38
	v_fmac_f32_e32 v161, v47, v47
	v_fmac_f32_e32 v189, v39, v39
	v_add_f32_e32 v161, v161, v189
	s_waitcnt vmcnt(2)
	v_lshlrev_b32_e32 v136, 16, v172
	v_and_b32_e32 v137, s63, v172
	v_pk_add_f32 v[28:29], v[28:29], v[136:137]
	v_lshlrev_b32_e32 v138, 16, v173
	v_and_b32_e32 v139, s63, v173
	v_pk_add_f32 v[30:31], v[30:31], v[138:139]
	v_lshlrev_b32_e32 v190, 16, v174
	v_and_b32_e32 v191, s63, v174
	v_pk_add_f32 v[24:25], v[24:25], v[190:191]
	v_lshlrev_b32_e32 v136, 16, v175
	v_and_b32_e32 v137, s63, v175
	v_pk_add_f32 v[26:27], v[26:27], v[136:137]
	v_lshlrev_b32_e32 v138, 16, v176
	v_and_b32_e32 v139, s63, v176
	v_pk_add_f32 v[20:21], v[20:21], v[138:139]
	v_lshlrev_b32_e32 v190, 16, v177
	v_and_b32_e32 v191, s63, v177
	v_pk_add_f32 v[22:23], v[22:23], v[190:191]
	v_lshlrev_b32_e32 v136, 16, v178
	v_and_b32_e32 v137, s63, v178
	v_pk_add_f32 v[16:17], v[16:17], v[136:137]
	v_lshlrev_b32_e32 v138, 16, v179
	v_and_b32_e32 v139, s63, v179
	v_pk_add_f32 v[18:19], v[18:19], v[138:139]
	v_mul_f32_e32 v162, v24, v24
	v_mul_f32_e32 v189, v16, v16
	v_fmac_f32_e32 v162, v25, v25
	v_fmac_f32_e32 v189, v17, v17
	v_fmac_f32_e32 v162, v26, v26
	v_fmac_f32_e32 v189, v18, v18
	v_fmac_f32_e32 v162, v27, v27
	v_fmac_f32_e32 v189, v19, v19
	v_fmac_f32_e32 v162, v28, v28
	v_fmac_f32_e32 v189, v20, v20
	v_fmac_f32_e32 v162, v29, v29
	v_fmac_f32_e32 v189, v21, v21
	v_fmac_f32_e32 v162, v30, v30
	v_fmac_f32_e32 v189, v22, v22
	v_fmac_f32_e32 v162, v31, v31
	v_fmac_f32_e32 v189, v23, v23
	v_add_f32_e32 v162, v162, v189
	s_waitcnt vmcnt(0)
	v_lshlrev_b32_e32 v190, 16, v180
	v_and_b32_e32 v191, s63, v180
	v_pk_add_f32 v[12:13], v[12:13], v[190:191]
	v_lshlrev_b32_e32 v136, 16, v181
	v_and_b32_e32 v137, s63, v181
	v_pk_add_f32 v[14:15], v[14:15], v[136:137]
	v_lshlrev_b32_e32 v138, 16, v182
	v_and_b32_e32 v139, s63, v182
	v_pk_add_f32 v[8:9], v[8:9], v[138:139]
	v_lshlrev_b32_e32 v190, 16, v183
	v_and_b32_e32 v191, s63, v183
	v_pk_add_f32 v[10:11], v[10:11], v[190:191]
	v_lshlrev_b32_e32 v136, 16, v184
	v_and_b32_e32 v137, s63, v184
	v_pk_add_f32 v[4:5], v[4:5], v[136:137]
	v_lshlrev_b32_e32 v138, 16, v185
	v_and_b32_e32 v139, s63, v185
	v_pk_add_f32 v[6:7], v[6:7], v[138:139]
	v_lshlrev_b32_e32 v190, 16, v186
	v_and_b32_e32 v191, s63, v186
	v_pk_add_f32 v[0:1], v[0:1], v[190:191]
	v_lshlrev_b32_e32 v136, 16, v187
	v_and_b32_e32 v137, s63, v187
	v_pk_add_f32 v[2:3], v[2:3], v[136:137]
	v_mul_f32_e32 v163, v8, v8
	v_mul_f32_e32 v189, v0, v0
	v_fmac_f32_e32 v163, v9, v9
	v_fmac_f32_e32 v189, v1, v1
	v_fmac_f32_e32 v163, v10, v10
	v_fmac_f32_e32 v189, v2, v2
	v_fmac_f32_e32 v163, v11, v11
	v_fmac_f32_e32 v189, v3, v3
	v_fmac_f32_e32 v163, v12, v12
	v_fmac_f32_e32 v189, v4, v4
	v_fmac_f32_e32 v163, v13, v13
	v_fmac_f32_e32 v189, v5, v5
	v_fmac_f32_e32 v163, v14, v14
	v_fmac_f32_e32 v189, v6, v6
	v_fmac_f32_e32 v163, v15, v15
	v_fmac_f32_e32 v189, v7, v7
	v_add_f32_e32 v163, v163, v189
	ds_bpermute_b32 v136, v134, v156
	ds_bpermute_b32 v137, v134, v157
	ds_bpermute_b32 v138, v134, v158
	ds_bpermute_b32 v139, v134, v159
	ds_bpermute_b32 v188, v134, v160
	ds_bpermute_b32 v189, v134, v161
	ds_bpermute_b32 v190, v134, v162
	ds_bpermute_b32 v191, v134, v163
	s_waitcnt lgkmcnt(0)
	v_add_f32_e32 v156, v156, v136
	v_add_f32_e32 v157, v157, v137
	v_add_f32_e32 v158, v158, v138
	v_add_f32_e32 v159, v159, v139
	v_add_f32_e32 v160, v160, v188
	v_add_f32_e32 v161, v161, v189
	v_add_f32_e32 v162, v162, v190
	v_add_f32_e32 v163, v163, v191
	ds_bpermute_b32 v136, v135, v156
	ds_bpermute_b32 v137, v135, v157
	ds_bpermute_b32 v138, v135, v158
	ds_bpermute_b32 v139, v135, v159
	ds_bpermute_b32 v188, v135, v160
	ds_bpermute_b32 v189, v135, v161
	ds_bpermute_b32 v190, v135, v162
	ds_bpermute_b32 v191, v135, v163
	s_waitcnt lgkmcnt(0)
	v_add_f32_e32 v156, v156, v136
	v_add_f32_e32 v157, v157, v137
	v_add_f32_e32 v158, v158, v138
	v_add_f32_e32 v159, v159, v139
	v_add_f32_e32 v160, v160, v188
	v_add_f32_e32 v161, v161, v189
	v_add_f32_e32 v162, v162, v190
	v_add_f32_e32 v163, v163, v191
	s_and_saveexec_b64 s[66:67], s[64:65]
	global_store_dword v130, v156, s[8:9] sc1
	global_store_dword v130, v157, s[8:9] offset:1024 sc1
	global_store_dword v130, v158, s[8:9] offset:2048 sc1
	global_store_dword v130, v159, s[8:9] offset:3072 sc1
	global_store_dword v130, v160, s[74:75] sc1
	global_store_dword v130, v161, s[74:75] offset:1024 sc1
	global_store_dword v130, v162, s[74:75] offset:2048 sc1
	global_store_dword v130, v163, s[74:75] offset:3072 sc1
	s_or_b64 exec, exec, s[66:67]
	global_load_dwordx4 v[210:213], v132, s[22:23]
	global_load_dwordx4 v[214:217], v132, s[22:23] offset:16
	global_load_dwordx4 v[218:221], v132, s[22:23] offset:128
	global_load_dwordx4 v[222:225], v132, s[22:23] offset:144
	s_waitcnt vmcnt(0)
	s_barrier
	s_barrier
	s_cmpk_gt_u32 s17, 0xff
	s_cbranch_scc1 .Lf11_w1_a
	s_and_saveexec_b64 s[40:41], s[14:15]
	s_cbranch_execz .Lf11_t0_done
	v_mov_b32_e32 v133, 0
	v_mov_b32_e32 v189, 1
	global_atomic_add v133, v189, s[78:79]
	s_mov_b32 s80, 0
